# GEMM K-loops: vmcnt and lgkmcnt waits before each barrier merged into one s_waitcnt
# speedup vs baseline: 1.0011x; 1.0011x over previous
.LBB0_212:
	s_ashr_i32 s11, s10, 31
	s_lshl_b64 s[12:13], s[10:11], 19
	v_readlane_b32 s14, v252, 27
	v_readlane_b32 s15, v252, 28
	s_add_u32 s28, s14, s12
	s_addc_u32 s29, s15, s13
	s_and_b64 s[12:13], s[42:43], exec
	s_cselect_b32 s3, s29, s17
	s_cselect_b32 s11, s28, s16
	s_ashr_i32 s9, s8, 31
	s_lshl_b64 s[12:13], s[8:9], 19
	s_add_u32 s36, s20, s12
	s_addc_u32 s37, s22, s13
	s_and_b64 s[12:13], s[42:43], exec
	s_cselect_b32 s9, s37, s41
	s_cselect_b32 s12, s36, s40
	s_add_u32 s16, s16, 0x40080
	s_addc_u32 s17, s17, 0
	s_add_u32 s13, s40, 0x100
	s_addc_u32 s14, s41, 0
	s_mov_b32 s15, -2
	s_add_u32 s18, s16, 0xfffc0080
	s_addc_u32 s19, s17, -1
	s_add_i32 s21, 0, 0x10000
	s_cmp_eq_u32 s15, 12
	s_cselect_b32 s45, s3, s19
	s_cselect_b32 s44, s11, s18
	v_add_u32_e32 v152, s21, v155
	s_cselect_b32 s41, s9, s14
	s_cselect_b32 s40, s12, s13
	s_add_i32 s24, 0, 0x14000
	ds_read_b128 v[182:185], v152
	ds_read_b128 v[186:189], v152 offset:1024
	ds_read_b128 v[190:193], v152 offset:2048
	ds_read_b128 v[194:197], v152 offset:3072
	v_add_u32_e32 v152, s24, v155
	ds_read_b128 v[198:201], v152
	ds_read_b128 v[202:205], v152 offset:1024
	ds_read_b128 v[206:209], v152 offset:2048
	ds_read_b128 v[210:213], v152 offset:3072
	s_add_i32 m0, s26, 0xc000
	ds_read_b128 v[214:217], v157
	ds_read_b128 v[218:221], v157 offset:1024
	ds_read_b128 v[222:225], v157 offset:2048
	ds_read_b128 v[226:229], v157 offset:3072
	ds_read_b128 v[230:233], v157 offset:4096
	ds_read_b128 v[234:237], v157 offset:5120
	ds_read_b128 v[238:241], v157 offset:6144
	ds_read_b128 v[242:245], v157 offset:7168
	global_load_lds_dwordx4 v148, s[16:17]
	s_add_i32 m0, s26, 0xe000
	s_nop 0
	global_load_lds_dwordx4 v150, s[16:17]
	s_waitcnt vmcnt(8) lgkmcnt(0)
	s_barrier
	v_mfma_f32_16x16x32_bf16 v[124:127], v[182:185], v[214:217], 0
	v_mfma_f32_16x16x32_bf16 v[120:123], v[190:193], v[214:217], 0
	v_mfma_f32_16x16x32_bf16 v[108:111], v[182:185], v[222:225], 0
	v_mfma_f32_16x16x32_bf16 v[104:107], v[190:193], v[222:225], 0
	v_mfma_f32_16x16x32_bf16 v[92:95], v[182:185], v[230:233], 0
	v_mfma_f32_16x16x32_bf16 v[88:91], v[190:193], v[230:233], 0
	v_mfma_f32_16x16x32_bf16 v[76:79], v[182:185], v[238:241], 0
	v_mfma_f32_16x16x32_bf16 v[72:75], v[190:193], v[238:241], 0
	v_mfma_f32_16x16x32_bf16 v[124:127], v[186:189], v[218:221], v[124:127]
	v_mfma_f32_16x16x32_bf16 v[120:123], v[194:197], v[218:221], v[120:123]
	v_mfma_f32_16x16x32_bf16 v[108:111], v[186:189], v[226:229], v[108:111]
	v_mfma_f32_16x16x32_bf16 v[104:107], v[194:197], v[226:229], v[104:107]
	v_mfma_f32_16x16x32_bf16 v[92:95], v[186:189], v[234:237], v[92:95]
	v_mfma_f32_16x16x32_bf16 v[88:91], v[194:197], v[234:237], v[88:91]
	v_mfma_f32_16x16x32_bf16 v[76:79], v[186:189], v[242:245], v[76:79]
	v_mfma_f32_16x16x32_bf16 v[72:75], v[194:197], v[242:245], v[72:75]
	v_mfma_f32_16x16x32_bf16 v[116:119], v[198:201], v[214:217], 0
	v_mfma_f32_16x16x32_bf16 v[112:115], v[206:209], v[214:217], 0
	v_mfma_f32_16x16x32_bf16 v[100:103], v[198:201], v[222:225], 0
	v_mfma_f32_16x16x32_bf16 v[96:99], v[206:209], v[222:225], 0
	v_mfma_f32_16x16x32_bf16 v[84:87], v[198:201], v[230:233], 0
	v_mfma_f32_16x16x32_bf16 v[80:83], v[206:209], v[230:233], 0
	v_mfma_f32_16x16x32_bf16 v[68:71], v[198:201], v[238:241], 0
	v_mfma_f32_16x16x32_bf16 v[64:67], v[206:209], v[238:241], 0
	v_mfma_f32_16x16x32_bf16 v[116:119], v[202:205], v[218:221], v[116:119]
	v_mfma_f32_16x16x32_bf16 v[112:115], v[210:213], v[218:221], v[112:115]
	v_mfma_f32_16x16x32_bf16 v[100:103], v[202:205], v[226:229], v[100:103]
	v_mfma_f32_16x16x32_bf16 v[96:99], v[210:213], v[226:229], v[96:99]
	v_mfma_f32_16x16x32_bf16 v[84:87], v[202:205], v[234:237], v[84:87]
	v_mfma_f32_16x16x32_bf16 v[80:83], v[210:213], v[234:237], v[80:83]
	v_mfma_f32_16x16x32_bf16 v[68:71], v[202:205], v[242:245], v[68:71]
	v_mfma_f32_16x16x32_bf16 v[64:67], v[210:213], v[242:245], v[64:67]
	s_barrier
	s_add_u32 s60, s40, 0x80
	s_addc_u32 s61, s41, 0
	s_add_u32 s62, s44, 0x80
	s_addc_u32 s63, s45, 0
	s_add_i32 s18, s21, s23
	s_mov_b32 m0, s18
	ds_read_b128 v[214:217], v157 offset:16384
	ds_read_b128 v[218:221], v157 offset:17408
	ds_read_b128 v[222:225], v157 offset:18432
	ds_read_b128 v[226:229], v157 offset:19456
	ds_read_b128 v[230:233], v157 offset:20480
	ds_read_b128 v[234:237], v157 offset:21504
	ds_read_b128 v[238:241], v157 offset:22528
	ds_read_b128 v[242:245], v157 offset:23552
	global_load_lds_dwordx4 v130, s[40:41]
	s_add_i32 m0, s18, 0x2000
	s_add_u32 s18, s40, 0x40000
	s_addc_u32 s19, s41, 0
	s_add_i32 s21, s24, s23
	global_load_lds_dwordx4 v142, s[40:41]
	s_mov_b32 m0, s21
	s_nop 0
	global_load_lds_dwordx4 v130, s[18:19]
	s_add_i32 m0, s21, 0x2000
	s_nop 0
	global_load_lds_dwordx4 v142, s[18:19]
	s_mov_b32 m0, s26
	s_nop 0
	global_load_lds_dwordx4 v146, s[44:45]
	s_mov_b32 m0, s34
	s_nop 0
	global_load_lds_dwordx4 v144, s[44:45]
	s_waitcnt vmcnt(8) lgkmcnt(0)
	s_barrier
	v_mfma_f32_16x16x32_bf16 v[60:63], v[182:185], v[214:217], 0
	v_mfma_f32_16x16x32_bf16 v[56:59], v[190:193], v[214:217], 0
	v_mfma_f32_16x16x32_bf16 v[44:47], v[182:185], v[222:225], 0
	v_mfma_f32_16x16x32_bf16 v[40:43], v[190:193], v[222:225], 0
	v_mfma_f32_16x16x32_bf16 v[28:31], v[182:185], v[230:233], 0
	v_mfma_f32_16x16x32_bf16 v[24:27], v[190:193], v[230:233], 0
	v_mfma_f32_16x16x32_bf16 v[12:15], v[182:185], v[238:241], 0
	v_mfma_f32_16x16x32_bf16 v[8:11], v[190:193], v[238:241], 0
	v_mfma_f32_16x16x32_bf16 v[60:63], v[186:189], v[218:221], v[60:63]
	v_mfma_f32_16x16x32_bf16 v[56:59], v[194:197], v[218:221], v[56:59]
	v_mfma_f32_16x16x32_bf16 v[44:47], v[186:189], v[226:229], v[44:47]
	v_mfma_f32_16x16x32_bf16 v[40:43], v[194:197], v[226:229], v[40:43]
	v_mfma_f32_16x16x32_bf16 v[28:31], v[186:189], v[234:237], v[28:31]
	v_mfma_f32_16x16x32_bf16 v[24:27], v[194:197], v[234:237], v[24:27]
	v_mfma_f32_16x16x32_bf16 v[12:15], v[186:189], v[242:245], v[12:15]
	v_mfma_f32_16x16x32_bf16 v[8:11], v[194:197], v[242:245], v[8:11]
	v_mfma_f32_16x16x32_bf16 v[52:55], v[198:201], v[214:217], 0
	v_mfma_f32_16x16x32_bf16 v[48:51], v[206:209], v[214:217], 0
	v_mfma_f32_16x16x32_bf16 v[36:39], v[198:201], v[222:225], 0
	v_mfma_f32_16x16x32_bf16 v[32:35], v[206:209], v[222:225], 0
	v_mfma_f32_16x16x32_bf16 v[20:23], v[198:201], v[230:233], 0
	v_mfma_f32_16x16x32_bf16 v[16:19], v[206:209], v[230:233], 0
	v_mfma_f32_16x16x32_bf16 v[4:7], v[198:201], v[238:241], 0
	v_mfma_f32_16x16x32_bf16 v[0:3], v[206:209], v[238:241], 0
	v_mfma_f32_16x16x32_bf16 v[52:55], v[202:205], v[218:221], v[52:55]
	v_mfma_f32_16x16x32_bf16 v[48:51], v[210:213], v[218:221], v[48:51]
	v_mfma_f32_16x16x32_bf16 v[36:39], v[202:205], v[226:229], v[36:39]
	v_mfma_f32_16x16x32_bf16 v[32:35], v[210:213], v[226:229], v[32:35]
	v_mfma_f32_16x16x32_bf16 v[20:23], v[202:205], v[234:237], v[20:23]
	v_mfma_f32_16x16x32_bf16 v[16:19], v[210:213], v[234:237], v[16:19]
	v_mfma_f32_16x16x32_bf16 v[4:7], v[202:205], v[242:245], v[4:7]
	v_mfma_f32_16x16x32_bf16 v[0:3], v[210:213], v[242:245], v[0:3]
	s_barrier
	s_add_i32 s21, 0, 0x18000
	v_add_u32_e32 v178, s21, v155
	s_add_i32 s24, 0, 0x1c000
	ds_read_b128 v[182:185], v178
	ds_read_b128 v[186:189], v178 offset:1024
	ds_read_b128 v[190:193], v178 offset:2048
	ds_read_b128 v[194:197], v178 offset:3072
	v_add_u32_e32 v178, s24, v155
	ds_read_b128 v[198:201], v178
	ds_read_b128 v[202:205], v178 offset:1024
	ds_read_b128 v[206:209], v178 offset:2048
	ds_read_b128 v[210:213], v178 offset:3072
	s_add_u32 s18, s44, 0x40000
	s_addc_u32 s19, s45, 0
	s_mov_b32 m0, s35
	ds_read_b128 v[214:217], v157 offset:32768
	ds_read_b128 v[218:221], v157 offset:33792
	ds_read_b128 v[222:225], v157 offset:34816
	ds_read_b128 v[226:229], v157 offset:35840
	ds_read_b128 v[230:233], v157 offset:36864
	ds_read_b128 v[234:237], v157 offset:37888
	ds_read_b128 v[238:241], v157 offset:38912
	ds_read_b128 v[242:245], v157 offset:39936
	global_load_lds_dwordx4 v146, s[18:19]
	s_mov_b32 m0, s46
	s_nop 0
	global_load_lds_dwordx4 v144, s[18:19]
	s_waitcnt vmcnt(8) lgkmcnt(0)
	s_barrier
	v_mfma_f32_16x16x32_bf16 v[124:127], v[182:185], v[214:217], v[124:127]
	v_mfma_f32_16x16x32_bf16 v[120:123], v[190:193], v[214:217], v[120:123]
	v_mfma_f32_16x16x32_bf16 v[108:111], v[182:185], v[222:225], v[108:111]
	v_mfma_f32_16x16x32_bf16 v[104:107], v[190:193], v[222:225], v[104:107]
	v_mfma_f32_16x16x32_bf16 v[92:95], v[182:185], v[230:233], v[92:95]
	v_mfma_f32_16x16x32_bf16 v[88:91], v[190:193], v[230:233], v[88:91]
	v_mfma_f32_16x16x32_bf16 v[76:79], v[182:185], v[238:241], v[76:79]
	v_mfma_f32_16x16x32_bf16 v[72:75], v[190:193], v[238:241], v[72:75]
	v_mfma_f32_16x16x32_bf16 v[124:127], v[186:189], v[218:221], v[124:127]
	v_mfma_f32_16x16x32_bf16 v[120:123], v[194:197], v[218:221], v[120:123]
	v_mfma_f32_16x16x32_bf16 v[108:111], v[186:189], v[226:229], v[108:111]
	v_mfma_f32_16x16x32_bf16 v[104:107], v[194:197], v[226:229], v[104:107]
	v_mfma_f32_16x16x32_bf16 v[92:95], v[186:189], v[234:237], v[92:95]
	v_mfma_f32_16x16x32_bf16 v[88:91], v[194:197], v[234:237], v[88:91]
	v_mfma_f32_16x16x32_bf16 v[76:79], v[186:189], v[242:245], v[76:79]
	v_mfma_f32_16x16x32_bf16 v[72:75], v[194:197], v[242:245], v[72:75]
	v_mfma_f32_16x16x32_bf16 v[116:119], v[198:201], v[214:217], v[116:119]
	v_mfma_f32_16x16x32_bf16 v[112:115], v[206:209], v[214:217], v[112:115]
	v_mfma_f32_16x16x32_bf16 v[100:103], v[198:201], v[222:225], v[100:103]
	v_mfma_f32_16x16x32_bf16 v[96:99], v[206:209], v[222:225], v[96:99]
	v_mfma_f32_16x16x32_bf16 v[84:87], v[198:201], v[230:233], v[84:87]
	v_mfma_f32_16x16x32_bf16 v[80:83], v[206:209], v[230:233], v[80:83]
	v_mfma_f32_16x16x32_bf16 v[68:71], v[198:201], v[238:241], v[68:71]
	v_mfma_f32_16x16x32_bf16 v[64:67], v[206:209], v[238:241], v[64:67]
	v_mfma_f32_16x16x32_bf16 v[116:119], v[202:205], v[218:221], v[116:119]
	v_mfma_f32_16x16x32_bf16 v[112:115], v[210:213], v[218:221], v[112:115]
	v_mfma_f32_16x16x32_bf16 v[100:103], v[202:205], v[226:229], v[100:103]
	v_mfma_f32_16x16x32_bf16 v[96:99], v[210:213], v[226:229], v[96:99]
	v_mfma_f32_16x16x32_bf16 v[84:87], v[202:205], v[234:237], v[84:87]
	v_mfma_f32_16x16x32_bf16 v[80:83], v[210:213], v[234:237], v[80:83]
	v_mfma_f32_16x16x32_bf16 v[68:71], v[202:205], v[242:245], v[68:71]
	v_mfma_f32_16x16x32_bf16 v[64:67], v[210:213], v[242:245], v[64:67]
	s_barrier
	s_add_i32 s18, s21, s23
	s_mov_b32 m0, s18
	ds_read_b128 v[214:217], v157 offset:49152
	ds_read_b128 v[218:221], v157 offset:50176
	ds_read_b128 v[222:225], v157 offset:51200
	ds_read_b128 v[226:229], v157 offset:52224
	ds_read_b128 v[230:233], v157 offset:53248
	ds_read_b128 v[234:237], v157 offset:54272
	ds_read_b128 v[238:241], v157 offset:55296
	ds_read_b128 v[242:245], v157 offset:56320
	global_load_lds_dwordx4 v130, s[60:61]
	s_add_i32 m0, s18, 0x2000
	s_add_u32 s18, s40, 0x40080
	s_addc_u32 s19, s41, 0
	s_add_i32 s21, s24, s23
	global_load_lds_dwordx4 v142, s[60:61]
	s_mov_b32 m0, s21
	s_nop 0
	global_load_lds_dwordx4 v130, s[18:19]
	s_add_i32 m0, s21, 0x2000
	s_nop 0
	global_load_lds_dwordx4 v142, s[18:19]
	s_mov_b32 m0, s47
	s_nop 0
	global_load_lds_dwordx4 v146, s[62:63]
	s_mov_b32 m0, s48
	s_nop 0
	global_load_lds_dwordx4 v144, s[62:63]
	s_waitcnt vmcnt(8) lgkmcnt(0)
	s_barrier
	v_mfma_f32_16x16x32_bf16 v[60:63], v[182:185], v[214:217], v[60:63]
	v_mfma_f32_16x16x32_bf16 v[56:59], v[190:193], v[214:217], v[56:59]
	v_mfma_f32_16x16x32_bf16 v[44:47], v[182:185], v[222:225], v[44:47]
	v_mfma_f32_16x16x32_bf16 v[40:43], v[190:193], v[222:225], v[40:43]
	v_mfma_f32_16x16x32_bf16 v[28:31], v[182:185], v[230:233], v[28:31]
	v_mfma_f32_16x16x32_bf16 v[24:27], v[190:193], v[230:233], v[24:27]
	v_mfma_f32_16x16x32_bf16 v[12:15], v[182:185], v[238:241], v[12:15]
	v_mfma_f32_16x16x32_bf16 v[8:11], v[190:193], v[238:241], v[8:11]
	v_mfma_f32_16x16x32_bf16 v[60:63], v[186:189], v[218:221], v[60:63]
	v_mfma_f32_16x16x32_bf16 v[56:59], v[194:197], v[218:221], v[56:59]
	v_mfma_f32_16x16x32_bf16 v[44:47], v[186:189], v[226:229], v[44:47]
	v_mfma_f32_16x16x32_bf16 v[40:43], v[194:197], v[226:229], v[40:43]
	v_mfma_f32_16x16x32_bf16 v[28:31], v[186:189], v[234:237], v[28:31]
	v_mfma_f32_16x16x32_bf16 v[24:27], v[194:197], v[234:237], v[24:27]
	v_mfma_f32_16x16x32_bf16 v[12:15], v[186:189], v[242:245], v[12:15]
	v_mfma_f32_16x16x32_bf16 v[8:11], v[194:197], v[242:245], v[8:11]
	v_mfma_f32_16x16x32_bf16 v[52:55], v[198:201], v[214:217], v[52:55]
	v_mfma_f32_16x16x32_bf16 v[48:51], v[206:209], v[214:217], v[48:51]
	v_mfma_f32_16x16x32_bf16 v[36:39], v[198:201], v[222:225], v[36:39]
	v_mfma_f32_16x16x32_bf16 v[32:35], v[206:209], v[222:225], v[32:35]
	v_mfma_f32_16x16x32_bf16 v[20:23], v[198:201], v[230:233], v[20:23]
	v_mfma_f32_16x16x32_bf16 v[16:19], v[206:209], v[230:233], v[16:19]
	v_mfma_f32_16x16x32_bf16 v[4:7], v[198:201], v[238:241], v[4:7]
	v_mfma_f32_16x16x32_bf16 v[0:3], v[206:209], v[238:241], v[0:3]
	v_mfma_f32_16x16x32_bf16 v[52:55], v[202:205], v[218:221], v[52:55]
	v_mfma_f32_16x16x32_bf16 v[48:51], v[210:213], v[218:221], v[48:51]
	v_mfma_f32_16x16x32_bf16 v[36:39], v[202:205], v[226:229], v[36:39]
	v_mfma_f32_16x16x32_bf16 v[32:35], v[210:213], v[226:229], v[32:35]
	v_mfma_f32_16x16x32_bf16 v[20:23], v[202:205], v[234:237], v[20:23]
	v_mfma_f32_16x16x32_bf16 v[16:19], v[210:213], v[234:237], v[16:19]
	v_mfma_f32_16x16x32_bf16 v[4:7], v[202:205], v[242:245], v[4:7]
	v_mfma_f32_16x16x32_bf16 v[0:3], v[210:213], v[242:245], v[0:3]
	s_barrier
	s_add_i32 s15, s15, 2
	s_add_u32 s16, s16, 0x100
	s_addc_u32 s17, s17, 0
	s_add_u32 s13, s13, 0x100
	s_addc_u32 s14, s14, 0
	s_cmp_gt_u32 s15, 13
	s_cbranch_scc1 .Lpeel_done_213
.LBB0_213:
	s_add_u32 s18, s16, 0xfffc0080
	s_addc_u32 s19, s17, -1
	s_add_i32 s21, 0, 0x10000
	s_cmp_eq_u32 s15, 12
	s_cselect_b32 s45, s3, s19
	s_cselect_b32 s44, s11, s18
	v_add_u32_e32 v152, s21, v155
	s_cselect_b32 s41, s9, s14
	s_cselect_b32 s40, s12, s13
	s_add_i32 s24, 0, 0x14000
	ds_read_b128 v[182:185], v152
	ds_read_b128 v[186:189], v152 offset:1024
	ds_read_b128 v[190:193], v152 offset:2048
	ds_read_b128 v[194:197], v152 offset:3072
	v_add_u32_e32 v152, s24, v155
	ds_read_b128 v[198:201], v152
	ds_read_b128 v[202:205], v152 offset:1024
	ds_read_b128 v[206:209], v152 offset:2048
	ds_read_b128 v[210:213], v152 offset:3072
	s_add_i32 m0, s26, 0xc000
	ds_read_b128 v[214:217], v157
	ds_read_b128 v[218:221], v157 offset:1024
	ds_read_b128 v[222:225], v157 offset:2048
	ds_read_b128 v[226:229], v157 offset:3072
	ds_read_b128 v[230:233], v157 offset:4096
	ds_read_b128 v[234:237], v157 offset:5120
	ds_read_b128 v[238:241], v157 offset:6144
	ds_read_b128 v[242:245], v157 offset:7168
	global_load_lds_dwordx4 v148, s[16:17]
	s_add_i32 m0, s26, 0xe000
	s_nop 0
	global_load_lds_dwordx4 v150, s[16:17]
	s_waitcnt vmcnt(8) lgkmcnt(0)
	s_barrier
	v_mfma_f32_16x16x32_bf16 v[124:127], v[182:185], v[214:217], v[124:127]
	v_mfma_f32_16x16x32_bf16 v[120:123], v[190:193], v[214:217], v[120:123]
	v_mfma_f32_16x16x32_bf16 v[108:111], v[182:185], v[222:225], v[108:111]
	v_mfma_f32_16x16x32_bf16 v[104:107], v[190:193], v[222:225], v[104:107]
	v_mfma_f32_16x16x32_bf16 v[92:95], v[182:185], v[230:233], v[92:95]
	v_mfma_f32_16x16x32_bf16 v[88:91], v[190:193], v[230:233], v[88:91]
	v_mfma_f32_16x16x32_bf16 v[76:79], v[182:185], v[238:241], v[76:79]
	v_mfma_f32_16x16x32_bf16 v[72:75], v[190:193], v[238:241], v[72:75]
	v_mfma_f32_16x16x32_bf16 v[124:127], v[186:189], v[218:221], v[124:127]
	v_mfma_f32_16x16x32_bf16 v[120:123], v[194:197], v[218:221], v[120:123]
	v_mfma_f32_16x16x32_bf16 v[108:111], v[186:189], v[226:229], v[108:111]
	v_mfma_f32_16x16x32_bf16 v[104:107], v[194:197], v[226:229], v[104:107]
	v_mfma_f32_16x16x32_bf16 v[92:95], v[186:189], v[234:237], v[92:95]
	v_mfma_f32_16x16x32_bf16 v[88:91], v[194:197], v[234:237], v[88:91]
	v_mfma_f32_16x16x32_bf16 v[76:79], v[186:189], v[242:245], v[76:79]
	v_mfma_f32_16x16x32_bf16 v[72:75], v[194:197], v[242:245], v[72:75]
	v_mfma_f32_16x16x32_bf16 v[116:119], v[198:201], v[214:217], v[116:119]
	v_mfma_f32_16x16x32_bf16 v[112:115], v[206:209], v[214:217], v[112:115]
	v_mfma_f32_16x16x32_bf16 v[100:103], v[198:201], v[222:225], v[100:103]
	v_mfma_f32_16x16x32_bf16 v[96:99], v[206:209], v[222:225], v[96:99]
	v_mfma_f32_16x16x32_bf16 v[84:87], v[198:201], v[230:233], v[84:87]
	v_mfma_f32_16x16x32_bf16 v[80:83], v[206:209], v[230:233], v[80:83]
	v_mfma_f32_16x16x32_bf16 v[68:71], v[198:201], v[238:241], v[68:71]
	v_mfma_f32_16x16x32_bf16 v[64:67], v[206:209], v[238:241], v[64:67]
	v_mfma_f32_16x16x32_bf16 v[116:119], v[202:205], v[218:221], v[116:119]
	v_mfma_f32_16x16x32_bf16 v[112:115], v[210:213], v[218:221], v[112:115]
	v_mfma_f32_16x16x32_bf16 v[100:103], v[202:205], v[226:229], v[100:103]
	v_mfma_f32_16x16x32_bf16 v[96:99], v[210:213], v[226:229], v[96:99]
	v_mfma_f32_16x16x32_bf16 v[84:87], v[202:205], v[234:237], v[84:87]
	v_mfma_f32_16x16x32_bf16 v[80:83], v[210:213], v[234:237], v[80:83]
	v_mfma_f32_16x16x32_bf16 v[68:71], v[202:205], v[242:245], v[68:71]
	v_mfma_f32_16x16x32_bf16 v[64:67], v[210:213], v[242:245], v[64:67]
	s_barrier
	s_add_u32 s60, s40, 0x80
	s_addc_u32 s61, s41, 0
	s_add_u32 s62, s44, 0x80
	s_addc_u32 s63, s45, 0
	s_add_i32 s18, s21, s23
	s_mov_b32 m0, s18
	ds_read_b128 v[214:217], v157 offset:16384
	ds_read_b128 v[218:221], v157 offset:17408
	ds_read_b128 v[222:225], v157 offset:18432
	ds_read_b128 v[226:229], v157 offset:19456
	ds_read_b128 v[230:233], v157 offset:20480
	ds_read_b128 v[234:237], v157 offset:21504
	ds_read_b128 v[238:241], v157 offset:22528
	ds_read_b128 v[242:245], v157 offset:23552
	global_load_lds_dwordx4 v130, s[40:41]
	s_add_i32 m0, s18, 0x2000
	s_add_u32 s18, s40, 0x40000
	s_addc_u32 s19, s41, 0
	s_add_i32 s21, s24, s23
	global_load_lds_dwordx4 v142, s[40:41]
	s_mov_b32 m0, s21
	s_nop 0
	global_load_lds_dwordx4 v130, s[18:19]
	s_add_i32 m0, s21, 0x2000
	s_nop 0
	global_load_lds_dwordx4 v142, s[18:19]
	s_mov_b32 m0, s26
	s_nop 0
	global_load_lds_dwordx4 v146, s[44:45]
	s_mov_b32 m0, s34
	s_nop 0
	global_load_lds_dwordx4 v144, s[44:45]
	s_waitcnt vmcnt(8) lgkmcnt(0)
	s_barrier
	v_mfma_f32_16x16x32_bf16 v[60:63], v[182:185], v[214:217], v[60:63]
	v_mfma_f32_16x16x32_bf16 v[56:59], v[190:193], v[214:217], v[56:59]
	v_mfma_f32_16x16x32_bf16 v[44:47], v[182:185], v[222:225], v[44:47]
	v_mfma_f32_16x16x32_bf16 v[40:43], v[190:193], v[222:225], v[40:43]
	v_mfma_f32_16x16x32_bf16 v[28:31], v[182:185], v[230:233], v[28:31]
	v_mfma_f32_16x16x32_bf16 v[24:27], v[190:193], v[230:233], v[24:27]
	v_mfma_f32_16x16x32_bf16 v[12:15], v[182:185], v[238:241], v[12:15]
	v_mfma_f32_16x16x32_bf16 v[8:11], v[190:193], v[238:241], v[8:11]
	v_mfma_f32_16x16x32_bf16 v[60:63], v[186:189], v[218:221], v[60:63]
	v_mfma_f32_16x16x32_bf16 v[56:59], v[194:197], v[218:221], v[56:59]
	v_mfma_f32_16x16x32_bf16 v[44:47], v[186:189], v[226:229], v[44:47]
	v_mfma_f32_16x16x32_bf16 v[40:43], v[194:197], v[226:229], v[40:43]
	v_mfma_f32_16x16x32_bf16 v[28:31], v[186:189], v[234:237], v[28:31]
	v_mfma_f32_16x16x32_bf16 v[24:27], v[194:197], v[234:237], v[24:27]
	v_mfma_f32_16x16x32_bf16 v[12:15], v[186:189], v[242:245], v[12:15]
	v_mfma_f32_16x16x32_bf16 v[8:11], v[194:197], v[242:245], v[8:11]
	v_mfma_f32_16x16x32_bf16 v[52:55], v[198:201], v[214:217], v[52:55]
	v_mfma_f32_16x16x32_bf16 v[48:51], v[206:209], v[214:217], v[48:51]
	v_mfma_f32_16x16x32_bf16 v[36:39], v[198:201], v[222:225], v[36:39]
	v_mfma_f32_16x16x32_bf16 v[32:35], v[206:209], v[222:225], v[32:35]
	v_mfma_f32_16x16x32_bf16 v[20:23], v[198:201], v[230:233], v[20:23]
	v_mfma_f32_16x16x32_bf16 v[16:19], v[206:209], v[230:233], v[16:19]
	v_mfma_f32_16x16x32_bf16 v[4:7], v[198:201], v[238:241], v[4:7]
	v_mfma_f32_16x16x32_bf16 v[0:3], v[206:209], v[238:241], v[0:3]
	v_mfma_f32_16x16x32_bf16 v[52:55], v[202:205], v[218:221], v[52:55]
	v_mfma_f32_16x16x32_bf16 v[48:51], v[210:213], v[218:221], v[48:51]
	v_mfma_f32_16x16x32_bf16 v[36:39], v[202:205], v[226:229], v[36:39]
	v_mfma_f32_16x16x32_bf16 v[32:35], v[210:213], v[226:229], v[32:35]
	v_mfma_f32_16x16x32_bf16 v[20:23], v[202:205], v[234:237], v[20:23]
	v_mfma_f32_16x16x32_bf16 v[16:19], v[210:213], v[234:237], v[16:19]
	v_mfma_f32_16x16x32_bf16 v[4:7], v[202:205], v[242:245], v[4:7]
	v_mfma_f32_16x16x32_bf16 v[0:3], v[210:213], v[242:245], v[0:3]
	s_barrier
	s_add_i32 s21, 0, 0x18000
	v_add_u32_e32 v178, s21, v155
	s_add_i32 s24, 0, 0x1c000
	ds_read_b128 v[182:185], v178
	ds_read_b128 v[186:189], v178 offset:1024
	ds_read_b128 v[190:193], v178 offset:2048
	ds_read_b128 v[194:197], v178 offset:3072
	v_add_u32_e32 v178, s24, v155
	ds_read_b128 v[198:201], v178
	ds_read_b128 v[202:205], v178 offset:1024
	ds_read_b128 v[206:209], v178 offset:2048
	ds_read_b128 v[210:213], v178 offset:3072
	s_add_u32 s18, s44, 0x40000
	s_addc_u32 s19, s45, 0
	s_mov_b32 m0, s35
	ds_read_b128 v[214:217], v157 offset:32768
	ds_read_b128 v[218:221], v157 offset:33792
	ds_read_b128 v[222:225], v157 offset:34816
	ds_read_b128 v[226:229], v157 offset:35840
	ds_read_b128 v[230:233], v157 offset:36864
	ds_read_b128 v[234:237], v157 offset:37888
	ds_read_b128 v[238:241], v157 offset:38912
	ds_read_b128 v[242:245], v157 offset:39936
	global_load_lds_dwordx4 v146, s[18:19]
	s_mov_b32 m0, s46
	s_nop 0
	global_load_lds_dwordx4 v144, s[18:19]
	s_waitcnt vmcnt(8) lgkmcnt(0)
	s_barrier
	v_mfma_f32_16x16x32_bf16 v[124:127], v[182:185], v[214:217], v[124:127]
	v_mfma_f32_16x16x32_bf16 v[120:123], v[190:193], v[214:217], v[120:123]
	v_mfma_f32_16x16x32_bf16 v[108:111], v[182:185], v[222:225], v[108:111]
	v_mfma_f32_16x16x32_bf16 v[104:107], v[190:193], v[222:225], v[104:107]
	v_mfma_f32_16x16x32_bf16 v[92:95], v[182:185], v[230:233], v[92:95]
	v_mfma_f32_16x16x32_bf16 v[88:91], v[190:193], v[230:233], v[88:91]
	v_mfma_f32_16x16x32_bf16 v[76:79], v[182:185], v[238:241], v[76:79]
	v_mfma_f32_16x16x32_bf16 v[72:75], v[190:193], v[238:241], v[72:75]
	v_mfma_f32_16x16x32_bf16 v[124:127], v[186:189], v[218:221], v[124:127]
	v_mfma_f32_16x16x32_bf16 v[120:123], v[194:197], v[218:221], v[120:123]
	v_mfma_f32_16x16x32_bf16 v[108:111], v[186:189], v[226:229], v[108:111]
	v_mfma_f32_16x16x32_bf16 v[104:107], v[194:197], v[226:229], v[104:107]
	v_mfma_f32_16x16x32_bf16 v[92:95], v[186:189], v[234:237], v[92:95]
	v_mfma_f32_16x16x32_bf16 v[88:91], v[194:197], v[234:237], v[88:91]
	v_mfma_f32_16x16x32_bf16 v[76:79], v[186:189], v[242:245], v[76:79]
	v_mfma_f32_16x16x32_bf16 v[72:75], v[194:197], v[242:245], v[72:75]
	v_mfma_f32_16x16x32_bf16 v[116:119], v[198:201], v[214:217], v[116:119]
	v_mfma_f32_16x16x32_bf16 v[112:115], v[206:209], v[214:217], v[112:115]
	v_mfma_f32_16x16x32_bf16 v[100:103], v[198:201], v[222:225], v[100:103]
	v_mfma_f32_16x16x32_bf16 v[96:99], v[206:209], v[222:225], v[96:99]
	v_mfma_f32_16x16x32_bf16 v[84:87], v[198:201], v[230:233], v[84:87]
	v_mfma_f32_16x16x32_bf16 v[80:83], v[206:209], v[230:233], v[80:83]
	v_mfma_f32_16x16x32_bf16 v[68:71], v[198:201], v[238:241], v[68:71]
	v_mfma_f32_16x16x32_bf16 v[64:67], v[206:209], v[238:241], v[64:67]
	v_mfma_f32_16x16x32_bf16 v[116:119], v[202:205], v[218:221], v[116:119]
	v_mfma_f32_16x16x32_bf16 v[112:115], v[210:213], v[218:221], v[112:115]
	v_mfma_f32_16x16x32_bf16 v[100:103], v[202:205], v[226:229], v[100:103]
	v_mfma_f32_16x16x32_bf16 v[96:99], v[210:213], v[226:229], v[96:99]
	v_mfma_f32_16x16x32_bf16 v[84:87], v[202:205], v[234:237], v[84:87]
	v_mfma_f32_16x16x32_bf16 v[80:83], v[210:213], v[234:237], v[80:83]
	v_mfma_f32_16x16x32_bf16 v[68:71], v[202:205], v[242:245], v[68:71]
	v_mfma_f32_16x16x32_bf16 v[64:67], v[210:213], v[242:245], v[64:67]
	s_barrier
	s_add_i32 s18, s21, s23
	s_mov_b32 m0, s18
	ds_read_b128 v[214:217], v157 offset:49152
	ds_read_b128 v[218:221], v157 offset:50176
	ds_read_b128 v[222:225], v157 offset:51200
	ds_read_b128 v[226:229], v157 offset:52224
	ds_read_b128 v[230:233], v157 offset:53248
	ds_read_b128 v[234:237], v157 offset:54272
	ds_read_b128 v[238:241], v157 offset:55296
	ds_read_b128 v[242:245], v157 offset:56320
	global_load_lds_dwordx4 v130, s[60:61]
	s_add_i32 m0, s18, 0x2000
	s_add_u32 s18, s40, 0x40080
	s_addc_u32 s19, s41, 0
	s_add_i32 s21, s24, s23
	global_load_lds_dwordx4 v142, s[60:61]
	s_mov_b32 m0, s21
	s_nop 0
	global_load_lds_dwordx4 v130, s[18:19]
	s_add_i32 m0, s21, 0x2000
	s_nop 0
	global_load_lds_dwordx4 v142, s[18:19]
	s_mov_b32 m0, s47
	s_nop 0
	global_load_lds_dwordx4 v146, s[62:63]
	s_mov_b32 m0, s48
	s_nop 0
	global_load_lds_dwordx4 v144, s[62:63]
	s_waitcnt vmcnt(8) lgkmcnt(0)
	s_barrier
	v_mfma_f32_16x16x32_bf16 v[60:63], v[182:185], v[214:217], v[60:63]
	v_mfma_f32_16x16x32_bf16 v[56:59], v[190:193], v[214:217], v[56:59]
	v_mfma_f32_16x16x32_bf16 v[44:47], v[182:185], v[222:225], v[44:47]
	v_mfma_f32_16x16x32_bf16 v[40:43], v[190:193], v[222:225], v[40:43]
	v_mfma_f32_16x16x32_bf16 v[28:31], v[182:185], v[230:233], v[28:31]
	v_mfma_f32_16x16x32_bf16 v[24:27], v[190:193], v[230:233], v[24:27]
	v_mfma_f32_16x16x32_bf16 v[12:15], v[182:185], v[238:241], v[12:15]
	v_mfma_f32_16x16x32_bf16 v[8:11], v[190:193], v[238:241], v[8:11]
	v_mfma_f32_16x16x32_bf16 v[60:63], v[186:189], v[218:221], v[60:63]
	v_mfma_f32_16x16x32_bf16 v[56:59], v[194:197], v[218:221], v[56:59]
	v_mfma_f32_16x16x32_bf16 v[44:47], v[186:189], v[226:229], v[44:47]
	v_mfma_f32_16x16x32_bf16 v[40:43], v[194:197], v[226:229], v[40:43]
	v_mfma_f32_16x16x32_bf16 v[28:31], v[186:189], v[234:237], v[28:31]
	v_mfma_f32_16x16x32_bf16 v[24:27], v[194:197], v[234:237], v[24:27]
	v_mfma_f32_16x16x32_bf16 v[12:15], v[186:189], v[242:245], v[12:15]
	v_mfma_f32_16x16x32_bf16 v[8:11], v[194:197], v[242:245], v[8:11]
	v_mfma_f32_16x16x32_bf16 v[52:55], v[198:201], v[214:217], v[52:55]
	v_mfma_f32_16x16x32_bf16 v[48:51], v[206:209], v[214:217], v[48:51]
	v_mfma_f32_16x16x32_bf16 v[36:39], v[198:201], v[222:225], v[36:39]
	v_mfma_f32_16x16x32_bf16 v[32:35], v[206:209], v[222:225], v[32:35]
	v_mfma_f32_16x16x32_bf16 v[20:23], v[198:201], v[230:233], v[20:23]
	v_mfma_f32_16x16x32_bf16 v[16:19], v[206:209], v[230:233], v[16:19]
	v_mfma_f32_16x16x32_bf16 v[4:7], v[198:201], v[238:241], v[4:7]
	v_mfma_f32_16x16x32_bf16 v[0:3], v[206:209], v[238:241], v[0:3]
	v_mfma_f32_16x16x32_bf16 v[52:55], v[202:205], v[218:221], v[52:55]
	v_mfma_f32_16x16x32_bf16 v[48:51], v[210:213], v[218:221], v[48:51]
	v_mfma_f32_16x16x32_bf16 v[36:39], v[202:205], v[226:229], v[36:39]
	v_mfma_f32_16x16x32_bf16 v[32:35], v[210:213], v[226:229], v[32:35]
	v_mfma_f32_16x16x32_bf16 v[20:23], v[202:205], v[234:237], v[20:23]
	v_mfma_f32_16x16x32_bf16 v[16:19], v[210:213], v[234:237], v[16:19]
	v_mfma_f32_16x16x32_bf16 v[4:7], v[202:205], v[242:245], v[4:7]
	v_mfma_f32_16x16x32_bf16 v[0:3], v[210:213], v[242:245], v[0:3]
	s_barrier
	s_add_i32 s15, s15, 2
	s_add_u32 s16, s16, 0x100
	s_addc_u32 s17, s17, 0
	s_add_u32 s13, s13, 0x100
	s_addc_u32 s14, s14, 0
	s_cmp_gt_u32 s15, 13
	s_cbranch_scc0 .LBB0_213

.LBB0_285:
	s_add_i32 s11, s49, -2
	s_add_u32 s50, s40, 0x100
	s_addc_u32 s51, s41, 0
	s_mov_b32 s42, 0
	s_add_i32 s52, s42, 2
	s_add_u32 s40, s36, 0x100
	s_addc_u32 s41, s37, 0
	s_add_i32 s22, 0, 0x10000
	s_cmp_eq_u32 s11, s42
	s_cselect_b32 s45, s17, s41
	s_cselect_b32 s44, s16, s40
	v_add_u32_e32 v156, s22, v153
	s_cselect_b32 s43, s29, s51
	s_cselect_b32 s42, s28, s50
	s_add_i32 s23, 0, 0x14000
	ds_read_b128 v[182:185], v156
	ds_read_b128 v[186:189], v156 offset:1024
	ds_read_b128 v[190:193], v156 offset:2048
	ds_read_b128 v[194:197], v156 offset:3072
	v_add_u32_e32 v156, s23, v153
	ds_read_b128 v[198:201], v156
	ds_read_b128 v[202:205], v156 offset:1024
	ds_read_b128 v[206:209], v156 offset:2048
	ds_read_b128 v[210:213], v156 offset:3072
	s_add_i32 m0, s13, 0xc000
	ds_read_b128 v[214:217], v155
	ds_read_b128 v[218:221], v155 offset:1024
	ds_read_b128 v[222:225], v155 offset:2048
	ds_read_b128 v[226:229], v155 offset:3072
	ds_read_b128 v[230:233], v155 offset:4096
	ds_read_b128 v[234:237], v155 offset:5120
	ds_read_b128 v[238:241], v155 offset:6144
	ds_read_b128 v[242:245], v155 offset:7168
	global_load_lds_dwordx4 v148, s[36:37]
	s_add_i32 m0, s13, 0xe000
	s_nop 0
	global_load_lds_dwordx4 v150, s[36:37]
	s_waitcnt vmcnt(8) lgkmcnt(0)
	s_barrier
	v_mfma_f32_16x16x32_bf16 v[124:127], v[182:185], v[214:217], 0
	v_mfma_f32_16x16x32_bf16 v[120:123], v[190:193], v[214:217], 0
	v_mfma_f32_16x16x32_bf16 v[116:119], v[182:185], v[222:225], 0
	v_mfma_f32_16x16x32_bf16 v[112:115], v[190:193], v[222:225], 0
	v_mfma_f32_16x16x32_bf16 v[100:103], v[182:185], v[230:233], 0
	v_mfma_f32_16x16x32_bf16 v[96:99], v[190:193], v[230:233], 0
	v_mfma_f32_16x16x32_bf16 v[84:87], v[182:185], v[238:241], 0
	v_mfma_f32_16x16x32_bf16 v[80:83], v[190:193], v[238:241], 0
	v_mfma_f32_16x16x32_bf16 v[124:127], v[186:189], v[218:221], v[124:127]
	v_mfma_f32_16x16x32_bf16 v[120:123], v[194:197], v[218:221], v[120:123]
	v_mfma_f32_16x16x32_bf16 v[116:119], v[186:189], v[226:229], v[116:119]
	v_mfma_f32_16x16x32_bf16 v[112:115], v[194:197], v[226:229], v[112:115]
	v_mfma_f32_16x16x32_bf16 v[100:103], v[186:189], v[234:237], v[100:103]
	v_mfma_f32_16x16x32_bf16 v[96:99], v[194:197], v[234:237], v[96:99]
	v_mfma_f32_16x16x32_bf16 v[84:87], v[186:189], v[242:245], v[84:87]
	v_mfma_f32_16x16x32_bf16 v[80:83], v[194:197], v[242:245], v[80:83]
	v_mfma_f32_16x16x32_bf16 v[108:111], v[198:201], v[214:217], 0
	v_mfma_f32_16x16x32_bf16 v[104:107], v[206:209], v[214:217], 0
	v_mfma_f32_16x16x32_bf16 v[92:95], v[198:201], v[222:225], 0
	v_mfma_f32_16x16x32_bf16 v[88:91], v[206:209], v[222:225], 0
	v_mfma_f32_16x16x32_bf16 v[76:79], v[198:201], v[230:233], 0
	v_mfma_f32_16x16x32_bf16 v[72:75], v[206:209], v[230:233], 0
	v_mfma_f32_16x16x32_bf16 v[68:71], v[198:201], v[238:241], 0
	v_mfma_f32_16x16x32_bf16 v[64:67], v[206:209], v[238:241], 0
	v_mfma_f32_16x16x32_bf16 v[108:111], v[202:205], v[218:221], v[108:111]
	v_mfma_f32_16x16x32_bf16 v[104:107], v[210:213], v[218:221], v[104:107]
	v_mfma_f32_16x16x32_bf16 v[92:95], v[202:205], v[226:229], v[92:95]
	v_mfma_f32_16x16x32_bf16 v[88:91], v[210:213], v[226:229], v[88:91]
	v_mfma_f32_16x16x32_bf16 v[76:79], v[202:205], v[234:237], v[76:79]
	v_mfma_f32_16x16x32_bf16 v[72:75], v[210:213], v[234:237], v[72:75]
	v_mfma_f32_16x16x32_bf16 v[68:71], v[202:205], v[242:245], v[68:71]
	v_mfma_f32_16x16x32_bf16 v[64:67], v[210:213], v[242:245], v[64:67]
	s_barrier
	s_add_u32 s60, s42, 0x80
	s_addc_u32 s61, s43, 0
	s_add_u32 s62, s44, 0x80
	s_addc_u32 s63, s45, 0
	s_add_i32 s21, s22, s12
	s_mov_b32 m0, s21
	ds_read_b128 v[214:217], v155 offset:16384
	ds_read_b128 v[218:221], v155 offset:17408
	ds_read_b128 v[222:225], v155 offset:18432
	ds_read_b128 v[226:229], v155 offset:19456
	ds_read_b128 v[230:233], v155 offset:20480
	ds_read_b128 v[234:237], v155 offset:21504
	ds_read_b128 v[238:241], v155 offset:22528
	ds_read_b128 v[242:245], v155 offset:23552
	global_load_lds_dwordx4 v130, s[42:43]
	s_add_i32 m0, s21, 0x2000
	s_add_u32 s34, s42, 0xb0000
	s_addc_u32 s35, s43, 0
	s_add_i32 s21, s23, s12
	global_load_lds_dwordx4 v146, s[42:43]
	s_mov_b32 m0, s21
	s_nop 0
	global_load_lds_dwordx4 v130, s[34:35]
	s_add_i32 m0, s21, 0x2000
	s_nop 0
	global_load_lds_dwordx4 v146, s[34:35]
	s_mov_b32 m0, s13
	s_nop 0
	global_load_lds_dwordx4 v142, s[44:45]
	s_mov_b32 m0, s19
	s_nop 0
	global_load_lds_dwordx4 v144, s[44:45]
	s_waitcnt vmcnt(8) lgkmcnt(0)
	s_barrier
	v_mfma_f32_16x16x32_bf16 v[60:63], v[182:185], v[214:217], 0
	v_mfma_f32_16x16x32_bf16 v[56:59], v[190:193], v[214:217], 0
	v_mfma_f32_16x16x32_bf16 v[52:55], v[182:185], v[222:225], 0
	v_mfma_f32_16x16x32_bf16 v[48:51], v[190:193], v[222:225], 0
	v_mfma_f32_16x16x32_bf16 v[36:39], v[182:185], v[230:233], 0
	v_mfma_f32_16x16x32_bf16 v[32:35], v[190:193], v[230:233], 0
	v_mfma_f32_16x16x32_bf16 v[20:23], v[182:185], v[238:241], 0
	v_mfma_f32_16x16x32_bf16 v[16:19], v[190:193], v[238:241], 0
	v_mfma_f32_16x16x32_bf16 v[60:63], v[186:189], v[218:221], v[60:63]
	v_mfma_f32_16x16x32_bf16 v[56:59], v[194:197], v[218:221], v[56:59]
	v_mfma_f32_16x16x32_bf16 v[52:55], v[186:189], v[226:229], v[52:55]
	v_mfma_f32_16x16x32_bf16 v[48:51], v[194:197], v[226:229], v[48:51]
	v_mfma_f32_16x16x32_bf16 v[36:39], v[186:189], v[234:237], v[36:39]
	v_mfma_f32_16x16x32_bf16 v[32:35], v[194:197], v[234:237], v[32:35]
	v_mfma_f32_16x16x32_bf16 v[20:23], v[186:189], v[242:245], v[20:23]
	v_mfma_f32_16x16x32_bf16 v[16:19], v[194:197], v[242:245], v[16:19]
	v_mfma_f32_16x16x32_bf16 v[44:47], v[198:201], v[214:217], 0
	v_mfma_f32_16x16x32_bf16 v[40:43], v[206:209], v[214:217], 0
	v_mfma_f32_16x16x32_bf16 v[28:31], v[198:201], v[222:225], 0
	v_mfma_f32_16x16x32_bf16 v[24:27], v[206:209], v[222:225], 0
	v_mfma_f32_16x16x32_bf16 v[12:15], v[198:201], v[230:233], 0
	v_mfma_f32_16x16x32_bf16 v[8:11], v[206:209], v[230:233], 0
	v_mfma_f32_16x16x32_bf16 v[4:7], v[198:201], v[238:241], 0
	v_mfma_f32_16x16x32_bf16 v[0:3], v[206:209], v[238:241], 0
	v_mfma_f32_16x16x32_bf16 v[44:47], v[202:205], v[218:221], v[44:47]
	v_mfma_f32_16x16x32_bf16 v[40:43], v[210:213], v[218:221], v[40:43]
	v_mfma_f32_16x16x32_bf16 v[28:31], v[202:205], v[226:229], v[28:31]
	v_mfma_f32_16x16x32_bf16 v[24:27], v[210:213], v[226:229], v[24:27]
	v_mfma_f32_16x16x32_bf16 v[12:15], v[202:205], v[234:237], v[12:15]
	v_mfma_f32_16x16x32_bf16 v[8:11], v[210:213], v[234:237], v[8:11]
	v_mfma_f32_16x16x32_bf16 v[4:7], v[202:205], v[242:245], v[4:7]
	v_mfma_f32_16x16x32_bf16 v[0:3], v[210:213], v[242:245], v[0:3]
	s_barrier
	s_add_i32 s34, 0, 0x18000
	v_add_u32_e32 v181, s34, v153
	s_add_i32 s35, 0, 0x1c000
	ds_read_b128 v[182:185], v181
	ds_read_b128 v[186:189], v181 offset:1024
	ds_read_b128 v[190:193], v181 offset:2048
	ds_read_b128 v[194:197], v181 offset:3072
	v_add_u32_e32 v181, s35, v153
	ds_read_b128 v[198:201], v181
	ds_read_b128 v[202:205], v181 offset:1024
	ds_read_b128 v[206:209], v181 offset:2048
	ds_read_b128 v[210:213], v181 offset:3072
	s_add_u32 s36, s44, 0xb0000
	s_addc_u32 s37, s45, 0
	s_mov_b32 m0, s20
	ds_read_b128 v[214:217], v155 offset:32768
	ds_read_b128 v[218:221], v155 offset:33792
	ds_read_b128 v[222:225], v155 offset:34816
	ds_read_b128 v[226:229], v155 offset:35840
	ds_read_b128 v[230:233], v155 offset:36864
	ds_read_b128 v[234:237], v155 offset:37888
	ds_read_b128 v[238:241], v155 offset:38912
	ds_read_b128 v[242:245], v155 offset:39936
	global_load_lds_dwordx4 v142, s[36:37]
	s_mov_b32 m0, s26
	s_nop 0
	global_load_lds_dwordx4 v144, s[36:37]
	s_waitcnt vmcnt(8) lgkmcnt(0)
	s_barrier
	v_mfma_f32_16x16x32_bf16 v[124:127], v[182:185], v[214:217], v[124:127]
	v_mfma_f32_16x16x32_bf16 v[120:123], v[190:193], v[214:217], v[120:123]
	v_mfma_f32_16x16x32_bf16 v[116:119], v[182:185], v[222:225], v[116:119]
	v_mfma_f32_16x16x32_bf16 v[112:115], v[190:193], v[222:225], v[112:115]
	v_mfma_f32_16x16x32_bf16 v[100:103], v[182:185], v[230:233], v[100:103]
	v_mfma_f32_16x16x32_bf16 v[96:99], v[190:193], v[230:233], v[96:99]
	v_mfma_f32_16x16x32_bf16 v[84:87], v[182:185], v[238:241], v[84:87]
	v_mfma_f32_16x16x32_bf16 v[80:83], v[190:193], v[238:241], v[80:83]
	v_mfma_f32_16x16x32_bf16 v[124:127], v[186:189], v[218:221], v[124:127]
	v_mfma_f32_16x16x32_bf16 v[120:123], v[194:197], v[218:221], v[120:123]
	v_mfma_f32_16x16x32_bf16 v[116:119], v[186:189], v[226:229], v[116:119]
	v_mfma_f32_16x16x32_bf16 v[112:115], v[194:197], v[226:229], v[112:115]
	v_mfma_f32_16x16x32_bf16 v[100:103], v[186:189], v[234:237], v[100:103]
	v_mfma_f32_16x16x32_bf16 v[96:99], v[194:197], v[234:237], v[96:99]
	v_mfma_f32_16x16x32_bf16 v[84:87], v[186:189], v[242:245], v[84:87]
	v_mfma_f32_16x16x32_bf16 v[80:83], v[194:197], v[242:245], v[80:83]
	v_mfma_f32_16x16x32_bf16 v[108:111], v[198:201], v[214:217], v[108:111]
	v_mfma_f32_16x16x32_bf16 v[104:107], v[206:209], v[214:217], v[104:107]
	v_mfma_f32_16x16x32_bf16 v[92:95], v[198:201], v[222:225], v[92:95]
	v_mfma_f32_16x16x32_bf16 v[88:91], v[206:209], v[222:225], v[88:91]
	v_mfma_f32_16x16x32_bf16 v[76:79], v[198:201], v[230:233], v[76:79]
	v_mfma_f32_16x16x32_bf16 v[72:75], v[206:209], v[230:233], v[72:75]
	v_mfma_f32_16x16x32_bf16 v[68:71], v[198:201], v[238:241], v[68:71]
	v_mfma_f32_16x16x32_bf16 v[64:67], v[206:209], v[238:241], v[64:67]
	v_mfma_f32_16x16x32_bf16 v[108:111], v[202:205], v[218:221], v[108:111]
	v_mfma_f32_16x16x32_bf16 v[104:107], v[210:213], v[218:221], v[104:107]
	v_mfma_f32_16x16x32_bf16 v[92:95], v[202:205], v[226:229], v[92:95]
	v_mfma_f32_16x16x32_bf16 v[88:91], v[210:213], v[226:229], v[88:91]
	v_mfma_f32_16x16x32_bf16 v[76:79], v[202:205], v[234:237], v[76:79]
	v_mfma_f32_16x16x32_bf16 v[72:75], v[210:213], v[234:237], v[72:75]
	v_mfma_f32_16x16x32_bf16 v[68:71], v[202:205], v[242:245], v[68:71]
	v_mfma_f32_16x16x32_bf16 v[64:67], v[210:213], v[242:245], v[64:67]
	s_barrier
	s_add_i32 s21, s34, s12
	s_mov_b32 m0, s21
	ds_read_b128 v[214:217], v155 offset:49152
	ds_read_b128 v[218:221], v155 offset:50176
	ds_read_b128 v[222:225], v155 offset:51200
	ds_read_b128 v[226:229], v155 offset:52224
	ds_read_b128 v[230:233], v155 offset:53248
	ds_read_b128 v[234:237], v155 offset:54272
	ds_read_b128 v[238:241], v155 offset:55296
	ds_read_b128 v[242:245], v155 offset:56320
	global_load_lds_dwordx4 v130, s[60:61]
	s_add_i32 m0, s21, 0x2000
	s_add_u32 s36, s42, 0xb0080
	s_addc_u32 s37, s43, 0
	s_add_i32 s21, s35, s12
	global_load_lds_dwordx4 v146, s[60:61]
	s_mov_b32 m0, s21
	s_nop 0
	global_load_lds_dwordx4 v130, s[36:37]
	s_add_i32 m0, s21, 0x2000
	s_nop 0
	global_load_lds_dwordx4 v146, s[36:37]
	s_mov_b32 m0, s33
	s_nop 0
	global_load_lds_dwordx4 v142, s[62:63]
	s_mov_b32 m0, s38
	s_nop 0
	global_load_lds_dwordx4 v144, s[62:63]
	s_waitcnt vmcnt(8) lgkmcnt(0)
	s_barrier
	v_mfma_f32_16x16x32_bf16 v[60:63], v[182:185], v[214:217], v[60:63]
	v_mfma_f32_16x16x32_bf16 v[56:59], v[190:193], v[214:217], v[56:59]
	v_mfma_f32_16x16x32_bf16 v[52:55], v[182:185], v[222:225], v[52:55]
	v_mfma_f32_16x16x32_bf16 v[48:51], v[190:193], v[222:225], v[48:51]
	v_mfma_f32_16x16x32_bf16 v[36:39], v[182:185], v[230:233], v[36:39]
	v_mfma_f32_16x16x32_bf16 v[32:35], v[190:193], v[230:233], v[32:35]
	v_mfma_f32_16x16x32_bf16 v[20:23], v[182:185], v[238:241], v[20:23]
	v_mfma_f32_16x16x32_bf16 v[16:19], v[190:193], v[238:241], v[16:19]
	v_mfma_f32_16x16x32_bf16 v[60:63], v[186:189], v[218:221], v[60:63]
	v_mfma_f32_16x16x32_bf16 v[56:59], v[194:197], v[218:221], v[56:59]
	v_mfma_f32_16x16x32_bf16 v[52:55], v[186:189], v[226:229], v[52:55]
	v_mfma_f32_16x16x32_bf16 v[48:51], v[194:197], v[226:229], v[48:51]
	v_mfma_f32_16x16x32_bf16 v[36:39], v[186:189], v[234:237], v[36:39]
	v_mfma_f32_16x16x32_bf16 v[32:35], v[194:197], v[234:237], v[32:35]
	v_mfma_f32_16x16x32_bf16 v[20:23], v[186:189], v[242:245], v[20:23]
	v_mfma_f32_16x16x32_bf16 v[16:19], v[194:197], v[242:245], v[16:19]
	v_mfma_f32_16x16x32_bf16 v[44:47], v[198:201], v[214:217], v[44:47]
	v_mfma_f32_16x16x32_bf16 v[40:43], v[206:209], v[214:217], v[40:43]
	v_mfma_f32_16x16x32_bf16 v[28:31], v[198:201], v[222:225], v[28:31]
	v_mfma_f32_16x16x32_bf16 v[24:27], v[206:209], v[222:225], v[24:27]
	v_mfma_f32_16x16x32_bf16 v[12:15], v[198:201], v[230:233], v[12:15]
	v_mfma_f32_16x16x32_bf16 v[8:11], v[206:209], v[230:233], v[8:11]
	v_mfma_f32_16x16x32_bf16 v[4:7], v[198:201], v[238:241], v[4:7]
	v_mfma_f32_16x16x32_bf16 v[0:3], v[206:209], v[238:241], v[0:3]
	v_mfma_f32_16x16x32_bf16 v[44:47], v[202:205], v[218:221], v[44:47]
	v_mfma_f32_16x16x32_bf16 v[40:43], v[210:213], v[218:221], v[40:43]
	v_mfma_f32_16x16x32_bf16 v[28:31], v[202:205], v[226:229], v[28:31]
	v_mfma_f32_16x16x32_bf16 v[24:27], v[210:213], v[226:229], v[24:27]
	v_mfma_f32_16x16x32_bf16 v[12:15], v[202:205], v[234:237], v[12:15]
	v_mfma_f32_16x16x32_bf16 v[8:11], v[210:213], v[234:237], v[8:11]
	v_mfma_f32_16x16x32_bf16 v[4:7], v[202:205], v[242:245], v[4:7]
	v_mfma_f32_16x16x32_bf16 v[0:3], v[210:213], v[242:245], v[0:3]
	s_barrier
	s_add_u32 s50, s50, 0x100
	s_addc_u32 s51, s51, 0
	s_cmp_ge_i32 s52, s49
	s_mov_b64 s[36:37], s[40:41]
	s_mov_b32 s42, s52
	s_cbranch_scc1 .Lpeel_done_286
.LBB0_286:
	s_add_i32 s52, s42, 2
	s_add_u32 s40, s36, 0x100
	s_addc_u32 s41, s37, 0
	s_add_i32 s22, 0, 0x10000
	s_cmp_eq_u32 s11, s42
	s_cselect_b32 s45, s17, s41
	s_cselect_b32 s44, s16, s40
	v_add_u32_e32 v156, s22, v153
	s_cselect_b32 s43, s29, s51
	s_cselect_b32 s42, s28, s50
	s_add_i32 s23, 0, 0x14000
	ds_read_b128 v[182:185], v156
	ds_read_b128 v[186:189], v156 offset:1024
	ds_read_b128 v[190:193], v156 offset:2048
	ds_read_b128 v[194:197], v156 offset:3072
	v_add_u32_e32 v156, s23, v153
	ds_read_b128 v[198:201], v156
	ds_read_b128 v[202:205], v156 offset:1024
	ds_read_b128 v[206:209], v156 offset:2048
	ds_read_b128 v[210:213], v156 offset:3072
	s_add_i32 m0, s13, 0xc000
	ds_read_b128 v[214:217], v155
	ds_read_b128 v[218:221], v155 offset:1024
	ds_read_b128 v[222:225], v155 offset:2048
	ds_read_b128 v[226:229], v155 offset:3072
	ds_read_b128 v[230:233], v155 offset:4096
	ds_read_b128 v[234:237], v155 offset:5120
	ds_read_b128 v[238:241], v155 offset:6144
	ds_read_b128 v[242:245], v155 offset:7168
	global_load_lds_dwordx4 v148, s[36:37]
	s_add_i32 m0, s13, 0xe000
	s_nop 0
	global_load_lds_dwordx4 v150, s[36:37]
	s_waitcnt vmcnt(8) lgkmcnt(0)
	s_barrier
	v_mfma_f32_16x16x32_bf16 v[124:127], v[182:185], v[214:217], v[124:127]
	v_mfma_f32_16x16x32_bf16 v[120:123], v[190:193], v[214:217], v[120:123]
	v_mfma_f32_16x16x32_bf16 v[116:119], v[182:185], v[222:225], v[116:119]
	v_mfma_f32_16x16x32_bf16 v[112:115], v[190:193], v[222:225], v[112:115]
	v_mfma_f32_16x16x32_bf16 v[100:103], v[182:185], v[230:233], v[100:103]
	v_mfma_f32_16x16x32_bf16 v[96:99], v[190:193], v[230:233], v[96:99]
	v_mfma_f32_16x16x32_bf16 v[84:87], v[182:185], v[238:241], v[84:87]
	v_mfma_f32_16x16x32_bf16 v[80:83], v[190:193], v[238:241], v[80:83]
	v_mfma_f32_16x16x32_bf16 v[124:127], v[186:189], v[218:221], v[124:127]
	v_mfma_f32_16x16x32_bf16 v[120:123], v[194:197], v[218:221], v[120:123]
	v_mfma_f32_16x16x32_bf16 v[116:119], v[186:189], v[226:229], v[116:119]
	v_mfma_f32_16x16x32_bf16 v[112:115], v[194:197], v[226:229], v[112:115]
	v_mfma_f32_16x16x32_bf16 v[100:103], v[186:189], v[234:237], v[100:103]
	v_mfma_f32_16x16x32_bf16 v[96:99], v[194:197], v[234:237], v[96:99]
	v_mfma_f32_16x16x32_bf16 v[84:87], v[186:189], v[242:245], v[84:87]
	v_mfma_f32_16x16x32_bf16 v[80:83], v[194:197], v[242:245], v[80:83]
	v_mfma_f32_16x16x32_bf16 v[108:111], v[198:201], v[214:217], v[108:111]
	v_mfma_f32_16x16x32_bf16 v[104:107], v[206:209], v[214:217], v[104:107]
	v_mfma_f32_16x16x32_bf16 v[92:95], v[198:201], v[222:225], v[92:95]
	v_mfma_f32_16x16x32_bf16 v[88:91], v[206:209], v[222:225], v[88:91]
	v_mfma_f32_16x16x32_bf16 v[76:79], v[198:201], v[230:233], v[76:79]
	v_mfma_f32_16x16x32_bf16 v[72:75], v[206:209], v[230:233], v[72:75]
	v_mfma_f32_16x16x32_bf16 v[68:71], v[198:201], v[238:241], v[68:71]
	v_mfma_f32_16x16x32_bf16 v[64:67], v[206:209], v[238:241], v[64:67]
	v_mfma_f32_16x16x32_bf16 v[108:111], v[202:205], v[218:221], v[108:111]
	v_mfma_f32_16x16x32_bf16 v[104:107], v[210:213], v[218:221], v[104:107]
	v_mfma_f32_16x16x32_bf16 v[92:95], v[202:205], v[226:229], v[92:95]
	v_mfma_f32_16x16x32_bf16 v[88:91], v[210:213], v[226:229], v[88:91]
	v_mfma_f32_16x16x32_bf16 v[76:79], v[202:205], v[234:237], v[76:79]
	v_mfma_f32_16x16x32_bf16 v[72:75], v[210:213], v[234:237], v[72:75]
	v_mfma_f32_16x16x32_bf16 v[68:71], v[202:205], v[242:245], v[68:71]
	v_mfma_f32_16x16x32_bf16 v[64:67], v[210:213], v[242:245], v[64:67]
	s_barrier
	s_add_u32 s60, s42, 0x80
	s_addc_u32 s61, s43, 0
	s_add_u32 s62, s44, 0x80
	s_addc_u32 s63, s45, 0
	s_add_i32 s21, s22, s12
	s_mov_b32 m0, s21
	ds_read_b128 v[214:217], v155 offset:16384
	ds_read_b128 v[218:221], v155 offset:17408
	ds_read_b128 v[222:225], v155 offset:18432
	ds_read_b128 v[226:229], v155 offset:19456
	ds_read_b128 v[230:233], v155 offset:20480
	ds_read_b128 v[234:237], v155 offset:21504
	ds_read_b128 v[238:241], v155 offset:22528
	ds_read_b128 v[242:245], v155 offset:23552
	global_load_lds_dwordx4 v130, s[42:43]
	s_add_i32 m0, s21, 0x2000
	s_add_u32 s34, s42, 0xb0000
	s_addc_u32 s35, s43, 0
	s_add_i32 s21, s23, s12
	global_load_lds_dwordx4 v146, s[42:43]
	s_mov_b32 m0, s21
	s_nop 0
	global_load_lds_dwordx4 v130, s[34:35]
	s_add_i32 m0, s21, 0x2000
	s_nop 0
	global_load_lds_dwordx4 v146, s[34:35]
	s_mov_b32 m0, s13
	s_nop 0
	global_load_lds_dwordx4 v142, s[44:45]
	s_mov_b32 m0, s19
	s_nop 0
	global_load_lds_dwordx4 v144, s[44:45]
	s_waitcnt vmcnt(8) lgkmcnt(0)
	s_barrier
	v_mfma_f32_16x16x32_bf16 v[60:63], v[182:185], v[214:217], v[60:63]
	v_mfma_f32_16x16x32_bf16 v[56:59], v[190:193], v[214:217], v[56:59]
	v_mfma_f32_16x16x32_bf16 v[52:55], v[182:185], v[222:225], v[52:55]
	v_mfma_f32_16x16x32_bf16 v[48:51], v[190:193], v[222:225], v[48:51]
	v_mfma_f32_16x16x32_bf16 v[36:39], v[182:185], v[230:233], v[36:39]
	v_mfma_f32_16x16x32_bf16 v[32:35], v[190:193], v[230:233], v[32:35]
	v_mfma_f32_16x16x32_bf16 v[20:23], v[182:185], v[238:241], v[20:23]
	v_mfma_f32_16x16x32_bf16 v[16:19], v[190:193], v[238:241], v[16:19]
	v_mfma_f32_16x16x32_bf16 v[60:63], v[186:189], v[218:221], v[60:63]
	v_mfma_f32_16x16x32_bf16 v[56:59], v[194:197], v[218:221], v[56:59]
	v_mfma_f32_16x16x32_bf16 v[52:55], v[186:189], v[226:229], v[52:55]
	v_mfma_f32_16x16x32_bf16 v[48:51], v[194:197], v[226:229], v[48:51]
	v_mfma_f32_16x16x32_bf16 v[36:39], v[186:189], v[234:237], v[36:39]
	v_mfma_f32_16x16x32_bf16 v[32:35], v[194:197], v[234:237], v[32:35]
	v_mfma_f32_16x16x32_bf16 v[20:23], v[186:189], v[242:245], v[20:23]
	v_mfma_f32_16x16x32_bf16 v[16:19], v[194:197], v[242:245], v[16:19]
	v_mfma_f32_16x16x32_bf16 v[44:47], v[198:201], v[214:217], v[44:47]
	v_mfma_f32_16x16x32_bf16 v[40:43], v[206:209], v[214:217], v[40:43]
	v_mfma_f32_16x16x32_bf16 v[28:31], v[198:201], v[222:225], v[28:31]
	v_mfma_f32_16x16x32_bf16 v[24:27], v[206:209], v[222:225], v[24:27]
	v_mfma_f32_16x16x32_bf16 v[12:15], v[198:201], v[230:233], v[12:15]
	v_mfma_f32_16x16x32_bf16 v[8:11], v[206:209], v[230:233], v[8:11]
	v_mfma_f32_16x16x32_bf16 v[4:7], v[198:201], v[238:241], v[4:7]
	v_mfma_f32_16x16x32_bf16 v[0:3], v[206:209], v[238:241], v[0:3]
	v_mfma_f32_16x16x32_bf16 v[44:47], v[202:205], v[218:221], v[44:47]
	v_mfma_f32_16x16x32_bf16 v[40:43], v[210:213], v[218:221], v[40:43]
	v_mfma_f32_16x16x32_bf16 v[28:31], v[202:205], v[226:229], v[28:31]
	v_mfma_f32_16x16x32_bf16 v[24:27], v[210:213], v[226:229], v[24:27]
	v_mfma_f32_16x16x32_bf16 v[12:15], v[202:205], v[234:237], v[12:15]
	v_mfma_f32_16x16x32_bf16 v[8:11], v[210:213], v[234:237], v[8:11]
	v_mfma_f32_16x16x32_bf16 v[4:7], v[202:205], v[242:245], v[4:7]
	v_mfma_f32_16x16x32_bf16 v[0:3], v[210:213], v[242:245], v[0:3]
	s_barrier
	s_add_i32 s34, 0, 0x18000
	v_add_u32_e32 v181, s34, v153
	s_add_i32 s35, 0, 0x1c000
	ds_read_b128 v[182:185], v181
	ds_read_b128 v[186:189], v181 offset:1024
	ds_read_b128 v[190:193], v181 offset:2048
	ds_read_b128 v[194:197], v181 offset:3072
	v_add_u32_e32 v181, s35, v153
	ds_read_b128 v[198:201], v181
	ds_read_b128 v[202:205], v181 offset:1024
	ds_read_b128 v[206:209], v181 offset:2048
	ds_read_b128 v[210:213], v181 offset:3072
	s_add_u32 s36, s44, 0xb0000
	s_addc_u32 s37, s45, 0
	s_mov_b32 m0, s20
	ds_read_b128 v[214:217], v155 offset:32768
	ds_read_b128 v[218:221], v155 offset:33792
	ds_read_b128 v[222:225], v155 offset:34816
	ds_read_b128 v[226:229], v155 offset:35840
	ds_read_b128 v[230:233], v155 offset:36864
	ds_read_b128 v[234:237], v155 offset:37888
	ds_read_b128 v[238:241], v155 offset:38912
	ds_read_b128 v[242:245], v155 offset:39936
	global_load_lds_dwordx4 v142, s[36:37]
	s_mov_b32 m0, s26
	s_nop 0
	global_load_lds_dwordx4 v144, s[36:37]
	s_waitcnt vmcnt(8) lgkmcnt(0)
	s_barrier
	v_mfma_f32_16x16x32_bf16 v[124:127], v[182:185], v[214:217], v[124:127]
	v_mfma_f32_16x16x32_bf16 v[120:123], v[190:193], v[214:217], v[120:123]
	v_mfma_f32_16x16x32_bf16 v[116:119], v[182:185], v[222:225], v[116:119]
	v_mfma_f32_16x16x32_bf16 v[112:115], v[190:193], v[222:225], v[112:115]
	v_mfma_f32_16x16x32_bf16 v[100:103], v[182:185], v[230:233], v[100:103]
	v_mfma_f32_16x16x32_bf16 v[96:99], v[190:193], v[230:233], v[96:99]
	v_mfma_f32_16x16x32_bf16 v[84:87], v[182:185], v[238:241], v[84:87]
	v_mfma_f32_16x16x32_bf16 v[80:83], v[190:193], v[238:241], v[80:83]
	v_mfma_f32_16x16x32_bf16 v[124:127], v[186:189], v[218:221], v[124:127]
	v_mfma_f32_16x16x32_bf16 v[120:123], v[194:197], v[218:221], v[120:123]
	v_mfma_f32_16x16x32_bf16 v[116:119], v[186:189], v[226:229], v[116:119]
	v_mfma_f32_16x16x32_bf16 v[112:115], v[194:197], v[226:229], v[112:115]
	v_mfma_f32_16x16x32_bf16 v[100:103], v[186:189], v[234:237], v[100:103]
	v_mfma_f32_16x16x32_bf16 v[96:99], v[194:197], v[234:237], v[96:99]
	v_mfma_f32_16x16x32_bf16 v[84:87], v[186:189], v[242:245], v[84:87]
	v_mfma_f32_16x16x32_bf16 v[80:83], v[194:197], v[242:245], v[80:83]
	v_mfma_f32_16x16x32_bf16 v[108:111], v[198:201], v[214:217], v[108:111]
	v_mfma_f32_16x16x32_bf16 v[104:107], v[206:209], v[214:217], v[104:107]
	v_mfma_f32_16x16x32_bf16 v[92:95], v[198:201], v[222:225], v[92:95]
	v_mfma_f32_16x16x32_bf16 v[88:91], v[206:209], v[222:225], v[88:91]
	v_mfma_f32_16x16x32_bf16 v[76:79], v[198:201], v[230:233], v[76:79]
	v_mfma_f32_16x16x32_bf16 v[72:75], v[206:209], v[230:233], v[72:75]
	v_mfma_f32_16x16x32_bf16 v[68:71], v[198:201], v[238:241], v[68:71]
	v_mfma_f32_16x16x32_bf16 v[64:67], v[206:209], v[238:241], v[64:67]
	v_mfma_f32_16x16x32_bf16 v[108:111], v[202:205], v[218:221], v[108:111]
	v_mfma_f32_16x16x32_bf16 v[104:107], v[210:213], v[218:221], v[104:107]
	v_mfma_f32_16x16x32_bf16 v[92:95], v[202:205], v[226:229], v[92:95]
	v_mfma_f32_16x16x32_bf16 v[88:91], v[210:213], v[226:229], v[88:91]
	v_mfma_f32_16x16x32_bf16 v[76:79], v[202:205], v[234:237], v[76:79]
	v_mfma_f32_16x16x32_bf16 v[72:75], v[210:213], v[234:237], v[72:75]
	v_mfma_f32_16x16x32_bf16 v[68:71], v[202:205], v[242:245], v[68:71]
	v_mfma_f32_16x16x32_bf16 v[64:67], v[210:213], v[242:245], v[64:67]
	s_barrier
	s_add_i32 s21, s34, s12
	s_mov_b32 m0, s21
	ds_read_b128 v[214:217], v155 offset:49152
	ds_read_b128 v[218:221], v155 offset:50176
	ds_read_b128 v[222:225], v155 offset:51200
	ds_read_b128 v[226:229], v155 offset:52224
	ds_read_b128 v[230:233], v155 offset:53248
	ds_read_b128 v[234:237], v155 offset:54272
	ds_read_b128 v[238:241], v155 offset:55296
	ds_read_b128 v[242:245], v155 offset:56320
	global_load_lds_dwordx4 v130, s[60:61]
	s_add_i32 m0, s21, 0x2000
	s_add_u32 s36, s42, 0xb0080
	s_addc_u32 s37, s43, 0
	s_add_i32 s21, s35, s12
	global_load_lds_dwordx4 v146, s[60:61]
	s_mov_b32 m0, s21
	s_nop 0
	global_load_lds_dwordx4 v130, s[36:37]
	s_add_i32 m0, s21, 0x2000
	s_nop 0
	global_load_lds_dwordx4 v146, s[36:37]
	s_mov_b32 m0, s33
	s_nop 0
	global_load_lds_dwordx4 v142, s[62:63]
	s_mov_b32 m0, s38
	s_nop 0
	global_load_lds_dwordx4 v144, s[62:63]
	s_waitcnt vmcnt(8) lgkmcnt(0)
	s_barrier
	v_mfma_f32_16x16x32_bf16 v[60:63], v[182:185], v[214:217], v[60:63]
	v_mfma_f32_16x16x32_bf16 v[56:59], v[190:193], v[214:217], v[56:59]
	v_mfma_f32_16x16x32_bf16 v[52:55], v[182:185], v[222:225], v[52:55]
	v_mfma_f32_16x16x32_bf16 v[48:51], v[190:193], v[222:225], v[48:51]
	v_mfma_f32_16x16x32_bf16 v[36:39], v[182:185], v[230:233], v[36:39]
	v_mfma_f32_16x16x32_bf16 v[32:35], v[190:193], v[230:233], v[32:35]
	v_mfma_f32_16x16x32_bf16 v[20:23], v[182:185], v[238:241], v[20:23]
	v_mfma_f32_16x16x32_bf16 v[16:19], v[190:193], v[238:241], v[16:19]
	v_mfma_f32_16x16x32_bf16 v[60:63], v[186:189], v[218:221], v[60:63]
	v_mfma_f32_16x16x32_bf16 v[56:59], v[194:197], v[218:221], v[56:59]
	v_mfma_f32_16x16x32_bf16 v[52:55], v[186:189], v[226:229], v[52:55]
	v_mfma_f32_16x16x32_bf16 v[48:51], v[194:197], v[226:229], v[48:51]
	v_mfma_f32_16x16x32_bf16 v[36:39], v[186:189], v[234:237], v[36:39]
	v_mfma_f32_16x16x32_bf16 v[32:35], v[194:197], v[234:237], v[32:35]
	v_mfma_f32_16x16x32_bf16 v[20:23], v[186:189], v[242:245], v[20:23]
	v_mfma_f32_16x16x32_bf16 v[16:19], v[194:197], v[242:245], v[16:19]
	v_mfma_f32_16x16x32_bf16 v[44:47], v[198:201], v[214:217], v[44:47]
	v_mfma_f32_16x16x32_bf16 v[40:43], v[206:209], v[214:217], v[40:43]
	v_mfma_f32_16x16x32_bf16 v[28:31], v[198:201], v[222:225], v[28:31]
	v_mfma_f32_16x16x32_bf16 v[24:27], v[206:209], v[222:225], v[24:27]
	v_mfma_f32_16x16x32_bf16 v[12:15], v[198:201], v[230:233], v[12:15]
	v_mfma_f32_16x16x32_bf16 v[8:11], v[206:209], v[230:233], v[8:11]
	v_mfma_f32_16x16x32_bf16 v[4:7], v[198:201], v[238:241], v[4:7]
	v_mfma_f32_16x16x32_bf16 v[0:3], v[206:209], v[238:241], v[0:3]
	v_mfma_f32_16x16x32_bf16 v[44:47], v[202:205], v[218:221], v[44:47]
	v_mfma_f32_16x16x32_bf16 v[40:43], v[210:213], v[218:221], v[40:43]
	v_mfma_f32_16x16x32_bf16 v[28:31], v[202:205], v[226:229], v[28:31]
	v_mfma_f32_16x16x32_bf16 v[24:27], v[210:213], v[226:229], v[24:27]
	v_mfma_f32_16x16x32_bf16 v[12:15], v[202:205], v[234:237], v[12:15]
	v_mfma_f32_16x16x32_bf16 v[8:11], v[210:213], v[234:237], v[8:11]
	v_mfma_f32_16x16x32_bf16 v[4:7], v[202:205], v[242:245], v[4:7]
	v_mfma_f32_16x16x32_bf16 v[0:3], v[210:213], v[242:245], v[0:3]
	s_barrier
	s_add_u32 s50, s50, 0x100
	s_addc_u32 s51, s51, 0
	s_cmp_ge_i32 s52, s49
	s_mov_b64 s[36:37], s[40:41]
	s_mov_b32 s42, s52
	s_cbranch_scc0 .LBB0_286

.LBB0_510:
	s_ashr_i32 s17, s16, 31
	s_lshl_b64 s[18:19], s[16:17], 19
	v_readlane_b32 s24, v252, 27
	v_readlane_b32 s25, v252, 28
	s_add_u32 s28, s24, s18
	s_addc_u32 s29, s25, s19
	s_and_b64 s[18:19], s[4:5], exec
	s_cselect_b32 s17, s29, s41
	s_cselect_b32 s18, s28, s40
	s_ashr_i32 s11, s10, 31
	s_lshl_b64 s[36:37], s[10:11], 19
	v_readlane_b32 s11, v252, 8
	s_add_u32 s36, s11, s36
	v_readlane_b32 s11, v252, 9
	s_addc_u32 s37, s11, s37
	s_and_b64 s[38:39], s[4:5], exec
	s_cselect_b32 s11, s37, s43
	s_cselect_b32 s19, s36, s42
	s_add_u32 s40, s40, 0x40080
	s_addc_u32 s41, s41, 0
	s_add_u32 s38, s42, 0x100
	s_addc_u32 s39, s43, 0
	s_mov_b32 s46, -2
	v_add_u32_e32 v156, s22, v153
	ds_read_b128 v[182:185], v156
	ds_read_b128 v[186:189], v156 offset:1024
	ds_read_b128 v[190:193], v156 offset:2048
	ds_read_b128 v[194:197], v156 offset:3072
	v_add_u32_e32 v156, s23, v153
	ds_read_b128 v[198:201], v156
	ds_read_b128 v[202:205], v156 offset:1024
	ds_read_b128 v[206:209], v156 offset:2048
	ds_read_b128 v[210:213], v156 offset:3072
	s_add_u32 s21, s40, 0xfffc0080
	s_addc_u32 s24, s41, -1
	s_cmp_eq_u32 s46, 12
	s_cselect_b32 s45, s17, s24
	s_cselect_b32 s44, s18, s21
	s_cselect_b32 s43, s11, s39
	s_cselect_b32 s42, s19, s38
	s_add_i32 m0, s12, 0xc000
	ds_read_b128 v[214:217], v155
	ds_read_b128 v[218:221], v155 offset:1024
	ds_read_b128 v[222:225], v155 offset:2048
	ds_read_b128 v[226:229], v155 offset:3072
	ds_read_b128 v[230:233], v155 offset:4096
	ds_read_b128 v[234:237], v155 offset:5120
	ds_read_b128 v[238:241], v155 offset:6144
	ds_read_b128 v[242:245], v155 offset:7168
	global_load_lds_dwordx4 v148, s[40:41]
	s_add_i32 m0, s12, 0xe000
	s_nop 0
	global_load_lds_dwordx4 v150, s[40:41]
	s_waitcnt vmcnt(8) lgkmcnt(0)
	s_barrier
	v_mfma_f32_16x16x32_bf16 v[124:127], v[182:185], v[214:217], 0
	v_mfma_f32_16x16x32_bf16 v[120:123], v[190:193], v[214:217], 0
	v_mfma_f32_16x16x32_bf16 v[116:119], v[182:185], v[222:225], 0
	v_mfma_f32_16x16x32_bf16 v[112:115], v[190:193], v[222:225], 0
	v_mfma_f32_16x16x32_bf16 v[100:103], v[182:185], v[230:233], 0
	v_mfma_f32_16x16x32_bf16 v[96:99], v[190:193], v[230:233], 0
	v_mfma_f32_16x16x32_bf16 v[84:87], v[182:185], v[238:241], 0
	v_mfma_f32_16x16x32_bf16 v[80:83], v[190:193], v[238:241], 0
	v_mfma_f32_16x16x32_bf16 v[124:127], v[186:189], v[218:221], v[124:127]
	v_mfma_f32_16x16x32_bf16 v[120:123], v[194:197], v[218:221], v[120:123]
	v_mfma_f32_16x16x32_bf16 v[116:119], v[186:189], v[226:229], v[116:119]
	v_mfma_f32_16x16x32_bf16 v[112:115], v[194:197], v[226:229], v[112:115]
	v_mfma_f32_16x16x32_bf16 v[100:103], v[186:189], v[234:237], v[100:103]
	v_mfma_f32_16x16x32_bf16 v[96:99], v[194:197], v[234:237], v[96:99]
	v_mfma_f32_16x16x32_bf16 v[84:87], v[186:189], v[242:245], v[84:87]
	v_mfma_f32_16x16x32_bf16 v[80:83], v[194:197], v[242:245], v[80:83]
	v_mfma_f32_16x16x32_bf16 v[108:111], v[198:201], v[214:217], 0
	v_mfma_f32_16x16x32_bf16 v[104:107], v[206:209], v[214:217], 0
	v_mfma_f32_16x16x32_bf16 v[92:95], v[198:201], v[222:225], 0
	v_mfma_f32_16x16x32_bf16 v[88:91], v[206:209], v[222:225], 0
	v_mfma_f32_16x16x32_bf16 v[76:79], v[198:201], v[230:233], 0
	v_mfma_f32_16x16x32_bf16 v[72:75], v[206:209], v[230:233], 0
	v_mfma_f32_16x16x32_bf16 v[68:71], v[198:201], v[238:241], 0
	v_mfma_f32_16x16x32_bf16 v[64:67], v[206:209], v[238:241], 0
	v_mfma_f32_16x16x32_bf16 v[108:111], v[202:205], v[218:221], v[108:111]
	v_mfma_f32_16x16x32_bf16 v[104:107], v[210:213], v[218:221], v[104:107]
	v_mfma_f32_16x16x32_bf16 v[92:95], v[202:205], v[226:229], v[92:95]
	v_mfma_f32_16x16x32_bf16 v[88:91], v[210:213], v[226:229], v[88:91]
	v_mfma_f32_16x16x32_bf16 v[76:79], v[202:205], v[234:237], v[76:79]
	v_mfma_f32_16x16x32_bf16 v[72:75], v[210:213], v[234:237], v[72:75]
	v_mfma_f32_16x16x32_bf16 v[68:71], v[202:205], v[242:245], v[68:71]
	v_mfma_f32_16x16x32_bf16 v[64:67], v[210:213], v[242:245], v[64:67]
	s_barrier
	s_add_u32 s60, s42, 0x80
	s_addc_u32 s61, s43, 0
	s_add_u32 s62, s44, 0x80
	s_addc_u32 s63, s45, 0
	s_add_i32 s21, s22, s3
	s_mov_b32 m0, s21
	ds_read_b128 v[214:217], v155 offset:16384
	ds_read_b128 v[218:221], v155 offset:17408
	ds_read_b128 v[222:225], v155 offset:18432
	ds_read_b128 v[226:229], v155 offset:19456
	ds_read_b128 v[230:233], v155 offset:20480
	ds_read_b128 v[234:237], v155 offset:21504
	ds_read_b128 v[238:241], v155 offset:22528
	ds_read_b128 v[242:245], v155 offset:23552
	global_load_lds_dwordx4 v130, s[42:43]
	s_add_i32 m0, s21, 0x2000
	s_add_u32 s48, s42, 0x40000
	s_addc_u32 s49, s43, 0
	s_add_i32 s21, s23, s3
	global_load_lds_dwordx4 v142, s[42:43]
	s_mov_b32 m0, s21
	s_nop 0
	global_load_lds_dwordx4 v130, s[48:49]
	s_add_i32 m0, s21, 0x2000
	s_nop 0
	global_load_lds_dwordx4 v142, s[48:49]
	s_mov_b32 m0, s12
	s_nop 0
	global_load_lds_dwordx4 v146, s[44:45]
	s_mov_b32 m0, s13
	s_nop 0
	global_load_lds_dwordx4 v144, s[44:45]
	s_waitcnt vmcnt(8) lgkmcnt(0)
	s_barrier
	v_mfma_f32_16x16x32_bf16 v[60:63], v[182:185], v[214:217], 0
	v_mfma_f32_16x16x32_bf16 v[56:59], v[190:193], v[214:217], 0
	v_mfma_f32_16x16x32_bf16 v[52:55], v[182:185], v[222:225], 0
	v_mfma_f32_16x16x32_bf16 v[48:51], v[190:193], v[222:225], 0
	v_mfma_f32_16x16x32_bf16 v[36:39], v[182:185], v[230:233], 0
	v_mfma_f32_16x16x32_bf16 v[32:35], v[190:193], v[230:233], 0
	v_mfma_f32_16x16x32_bf16 v[20:23], v[182:185], v[238:241], 0
	v_mfma_f32_16x16x32_bf16 v[16:19], v[190:193], v[238:241], 0
	v_mfma_f32_16x16x32_bf16 v[60:63], v[186:189], v[218:221], v[60:63]
	v_mfma_f32_16x16x32_bf16 v[56:59], v[194:197], v[218:221], v[56:59]
	v_mfma_f32_16x16x32_bf16 v[52:55], v[186:189], v[226:229], v[52:55]
	v_mfma_f32_16x16x32_bf16 v[48:51], v[194:197], v[226:229], v[48:51]
	v_mfma_f32_16x16x32_bf16 v[36:39], v[186:189], v[234:237], v[36:39]
	v_mfma_f32_16x16x32_bf16 v[32:35], v[194:197], v[234:237], v[32:35]
	v_mfma_f32_16x16x32_bf16 v[20:23], v[186:189], v[242:245], v[20:23]
	v_mfma_f32_16x16x32_bf16 v[16:19], v[194:197], v[242:245], v[16:19]
	v_mfma_f32_16x16x32_bf16 v[44:47], v[198:201], v[214:217], 0
	v_mfma_f32_16x16x32_bf16 v[40:43], v[206:209], v[214:217], 0
	v_mfma_f32_16x16x32_bf16 v[28:31], v[198:201], v[222:225], 0
	v_mfma_f32_16x16x32_bf16 v[24:27], v[206:209], v[222:225], 0
	v_mfma_f32_16x16x32_bf16 v[12:15], v[198:201], v[230:233], 0
	v_mfma_f32_16x16x32_bf16 v[8:11], v[206:209], v[230:233], 0
	v_mfma_f32_16x16x32_bf16 v[4:7], v[198:201], v[238:241], 0
	v_mfma_f32_16x16x32_bf16 v[0:3], v[206:209], v[238:241], 0
	v_mfma_f32_16x16x32_bf16 v[44:47], v[202:205], v[218:221], v[44:47]
	v_mfma_f32_16x16x32_bf16 v[40:43], v[210:213], v[218:221], v[40:43]
	v_mfma_f32_16x16x32_bf16 v[28:31], v[202:205], v[226:229], v[28:31]
	v_mfma_f32_16x16x32_bf16 v[24:27], v[210:213], v[226:229], v[24:27]
	v_mfma_f32_16x16x32_bf16 v[12:15], v[202:205], v[234:237], v[12:15]
	v_mfma_f32_16x16x32_bf16 v[8:11], v[210:213], v[234:237], v[8:11]
	v_mfma_f32_16x16x32_bf16 v[4:7], v[202:205], v[242:245], v[4:7]
	v_mfma_f32_16x16x32_bf16 v[0:3], v[210:213], v[242:245], v[0:3]
	s_barrier
	v_add_u32_e32 v181, s34, v153
	ds_read_b128 v[182:185], v181
	ds_read_b128 v[186:189], v181 offset:1024
	ds_read_b128 v[190:193], v181 offset:2048
	ds_read_b128 v[194:197], v181 offset:3072
	v_add_u32_e32 v181, s35, v153
	ds_read_b128 v[198:201], v181
	ds_read_b128 v[202:205], v181 offset:1024
	ds_read_b128 v[206:209], v181 offset:2048
	ds_read_b128 v[210:213], v181 offset:3072
	s_add_u32 s44, s44, 0x40000
	s_addc_u32 s45, s45, 0
	s_mov_b32 m0, s20
	ds_read_b128 v[214:217], v155 offset:32768
	ds_read_b128 v[218:221], v155 offset:33792
	ds_read_b128 v[222:225], v155 offset:34816
	ds_read_b128 v[226:229], v155 offset:35840
	ds_read_b128 v[230:233], v155 offset:36864
	ds_read_b128 v[234:237], v155 offset:37888
	ds_read_b128 v[238:241], v155 offset:38912
	ds_read_b128 v[242:245], v155 offset:39936
	global_load_lds_dwordx4 v146, s[44:45]
	s_mov_b32 m0, s26
	s_nop 0
	global_load_lds_dwordx4 v144, s[44:45]
	s_waitcnt vmcnt(8) lgkmcnt(0)
	s_barrier
	v_mfma_f32_16x16x32_bf16 v[124:127], v[182:185], v[214:217], v[124:127]
	v_mfma_f32_16x16x32_bf16 v[120:123], v[190:193], v[214:217], v[120:123]
	v_mfma_f32_16x16x32_bf16 v[116:119], v[182:185], v[222:225], v[116:119]
	v_mfma_f32_16x16x32_bf16 v[112:115], v[190:193], v[222:225], v[112:115]
	v_mfma_f32_16x16x32_bf16 v[100:103], v[182:185], v[230:233], v[100:103]
	v_mfma_f32_16x16x32_bf16 v[96:99], v[190:193], v[230:233], v[96:99]
	v_mfma_f32_16x16x32_bf16 v[84:87], v[182:185], v[238:241], v[84:87]
	v_mfma_f32_16x16x32_bf16 v[80:83], v[190:193], v[238:241], v[80:83]
	v_mfma_f32_16x16x32_bf16 v[124:127], v[186:189], v[218:221], v[124:127]
	v_mfma_f32_16x16x32_bf16 v[120:123], v[194:197], v[218:221], v[120:123]
	v_mfma_f32_16x16x32_bf16 v[116:119], v[186:189], v[226:229], v[116:119]
	v_mfma_f32_16x16x32_bf16 v[112:115], v[194:197], v[226:229], v[112:115]
	v_mfma_f32_16x16x32_bf16 v[100:103], v[186:189], v[234:237], v[100:103]
	v_mfma_f32_16x16x32_bf16 v[96:99], v[194:197], v[234:237], v[96:99]
	v_mfma_f32_16x16x32_bf16 v[84:87], v[186:189], v[242:245], v[84:87]
	v_mfma_f32_16x16x32_bf16 v[80:83], v[194:197], v[242:245], v[80:83]
	v_mfma_f32_16x16x32_bf16 v[108:111], v[198:201], v[214:217], v[108:111]
	v_mfma_f32_16x16x32_bf16 v[104:107], v[206:209], v[214:217], v[104:107]
	v_mfma_f32_16x16x32_bf16 v[92:95], v[198:201], v[222:225], v[92:95]
	v_mfma_f32_16x16x32_bf16 v[88:91], v[206:209], v[222:225], v[88:91]
	v_mfma_f32_16x16x32_bf16 v[76:79], v[198:201], v[230:233], v[76:79]
	v_mfma_f32_16x16x32_bf16 v[72:75], v[206:209], v[230:233], v[72:75]
	v_mfma_f32_16x16x32_bf16 v[68:71], v[198:201], v[238:241], v[68:71]
	v_mfma_f32_16x16x32_bf16 v[64:67], v[206:209], v[238:241], v[64:67]
	v_mfma_f32_16x16x32_bf16 v[108:111], v[202:205], v[218:221], v[108:111]
	v_mfma_f32_16x16x32_bf16 v[104:107], v[210:213], v[218:221], v[104:107]
	v_mfma_f32_16x16x32_bf16 v[92:95], v[202:205], v[226:229], v[92:95]
	v_mfma_f32_16x16x32_bf16 v[88:91], v[210:213], v[226:229], v[88:91]
	v_mfma_f32_16x16x32_bf16 v[76:79], v[202:205], v[234:237], v[76:79]
	v_mfma_f32_16x16x32_bf16 v[72:75], v[210:213], v[234:237], v[72:75]
	v_mfma_f32_16x16x32_bf16 v[68:71], v[202:205], v[242:245], v[68:71]
	v_mfma_f32_16x16x32_bf16 v[64:67], v[210:213], v[242:245], v[64:67]
	s_barrier
	s_add_i32 s21, s34, s3
	s_mov_b32 m0, s21
	ds_read_b128 v[214:217], v155 offset:49152
	ds_read_b128 v[218:221], v155 offset:50176
	ds_read_b128 v[222:225], v155 offset:51200
	ds_read_b128 v[226:229], v155 offset:52224
	ds_read_b128 v[230:233], v155 offset:53248
	ds_read_b128 v[234:237], v155 offset:54272
	ds_read_b128 v[238:241], v155 offset:55296
	ds_read_b128 v[242:245], v155 offset:56320
	global_load_lds_dwordx4 v130, s[60:61]
	s_add_i32 m0, s21, 0x2000
	s_add_u32 s42, s42, 0x40080
	s_addc_u32 s43, s43, 0
	s_add_i32 s21, s35, s3
	global_load_lds_dwordx4 v142, s[60:61]
	s_mov_b32 m0, s21
	s_nop 0
	global_load_lds_dwordx4 v130, s[42:43]
	s_add_i32 m0, s21, 0x2000
	s_nop 0
	global_load_lds_dwordx4 v142, s[42:43]
	s_mov_b32 m0, s0
	s_nop 0
	global_load_lds_dwordx4 v146, s[62:63]
	s_mov_b32 m0, s1
	s_nop 0
	global_load_lds_dwordx4 v144, s[62:63]
	s_waitcnt vmcnt(8) lgkmcnt(0)
	s_barrier
	v_mfma_f32_16x16x32_bf16 v[60:63], v[182:185], v[214:217], v[60:63]
	v_mfma_f32_16x16x32_bf16 v[56:59], v[190:193], v[214:217], v[56:59]
	v_mfma_f32_16x16x32_bf16 v[52:55], v[182:185], v[222:225], v[52:55]
	v_mfma_f32_16x16x32_bf16 v[48:51], v[190:193], v[222:225], v[48:51]
	v_mfma_f32_16x16x32_bf16 v[36:39], v[182:185], v[230:233], v[36:39]
	v_mfma_f32_16x16x32_bf16 v[32:35], v[190:193], v[230:233], v[32:35]
	v_mfma_f32_16x16x32_bf16 v[20:23], v[182:185], v[238:241], v[20:23]
	v_mfma_f32_16x16x32_bf16 v[16:19], v[190:193], v[238:241], v[16:19]
	v_mfma_f32_16x16x32_bf16 v[60:63], v[186:189], v[218:221], v[60:63]
	v_mfma_f32_16x16x32_bf16 v[56:59], v[194:197], v[218:221], v[56:59]
	v_mfma_f32_16x16x32_bf16 v[52:55], v[186:189], v[226:229], v[52:55]
	v_mfma_f32_16x16x32_bf16 v[48:51], v[194:197], v[226:229], v[48:51]
	v_mfma_f32_16x16x32_bf16 v[36:39], v[186:189], v[234:237], v[36:39]
	v_mfma_f32_16x16x32_bf16 v[32:35], v[194:197], v[234:237], v[32:35]
	v_mfma_f32_16x16x32_bf16 v[20:23], v[186:189], v[242:245], v[20:23]
	v_mfma_f32_16x16x32_bf16 v[16:19], v[194:197], v[242:245], v[16:19]
	v_mfma_f32_16x16x32_bf16 v[44:47], v[198:201], v[214:217], v[44:47]
	v_mfma_f32_16x16x32_bf16 v[40:43], v[206:209], v[214:217], v[40:43]
	v_mfma_f32_16x16x32_bf16 v[28:31], v[198:201], v[222:225], v[28:31]
	v_mfma_f32_16x16x32_bf16 v[24:27], v[206:209], v[222:225], v[24:27]
	v_mfma_f32_16x16x32_bf16 v[12:15], v[198:201], v[230:233], v[12:15]
	v_mfma_f32_16x16x32_bf16 v[8:11], v[206:209], v[230:233], v[8:11]
	v_mfma_f32_16x16x32_bf16 v[4:7], v[198:201], v[238:241], v[4:7]
	v_mfma_f32_16x16x32_bf16 v[0:3], v[206:209], v[238:241], v[0:3]
	v_mfma_f32_16x16x32_bf16 v[44:47], v[202:205], v[218:221], v[44:47]
	v_mfma_f32_16x16x32_bf16 v[40:43], v[210:213], v[218:221], v[40:43]
	v_mfma_f32_16x16x32_bf16 v[28:31], v[202:205], v[226:229], v[28:31]
	v_mfma_f32_16x16x32_bf16 v[24:27], v[210:213], v[226:229], v[24:27]
	v_mfma_f32_16x16x32_bf16 v[12:15], v[202:205], v[234:237], v[12:15]
	v_mfma_f32_16x16x32_bf16 v[8:11], v[210:213], v[234:237], v[8:11]
	v_mfma_f32_16x16x32_bf16 v[4:7], v[202:205], v[242:245], v[4:7]
	v_mfma_f32_16x16x32_bf16 v[0:3], v[210:213], v[242:245], v[0:3]
	s_barrier
	s_add_i32 s46, s46, 2
	s_add_u32 s40, s40, 0x100
	s_addc_u32 s41, s41, 0
	s_add_u32 s38, s38, 0x100
	s_addc_u32 s39, s39, 0
	s_cmp_gt_u32 s46, 13
	s_cbranch_scc1 .Lpeel_done_511
.LBB0_511:
	v_add_u32_e32 v156, s22, v153
	ds_read_b128 v[182:185], v156
	ds_read_b128 v[186:189], v156 offset:1024
	ds_read_b128 v[190:193], v156 offset:2048
	ds_read_b128 v[194:197], v156 offset:3072
	v_add_u32_e32 v156, s23, v153
	ds_read_b128 v[198:201], v156
	ds_read_b128 v[202:205], v156 offset:1024
	ds_read_b128 v[206:209], v156 offset:2048
	ds_read_b128 v[210:213], v156 offset:3072
	s_add_u32 s21, s40, 0xfffc0080
	s_addc_u32 s24, s41, -1
	s_cmp_eq_u32 s46, 12
	s_cselect_b32 s45, s17, s24
	s_cselect_b32 s44, s18, s21
	s_cselect_b32 s43, s11, s39
	s_cselect_b32 s42, s19, s38
	s_add_i32 m0, s12, 0xc000
	ds_read_b128 v[214:217], v155
	ds_read_b128 v[218:221], v155 offset:1024
	ds_read_b128 v[222:225], v155 offset:2048
	ds_read_b128 v[226:229], v155 offset:3072
	ds_read_b128 v[230:233], v155 offset:4096
	ds_read_b128 v[234:237], v155 offset:5120
	ds_read_b128 v[238:241], v155 offset:6144
	ds_read_b128 v[242:245], v155 offset:7168
	global_load_lds_dwordx4 v148, s[40:41]
	s_add_i32 m0, s12, 0xe000
	s_nop 0
	global_load_lds_dwordx4 v150, s[40:41]
	s_waitcnt vmcnt(8) lgkmcnt(0)
	s_barrier
	v_mfma_f32_16x16x32_bf16 v[124:127], v[182:185], v[214:217], v[124:127]
	v_mfma_f32_16x16x32_bf16 v[120:123], v[190:193], v[214:217], v[120:123]
	v_mfma_f32_16x16x32_bf16 v[116:119], v[182:185], v[222:225], v[116:119]
	v_mfma_f32_16x16x32_bf16 v[112:115], v[190:193], v[222:225], v[112:115]
	v_mfma_f32_16x16x32_bf16 v[100:103], v[182:185], v[230:233], v[100:103]
	v_mfma_f32_16x16x32_bf16 v[96:99], v[190:193], v[230:233], v[96:99]
	v_mfma_f32_16x16x32_bf16 v[84:87], v[182:185], v[238:241], v[84:87]
	v_mfma_f32_16x16x32_bf16 v[80:83], v[190:193], v[238:241], v[80:83]
	v_mfma_f32_16x16x32_bf16 v[124:127], v[186:189], v[218:221], v[124:127]
	v_mfma_f32_16x16x32_bf16 v[120:123], v[194:197], v[218:221], v[120:123]
	v_mfma_f32_16x16x32_bf16 v[116:119], v[186:189], v[226:229], v[116:119]
	v_mfma_f32_16x16x32_bf16 v[112:115], v[194:197], v[226:229], v[112:115]
	v_mfma_f32_16x16x32_bf16 v[100:103], v[186:189], v[234:237], v[100:103]
	v_mfma_f32_16x16x32_bf16 v[96:99], v[194:197], v[234:237], v[96:99]
	v_mfma_f32_16x16x32_bf16 v[84:87], v[186:189], v[242:245], v[84:87]
	v_mfma_f32_16x16x32_bf16 v[80:83], v[194:197], v[242:245], v[80:83]
	v_mfma_f32_16x16x32_bf16 v[108:111], v[198:201], v[214:217], v[108:111]
	v_mfma_f32_16x16x32_bf16 v[104:107], v[206:209], v[214:217], v[104:107]
	v_mfma_f32_16x16x32_bf16 v[92:95], v[198:201], v[222:225], v[92:95]
	v_mfma_f32_16x16x32_bf16 v[88:91], v[206:209], v[222:225], v[88:91]
	v_mfma_f32_16x16x32_bf16 v[76:79], v[198:201], v[230:233], v[76:79]
	v_mfma_f32_16x16x32_bf16 v[72:75], v[206:209], v[230:233], v[72:75]
	v_mfma_f32_16x16x32_bf16 v[68:71], v[198:201], v[238:241], v[68:71]
	v_mfma_f32_16x16x32_bf16 v[64:67], v[206:209], v[238:241], v[64:67]
	v_mfma_f32_16x16x32_bf16 v[108:111], v[202:205], v[218:221], v[108:111]
	v_mfma_f32_16x16x32_bf16 v[104:107], v[210:213], v[218:221], v[104:107]
	v_mfma_f32_16x16x32_bf16 v[92:95], v[202:205], v[226:229], v[92:95]
	v_mfma_f32_16x16x32_bf16 v[88:91], v[210:213], v[226:229], v[88:91]
	v_mfma_f32_16x16x32_bf16 v[76:79], v[202:205], v[234:237], v[76:79]
	v_mfma_f32_16x16x32_bf16 v[72:75], v[210:213], v[234:237], v[72:75]
	v_mfma_f32_16x16x32_bf16 v[68:71], v[202:205], v[242:245], v[68:71]
	v_mfma_f32_16x16x32_bf16 v[64:67], v[210:213], v[242:245], v[64:67]
	s_barrier
	s_add_u32 s60, s42, 0x80
	s_addc_u32 s61, s43, 0
	s_add_u32 s62, s44, 0x80
	s_addc_u32 s63, s45, 0
	s_add_i32 s21, s22, s3
	s_mov_b32 m0, s21
	ds_read_b128 v[214:217], v155 offset:16384
	ds_read_b128 v[218:221], v155 offset:17408
	ds_read_b128 v[222:225], v155 offset:18432
	ds_read_b128 v[226:229], v155 offset:19456
	ds_read_b128 v[230:233], v155 offset:20480
	ds_read_b128 v[234:237], v155 offset:21504
	ds_read_b128 v[238:241], v155 offset:22528
	ds_read_b128 v[242:245], v155 offset:23552
	global_load_lds_dwordx4 v130, s[42:43]
	s_add_i32 m0, s21, 0x2000
	s_add_u32 s48, s42, 0x40000
	s_addc_u32 s49, s43, 0
	s_add_i32 s21, s23, s3
	global_load_lds_dwordx4 v142, s[42:43]
	s_mov_b32 m0, s21
	s_nop 0
	global_load_lds_dwordx4 v130, s[48:49]
	s_add_i32 m0, s21, 0x2000
	s_nop 0
	global_load_lds_dwordx4 v142, s[48:49]
	s_mov_b32 m0, s12
	s_nop 0
	global_load_lds_dwordx4 v146, s[44:45]
	s_mov_b32 m0, s13
	s_nop 0
	global_load_lds_dwordx4 v144, s[44:45]
	s_waitcnt vmcnt(8) lgkmcnt(0)
	s_barrier
	v_mfma_f32_16x16x32_bf16 v[60:63], v[182:185], v[214:217], v[60:63]
	v_mfma_f32_16x16x32_bf16 v[56:59], v[190:193], v[214:217], v[56:59]
	v_mfma_f32_16x16x32_bf16 v[52:55], v[182:185], v[222:225], v[52:55]
	v_mfma_f32_16x16x32_bf16 v[48:51], v[190:193], v[222:225], v[48:51]
	v_mfma_f32_16x16x32_bf16 v[36:39], v[182:185], v[230:233], v[36:39]
	v_mfma_f32_16x16x32_bf16 v[32:35], v[190:193], v[230:233], v[32:35]
	v_mfma_f32_16x16x32_bf16 v[20:23], v[182:185], v[238:241], v[20:23]
	v_mfma_f32_16x16x32_bf16 v[16:19], v[190:193], v[238:241], v[16:19]
	v_mfma_f32_16x16x32_bf16 v[60:63], v[186:189], v[218:221], v[60:63]
	v_mfma_f32_16x16x32_bf16 v[56:59], v[194:197], v[218:221], v[56:59]
	v_mfma_f32_16x16x32_bf16 v[52:55], v[186:189], v[226:229], v[52:55]
	v_mfma_f32_16x16x32_bf16 v[48:51], v[194:197], v[226:229], v[48:51]
	v_mfma_f32_16x16x32_bf16 v[36:39], v[186:189], v[234:237], v[36:39]
	v_mfma_f32_16x16x32_bf16 v[32:35], v[194:197], v[234:237], v[32:35]
	v_mfma_f32_16x16x32_bf16 v[20:23], v[186:189], v[242:245], v[20:23]
	v_mfma_f32_16x16x32_bf16 v[16:19], v[194:197], v[242:245], v[16:19]
	v_mfma_f32_16x16x32_bf16 v[44:47], v[198:201], v[214:217], v[44:47]
	v_mfma_f32_16x16x32_bf16 v[40:43], v[206:209], v[214:217], v[40:43]
	v_mfma_f32_16x16x32_bf16 v[28:31], v[198:201], v[222:225], v[28:31]
	v_mfma_f32_16x16x32_bf16 v[24:27], v[206:209], v[222:225], v[24:27]
	v_mfma_f32_16x16x32_bf16 v[12:15], v[198:201], v[230:233], v[12:15]
	v_mfma_f32_16x16x32_bf16 v[8:11], v[206:209], v[230:233], v[8:11]
	v_mfma_f32_16x16x32_bf16 v[4:7], v[198:201], v[238:241], v[4:7]
	v_mfma_f32_16x16x32_bf16 v[0:3], v[206:209], v[238:241], v[0:3]
	v_mfma_f32_16x16x32_bf16 v[44:47], v[202:205], v[218:221], v[44:47]
	v_mfma_f32_16x16x32_bf16 v[40:43], v[210:213], v[218:221], v[40:43]
	v_mfma_f32_16x16x32_bf16 v[28:31], v[202:205], v[226:229], v[28:31]
	v_mfma_f32_16x16x32_bf16 v[24:27], v[210:213], v[226:229], v[24:27]
	v_mfma_f32_16x16x32_bf16 v[12:15], v[202:205], v[234:237], v[12:15]
	v_mfma_f32_16x16x32_bf16 v[8:11], v[210:213], v[234:237], v[8:11]
	v_mfma_f32_16x16x32_bf16 v[4:7], v[202:205], v[242:245], v[4:7]
	v_mfma_f32_16x16x32_bf16 v[0:3], v[210:213], v[242:245], v[0:3]
	s_barrier
	v_add_u32_e32 v181, s34, v153
	ds_read_b128 v[182:185], v181
	ds_read_b128 v[186:189], v181 offset:1024
	ds_read_b128 v[190:193], v181 offset:2048
	ds_read_b128 v[194:197], v181 offset:3072
	v_add_u32_e32 v181, s35, v153
	ds_read_b128 v[198:201], v181
	ds_read_b128 v[202:205], v181 offset:1024
	ds_read_b128 v[206:209], v181 offset:2048
	ds_read_b128 v[210:213], v181 offset:3072
	s_add_u32 s44, s44, 0x40000
	s_addc_u32 s45, s45, 0
	s_mov_b32 m0, s20
	ds_read_b128 v[214:217], v155 offset:32768
	ds_read_b128 v[218:221], v155 offset:33792
	ds_read_b128 v[222:225], v155 offset:34816
	ds_read_b128 v[226:229], v155 offset:35840
	ds_read_b128 v[230:233], v155 offset:36864
	ds_read_b128 v[234:237], v155 offset:37888
	ds_read_b128 v[238:241], v155 offset:38912
	ds_read_b128 v[242:245], v155 offset:39936
	global_load_lds_dwordx4 v146, s[44:45]
	s_mov_b32 m0, s26
	s_nop 0
	global_load_lds_dwordx4 v144, s[44:45]
	s_waitcnt vmcnt(8) lgkmcnt(0)
	s_barrier
	v_mfma_f32_16x16x32_bf16 v[124:127], v[182:185], v[214:217], v[124:127]
	v_mfma_f32_16x16x32_bf16 v[120:123], v[190:193], v[214:217], v[120:123]
	v_mfma_f32_16x16x32_bf16 v[116:119], v[182:185], v[222:225], v[116:119]
	v_mfma_f32_16x16x32_bf16 v[112:115], v[190:193], v[222:225], v[112:115]
	v_mfma_f32_16x16x32_bf16 v[100:103], v[182:185], v[230:233], v[100:103]
	v_mfma_f32_16x16x32_bf16 v[96:99], v[190:193], v[230:233], v[96:99]
	v_mfma_f32_16x16x32_bf16 v[84:87], v[182:185], v[238:241], v[84:87]
	v_mfma_f32_16x16x32_bf16 v[80:83], v[190:193], v[238:241], v[80:83]
	v_mfma_f32_16x16x32_bf16 v[124:127], v[186:189], v[218:221], v[124:127]
	v_mfma_f32_16x16x32_bf16 v[120:123], v[194:197], v[218:221], v[120:123]
	v_mfma_f32_16x16x32_bf16 v[116:119], v[186:189], v[226:229], v[116:119]
	v_mfma_f32_16x16x32_bf16 v[112:115], v[194:197], v[226:229], v[112:115]
	v_mfma_f32_16x16x32_bf16 v[100:103], v[186:189], v[234:237], v[100:103]
	v_mfma_f32_16x16x32_bf16 v[96:99], v[194:197], v[234:237], v[96:99]
	v_mfma_f32_16x16x32_bf16 v[84:87], v[186:189], v[242:245], v[84:87]
	v_mfma_f32_16x16x32_bf16 v[80:83], v[194:197], v[242:245], v[80:83]
	v_mfma_f32_16x16x32_bf16 v[108:111], v[198:201], v[214:217], v[108:111]
	v_mfma_f32_16x16x32_bf16 v[104:107], v[206:209], v[214:217], v[104:107]
	v_mfma_f32_16x16x32_bf16 v[92:95], v[198:201], v[222:225], v[92:95]
	v_mfma_f32_16x16x32_bf16 v[88:91], v[206:209], v[222:225], v[88:91]
	v_mfma_f32_16x16x32_bf16 v[76:79], v[198:201], v[230:233], v[76:79]
	v_mfma_f32_16x16x32_bf16 v[72:75], v[206:209], v[230:233], v[72:75]
	v_mfma_f32_16x16x32_bf16 v[68:71], v[198:201], v[238:241], v[68:71]
	v_mfma_f32_16x16x32_bf16 v[64:67], v[206:209], v[238:241], v[64:67]
	v_mfma_f32_16x16x32_bf16 v[108:111], v[202:205], v[218:221], v[108:111]
	v_mfma_f32_16x16x32_bf16 v[104:107], v[210:213], v[218:221], v[104:107]
	v_mfma_f32_16x16x32_bf16 v[92:95], v[202:205], v[226:229], v[92:95]
	v_mfma_f32_16x16x32_bf16 v[88:91], v[210:213], v[226:229], v[88:91]
	v_mfma_f32_16x16x32_bf16 v[76:79], v[202:205], v[234:237], v[76:79]
	v_mfma_f32_16x16x32_bf16 v[72:75], v[210:213], v[234:237], v[72:75]
	v_mfma_f32_16x16x32_bf16 v[68:71], v[202:205], v[242:245], v[68:71]
	v_mfma_f32_16x16x32_bf16 v[64:67], v[210:213], v[242:245], v[64:67]
	s_barrier
	s_add_i32 s21, s34, s3
	s_mov_b32 m0, s21
	ds_read_b128 v[214:217], v155 offset:49152
	ds_read_b128 v[218:221], v155 offset:50176
	ds_read_b128 v[222:225], v155 offset:51200
	ds_read_b128 v[226:229], v155 offset:52224
	ds_read_b128 v[230:233], v155 offset:53248
	ds_read_b128 v[234:237], v155 offset:54272
	ds_read_b128 v[238:241], v155 offset:55296
	ds_read_b128 v[242:245], v155 offset:56320
	global_load_lds_dwordx4 v130, s[60:61]
	s_add_i32 m0, s21, 0x2000
	s_add_u32 s42, s42, 0x40080
	s_addc_u32 s43, s43, 0
	s_add_i32 s21, s35, s3
	global_load_lds_dwordx4 v142, s[60:61]
	s_mov_b32 m0, s21
	s_nop 0
	global_load_lds_dwordx4 v130, s[42:43]
	s_add_i32 m0, s21, 0x2000
	s_nop 0
	global_load_lds_dwordx4 v142, s[42:43]
	s_mov_b32 m0, s0
	s_nop 0
	global_load_lds_dwordx4 v146, s[62:63]
	s_mov_b32 m0, s1
	s_nop 0
	global_load_lds_dwordx4 v144, s[62:63]
	s_waitcnt vmcnt(8) lgkmcnt(0)
	s_barrier
	v_mfma_f32_16x16x32_bf16 v[60:63], v[182:185], v[214:217], v[60:63]
	v_mfma_f32_16x16x32_bf16 v[56:59], v[190:193], v[214:217], v[56:59]
	v_mfma_f32_16x16x32_bf16 v[52:55], v[182:185], v[222:225], v[52:55]
	v_mfma_f32_16x16x32_bf16 v[48:51], v[190:193], v[222:225], v[48:51]
	v_mfma_f32_16x16x32_bf16 v[36:39], v[182:185], v[230:233], v[36:39]
	v_mfma_f32_16x16x32_bf16 v[32:35], v[190:193], v[230:233], v[32:35]
	v_mfma_f32_16x16x32_bf16 v[20:23], v[182:185], v[238:241], v[20:23]
	v_mfma_f32_16x16x32_bf16 v[16:19], v[190:193], v[238:241], v[16:19]
	v_mfma_f32_16x16x32_bf16 v[60:63], v[186:189], v[218:221], v[60:63]
	v_mfma_f32_16x16x32_bf16 v[56:59], v[194:197], v[218:221], v[56:59]
	v_mfma_f32_16x16x32_bf16 v[52:55], v[186:189], v[226:229], v[52:55]
	v_mfma_f32_16x16x32_bf16 v[48:51], v[194:197], v[226:229], v[48:51]
	v_mfma_f32_16x16x32_bf16 v[36:39], v[186:189], v[234:237], v[36:39]
	v_mfma_f32_16x16x32_bf16 v[32:35], v[194:197], v[234:237], v[32:35]
	v_mfma_f32_16x16x32_bf16 v[20:23], v[186:189], v[242:245], v[20:23]
	v_mfma_f32_16x16x32_bf16 v[16:19], v[194:197], v[242:245], v[16:19]
	v_mfma_f32_16x16x32_bf16 v[44:47], v[198:201], v[214:217], v[44:47]
	v_mfma_f32_16x16x32_bf16 v[40:43], v[206:209], v[214:217], v[40:43]
	v_mfma_f32_16x16x32_bf16 v[28:31], v[198:201], v[222:225], v[28:31]
	v_mfma_f32_16x16x32_bf16 v[24:27], v[206:209], v[222:225], v[24:27]
	v_mfma_f32_16x16x32_bf16 v[12:15], v[198:201], v[230:233], v[12:15]
	v_mfma_f32_16x16x32_bf16 v[8:11], v[206:209], v[230:233], v[8:11]
	v_mfma_f32_16x16x32_bf16 v[4:7], v[198:201], v[238:241], v[4:7]
	v_mfma_f32_16x16x32_bf16 v[0:3], v[206:209], v[238:241], v[0:3]
	v_mfma_f32_16x16x32_bf16 v[44:47], v[202:205], v[218:221], v[44:47]
	v_mfma_f32_16x16x32_bf16 v[40:43], v[210:213], v[218:221], v[40:43]
	v_mfma_f32_16x16x32_bf16 v[28:31], v[202:205], v[226:229], v[28:31]
	v_mfma_f32_16x16x32_bf16 v[24:27], v[210:213], v[226:229], v[24:27]
	v_mfma_f32_16x16x32_bf16 v[12:15], v[202:205], v[234:237], v[12:15]
	v_mfma_f32_16x16x32_bf16 v[8:11], v[210:213], v[234:237], v[8:11]
	v_mfma_f32_16x16x32_bf16 v[4:7], v[202:205], v[242:245], v[4:7]
	v_mfma_f32_16x16x32_bf16 v[0:3], v[210:213], v[242:245], v[0:3]
	s_barrier
	s_add_i32 s46, s46, 2
	s_add_u32 s40, s40, 0x100
	s_addc_u32 s41, s41, 0
	s_add_u32 s38, s38, 0x100
	s_addc_u32 s39, s39, 0
	s_cmp_gt_u32 s46, 13
	s_cbranch_scc0 .LBB0_511

.LBB0_854:
	s_add_i32 s11, s48, -2
	s_add_u32 s29, s42, 0x100
	s_addc_u32 s49, s43, 0
	s_mov_b32 s44, 0
	v_add_u32_e32 v156, s22, v153
	ds_read_b128 v[182:185], v156
	ds_read_b128 v[186:189], v156 offset:1024
	ds_read_b128 v[190:193], v156 offset:2048
	ds_read_b128 v[194:197], v156 offset:3072
	v_add_u32_e32 v156, s23, v153
	ds_read_b128 v[198:201], v156
	ds_read_b128 v[202:205], v156 offset:1024
	ds_read_b128 v[206:209], v156 offset:2048
	ds_read_b128 v[210:213], v156 offset:3072
	s_add_i32 s50, s44, 2
	s_add_u32 s42, s40, 0x100
	s_addc_u32 s43, s41, 0
	s_cmp_eq_u32 s11, s44
	s_cselect_b32 s44, s36, s29
	s_cselect_b32 s47, s17, s43
	s_cselect_b32 s46, s16, s42
	s_cselect_b32 s45, s37, s49
	s_add_i32 m0, s12, 0xc000
	ds_read_b128 v[214:217], v155
	ds_read_b128 v[218:221], v155 offset:1024
	ds_read_b128 v[222:225], v155 offset:2048
	ds_read_b128 v[226:229], v155 offset:3072
	ds_read_b128 v[230:233], v155 offset:4096
	ds_read_b128 v[234:237], v155 offset:5120
	ds_read_b128 v[238:241], v155 offset:6144
	ds_read_b128 v[242:245], v155 offset:7168
	global_load_lds_dwordx4 v148, s[40:41]
	s_add_i32 m0, s12, 0xe000
	s_nop 0
	global_load_lds_dwordx4 v150, s[40:41]
	s_waitcnt vmcnt(8) lgkmcnt(0)
	s_barrier
	v_mfma_f32_16x16x32_bf16 v[124:127], v[182:185], v[214:217], 0
	v_mfma_f32_16x16x32_bf16 v[120:123], v[190:193], v[214:217], 0
	v_mfma_f32_16x16x32_bf16 v[116:119], v[182:185], v[222:225], 0
	v_mfma_f32_16x16x32_bf16 v[112:115], v[190:193], v[222:225], 0
	v_mfma_f32_16x16x32_bf16 v[100:103], v[182:185], v[230:233], 0
	v_mfma_f32_16x16x32_bf16 v[96:99], v[190:193], v[230:233], 0
	v_mfma_f32_16x16x32_bf16 v[84:87], v[182:185], v[238:241], 0
	v_mfma_f32_16x16x32_bf16 v[80:83], v[190:193], v[238:241], 0
	v_mfma_f32_16x16x32_bf16 v[124:127], v[186:189], v[218:221], v[124:127]
	v_mfma_f32_16x16x32_bf16 v[120:123], v[194:197], v[218:221], v[120:123]
	v_mfma_f32_16x16x32_bf16 v[116:119], v[186:189], v[226:229], v[116:119]
	v_mfma_f32_16x16x32_bf16 v[112:115], v[194:197], v[226:229], v[112:115]
	v_mfma_f32_16x16x32_bf16 v[100:103], v[186:189], v[234:237], v[100:103]
	v_mfma_f32_16x16x32_bf16 v[96:99], v[194:197], v[234:237], v[96:99]
	v_mfma_f32_16x16x32_bf16 v[84:87], v[186:189], v[242:245], v[84:87]
	v_mfma_f32_16x16x32_bf16 v[80:83], v[194:197], v[242:245], v[80:83]
	v_mfma_f32_16x16x32_bf16 v[108:111], v[198:201], v[214:217], 0
	v_mfma_f32_16x16x32_bf16 v[104:107], v[206:209], v[214:217], 0
	v_mfma_f32_16x16x32_bf16 v[92:95], v[198:201], v[222:225], 0
	v_mfma_f32_16x16x32_bf16 v[88:91], v[206:209], v[222:225], 0
	v_mfma_f32_16x16x32_bf16 v[76:79], v[198:201], v[230:233], 0
	v_mfma_f32_16x16x32_bf16 v[72:75], v[206:209], v[230:233], 0
	v_mfma_f32_16x16x32_bf16 v[68:71], v[198:201], v[238:241], 0
	v_mfma_f32_16x16x32_bf16 v[64:67], v[206:209], v[238:241], 0
	v_mfma_f32_16x16x32_bf16 v[108:111], v[202:205], v[218:221], v[108:111]
	v_mfma_f32_16x16x32_bf16 v[104:107], v[210:213], v[218:221], v[104:107]
	v_mfma_f32_16x16x32_bf16 v[92:95], v[202:205], v[226:229], v[92:95]
	v_mfma_f32_16x16x32_bf16 v[88:91], v[210:213], v[226:229], v[88:91]
	v_mfma_f32_16x16x32_bf16 v[76:79], v[202:205], v[234:237], v[76:79]
	v_mfma_f32_16x16x32_bf16 v[72:75], v[210:213], v[234:237], v[72:75]
	v_mfma_f32_16x16x32_bf16 v[68:71], v[202:205], v[242:245], v[68:71]
	v_mfma_f32_16x16x32_bf16 v[64:67], v[210:213], v[242:245], v[64:67]
	s_barrier
	s_add_u32 s60, s44, 0x80
	s_addc_u32 s61, s45, 0
	s_add_u32 s62, s46, 0x80
	s_addc_u32 s63, s47, 0
	s_add_i32 s21, s22, s3
	s_mov_b32 m0, s21
	ds_read_b128 v[214:217], v155 offset:16384
	ds_read_b128 v[218:221], v155 offset:17408
	ds_read_b128 v[222:225], v155 offset:18432
	ds_read_b128 v[226:229], v155 offset:19456
	ds_read_b128 v[230:233], v155 offset:20480
	ds_read_b128 v[234:237], v155 offset:21504
	ds_read_b128 v[238:241], v155 offset:22528
	ds_read_b128 v[242:245], v155 offset:23552
	global_load_lds_dwordx4 v130, s[44:45]
	s_add_i32 m0, s21, 0x2000
	s_add_u32 s24, s44, 0x40000
	s_addc_u32 s25, s45, 0
	s_add_i32 s21, s23, s3
	global_load_lds_dwordx4 v146, s[44:45]
	s_mov_b32 m0, s21
	s_nop 0
	global_load_lds_dwordx4 v130, s[24:25]
	s_add_i32 m0, s21, 0x2000
	s_nop 0
	global_load_lds_dwordx4 v146, s[24:25]
	s_mov_b32 m0, s12
	s_nop 0
	global_load_lds_dwordx4 v142, s[46:47]
	s_mov_b32 m0, s13
	s_nop 0
	global_load_lds_dwordx4 v144, s[46:47]
	s_waitcnt vmcnt(8) lgkmcnt(0)
	s_barrier
	v_mfma_f32_16x16x32_bf16 v[60:63], v[182:185], v[214:217], 0
	v_mfma_f32_16x16x32_bf16 v[56:59], v[190:193], v[214:217], 0
	v_mfma_f32_16x16x32_bf16 v[52:55], v[182:185], v[222:225], 0
	v_mfma_f32_16x16x32_bf16 v[48:51], v[190:193], v[222:225], 0
	v_mfma_f32_16x16x32_bf16 v[36:39], v[182:185], v[230:233], 0
	v_mfma_f32_16x16x32_bf16 v[32:35], v[190:193], v[230:233], 0
	v_mfma_f32_16x16x32_bf16 v[20:23], v[182:185], v[238:241], 0
	v_mfma_f32_16x16x32_bf16 v[16:19], v[190:193], v[238:241], 0
	v_mfma_f32_16x16x32_bf16 v[60:63], v[186:189], v[218:221], v[60:63]
	v_mfma_f32_16x16x32_bf16 v[56:59], v[194:197], v[218:221], v[56:59]
	v_mfma_f32_16x16x32_bf16 v[52:55], v[186:189], v[226:229], v[52:55]
	v_mfma_f32_16x16x32_bf16 v[48:51], v[194:197], v[226:229], v[48:51]
	v_mfma_f32_16x16x32_bf16 v[36:39], v[186:189], v[234:237], v[36:39]
	v_mfma_f32_16x16x32_bf16 v[32:35], v[194:197], v[234:237], v[32:35]
	v_mfma_f32_16x16x32_bf16 v[20:23], v[186:189], v[242:245], v[20:23]
	v_mfma_f32_16x16x32_bf16 v[16:19], v[194:197], v[242:245], v[16:19]
	v_mfma_f32_16x16x32_bf16 v[44:47], v[198:201], v[214:217], 0
	v_mfma_f32_16x16x32_bf16 v[40:43], v[206:209], v[214:217], 0
	v_mfma_f32_16x16x32_bf16 v[28:31], v[198:201], v[222:225], 0
	v_mfma_f32_16x16x32_bf16 v[24:27], v[206:209], v[222:225], 0
	v_mfma_f32_16x16x32_bf16 v[12:15], v[198:201], v[230:233], 0
	v_mfma_f32_16x16x32_bf16 v[8:11], v[206:209], v[230:233], 0
	v_mfma_f32_16x16x32_bf16 v[4:7], v[198:201], v[238:241], 0
	v_mfma_f32_16x16x32_bf16 v[0:3], v[206:209], v[238:241], 0
	v_mfma_f32_16x16x32_bf16 v[44:47], v[202:205], v[218:221], v[44:47]
	v_mfma_f32_16x16x32_bf16 v[40:43], v[210:213], v[218:221], v[40:43]
	v_mfma_f32_16x16x32_bf16 v[28:31], v[202:205], v[226:229], v[28:31]
	v_mfma_f32_16x16x32_bf16 v[24:27], v[210:213], v[226:229], v[24:27]
	v_mfma_f32_16x16x32_bf16 v[12:15], v[202:205], v[234:237], v[12:15]
	v_mfma_f32_16x16x32_bf16 v[8:11], v[210:213], v[234:237], v[8:11]
	v_mfma_f32_16x16x32_bf16 v[4:7], v[202:205], v[242:245], v[4:7]
	v_mfma_f32_16x16x32_bf16 v[0:3], v[210:213], v[242:245], v[0:3]
	s_barrier
	v_add_u32_e32 v181, s34, v153
	ds_read_b128 v[182:185], v181
	ds_read_b128 v[186:189], v181 offset:1024
	ds_read_b128 v[190:193], v181 offset:2048
	ds_read_b128 v[194:197], v181 offset:3072
	v_add_u32_e32 v181, s35, v153
	ds_read_b128 v[198:201], v181
	ds_read_b128 v[202:205], v181 offset:1024
	ds_read_b128 v[206:209], v181 offset:2048
	ds_read_b128 v[210:213], v181 offset:3072
	s_add_u32 s24, s46, 0xc0000
	s_addc_u32 s25, s47, 0
	s_mov_b32 m0, s18
	ds_read_b128 v[214:217], v155 offset:32768
	ds_read_b128 v[218:221], v155 offset:33792
	ds_read_b128 v[222:225], v155 offset:34816
	ds_read_b128 v[226:229], v155 offset:35840
	ds_read_b128 v[230:233], v155 offset:36864
	ds_read_b128 v[234:237], v155 offset:37888
	ds_read_b128 v[238:241], v155 offset:38912
	ds_read_b128 v[242:245], v155 offset:39936
	global_load_lds_dwordx4 v142, s[24:25]
	s_mov_b32 m0, s19
	s_nop 0
	global_load_lds_dwordx4 v144, s[24:25]
	s_waitcnt vmcnt(8) lgkmcnt(0)
	s_barrier
	v_mfma_f32_16x16x32_bf16 v[124:127], v[182:185], v[214:217], v[124:127]
	v_mfma_f32_16x16x32_bf16 v[120:123], v[190:193], v[214:217], v[120:123]
	v_mfma_f32_16x16x32_bf16 v[116:119], v[182:185], v[222:225], v[116:119]
	v_mfma_f32_16x16x32_bf16 v[112:115], v[190:193], v[222:225], v[112:115]
	v_mfma_f32_16x16x32_bf16 v[100:103], v[182:185], v[230:233], v[100:103]
	v_mfma_f32_16x16x32_bf16 v[96:99], v[190:193], v[230:233], v[96:99]
	v_mfma_f32_16x16x32_bf16 v[84:87], v[182:185], v[238:241], v[84:87]
	v_mfma_f32_16x16x32_bf16 v[80:83], v[190:193], v[238:241], v[80:83]
	v_mfma_f32_16x16x32_bf16 v[124:127], v[186:189], v[218:221], v[124:127]
	v_mfma_f32_16x16x32_bf16 v[120:123], v[194:197], v[218:221], v[120:123]
	v_mfma_f32_16x16x32_bf16 v[116:119], v[186:189], v[226:229], v[116:119]
	v_mfma_f32_16x16x32_bf16 v[112:115], v[194:197], v[226:229], v[112:115]
	v_mfma_f32_16x16x32_bf16 v[100:103], v[186:189], v[234:237], v[100:103]
	v_mfma_f32_16x16x32_bf16 v[96:99], v[194:197], v[234:237], v[96:99]
	v_mfma_f32_16x16x32_bf16 v[84:87], v[186:189], v[242:245], v[84:87]
	v_mfma_f32_16x16x32_bf16 v[80:83], v[194:197], v[242:245], v[80:83]
	v_mfma_f32_16x16x32_bf16 v[108:111], v[198:201], v[214:217], v[108:111]
	v_mfma_f32_16x16x32_bf16 v[104:107], v[206:209], v[214:217], v[104:107]
	v_mfma_f32_16x16x32_bf16 v[92:95], v[198:201], v[222:225], v[92:95]
	v_mfma_f32_16x16x32_bf16 v[88:91], v[206:209], v[222:225], v[88:91]
	v_mfma_f32_16x16x32_bf16 v[76:79], v[198:201], v[230:233], v[76:79]
	v_mfma_f32_16x16x32_bf16 v[72:75], v[206:209], v[230:233], v[72:75]
	v_mfma_f32_16x16x32_bf16 v[68:71], v[198:201], v[238:241], v[68:71]
	v_mfma_f32_16x16x32_bf16 v[64:67], v[206:209], v[238:241], v[64:67]
	v_mfma_f32_16x16x32_bf16 v[108:111], v[202:205], v[218:221], v[108:111]
	v_mfma_f32_16x16x32_bf16 v[104:107], v[210:213], v[218:221], v[104:107]
	v_mfma_f32_16x16x32_bf16 v[92:95], v[202:205], v[226:229], v[92:95]
	v_mfma_f32_16x16x32_bf16 v[88:91], v[210:213], v[226:229], v[88:91]
	v_mfma_f32_16x16x32_bf16 v[76:79], v[202:205], v[234:237], v[76:79]
	v_mfma_f32_16x16x32_bf16 v[72:75], v[210:213], v[234:237], v[72:75]
	v_mfma_f32_16x16x32_bf16 v[68:71], v[202:205], v[242:245], v[68:71]
	v_mfma_f32_16x16x32_bf16 v[64:67], v[210:213], v[242:245], v[64:67]
	s_barrier
	s_add_i32 s21, s34, s3
	s_mov_b32 m0, s21
	ds_read_b128 v[214:217], v155 offset:49152
	ds_read_b128 v[218:221], v155 offset:50176
	ds_read_b128 v[222:225], v155 offset:51200
	ds_read_b128 v[226:229], v155 offset:52224
	ds_read_b128 v[230:233], v155 offset:53248
	ds_read_b128 v[234:237], v155 offset:54272
	ds_read_b128 v[238:241], v155 offset:55296
	ds_read_b128 v[242:245], v155 offset:56320
	global_load_lds_dwordx4 v130, s[60:61]
	s_add_i32 m0, s21, 0x2000
	s_add_u32 s24, s44, 0x40080
	s_addc_u32 s25, s45, 0
	s_add_i32 s21, s35, s3
	global_load_lds_dwordx4 v146, s[60:61]
	s_mov_b32 m0, s21
	s_nop 0
	global_load_lds_dwordx4 v130, s[24:25]
	s_add_i32 m0, s21, 0x2000
	s_nop 0
	global_load_lds_dwordx4 v146, s[24:25]
	s_mov_b32 m0, s20
	s_nop 0
	global_load_lds_dwordx4 v142, s[62:63]
	s_mov_b32 m0, s26
	s_nop 0
	global_load_lds_dwordx4 v144, s[62:63]
	s_waitcnt vmcnt(8) lgkmcnt(0)
	s_barrier
	v_mfma_f32_16x16x32_bf16 v[60:63], v[182:185], v[214:217], v[60:63]
	v_mfma_f32_16x16x32_bf16 v[56:59], v[190:193], v[214:217], v[56:59]
	v_mfma_f32_16x16x32_bf16 v[52:55], v[182:185], v[222:225], v[52:55]
	v_mfma_f32_16x16x32_bf16 v[48:51], v[190:193], v[222:225], v[48:51]
	v_mfma_f32_16x16x32_bf16 v[36:39], v[182:185], v[230:233], v[36:39]
	v_mfma_f32_16x16x32_bf16 v[32:35], v[190:193], v[230:233], v[32:35]
	v_mfma_f32_16x16x32_bf16 v[20:23], v[182:185], v[238:241], v[20:23]
	v_mfma_f32_16x16x32_bf16 v[16:19], v[190:193], v[238:241], v[16:19]
	v_mfma_f32_16x16x32_bf16 v[60:63], v[186:189], v[218:221], v[60:63]
	v_mfma_f32_16x16x32_bf16 v[56:59], v[194:197], v[218:221], v[56:59]
	v_mfma_f32_16x16x32_bf16 v[52:55], v[186:189], v[226:229], v[52:55]
	v_mfma_f32_16x16x32_bf16 v[48:51], v[194:197], v[226:229], v[48:51]
	v_mfma_f32_16x16x32_bf16 v[36:39], v[186:189], v[234:237], v[36:39]
	v_mfma_f32_16x16x32_bf16 v[32:35], v[194:197], v[234:237], v[32:35]
	v_mfma_f32_16x16x32_bf16 v[20:23], v[186:189], v[242:245], v[20:23]
	v_mfma_f32_16x16x32_bf16 v[16:19], v[194:197], v[242:245], v[16:19]
	v_mfma_f32_16x16x32_bf16 v[44:47], v[198:201], v[214:217], v[44:47]
	v_mfma_f32_16x16x32_bf16 v[40:43], v[206:209], v[214:217], v[40:43]
	v_mfma_f32_16x16x32_bf16 v[28:31], v[198:201], v[222:225], v[28:31]
	v_mfma_f32_16x16x32_bf16 v[24:27], v[206:209], v[222:225], v[24:27]
	v_mfma_f32_16x16x32_bf16 v[12:15], v[198:201], v[230:233], v[12:15]
	v_mfma_f32_16x16x32_bf16 v[8:11], v[206:209], v[230:233], v[8:11]
	v_mfma_f32_16x16x32_bf16 v[4:7], v[198:201], v[238:241], v[4:7]
	v_mfma_f32_16x16x32_bf16 v[0:3], v[206:209], v[238:241], v[0:3]
	v_mfma_f32_16x16x32_bf16 v[44:47], v[202:205], v[218:221], v[44:47]
	v_mfma_f32_16x16x32_bf16 v[40:43], v[210:213], v[218:221], v[40:43]
	v_mfma_f32_16x16x32_bf16 v[28:31], v[202:205], v[226:229], v[28:31]
	v_mfma_f32_16x16x32_bf16 v[24:27], v[210:213], v[226:229], v[24:27]
	v_mfma_f32_16x16x32_bf16 v[12:15], v[202:205], v[234:237], v[12:15]
	v_mfma_f32_16x16x32_bf16 v[8:11], v[210:213], v[234:237], v[8:11]
	v_mfma_f32_16x16x32_bf16 v[4:7], v[202:205], v[242:245], v[4:7]
	v_mfma_f32_16x16x32_bf16 v[0:3], v[210:213], v[242:245], v[0:3]
	s_barrier
	s_add_u32 s29, s29, 0x100
	s_addc_u32 s49, s49, 0
	s_cmp_ge_i32 s50, s48
	s_mov_b64 s[40:41], s[42:43]
	s_mov_b32 s44, s50
	s_cbranch_scc1 .Lpeel_done_855
.LBB0_855:
	v_add_u32_e32 v156, s22, v153
	ds_read_b128 v[182:185], v156
	ds_read_b128 v[186:189], v156 offset:1024
	ds_read_b128 v[190:193], v156 offset:2048
	ds_read_b128 v[194:197], v156 offset:3072
	v_add_u32_e32 v156, s23, v153
	ds_read_b128 v[198:201], v156
	ds_read_b128 v[202:205], v156 offset:1024
	ds_read_b128 v[206:209], v156 offset:2048
	ds_read_b128 v[210:213], v156 offset:3072
	s_add_i32 s50, s44, 2
	s_add_u32 s42, s40, 0x100
	s_addc_u32 s43, s41, 0
	s_cmp_eq_u32 s11, s44
	s_cselect_b32 s44, s36, s29
	s_cselect_b32 s47, s17, s43
	s_cselect_b32 s46, s16, s42
	s_cselect_b32 s45, s37, s49
	s_add_i32 m0, s12, 0xc000
	ds_read_b128 v[214:217], v155
	ds_read_b128 v[218:221], v155 offset:1024
	ds_read_b128 v[222:225], v155 offset:2048
	ds_read_b128 v[226:229], v155 offset:3072
	ds_read_b128 v[230:233], v155 offset:4096
	ds_read_b128 v[234:237], v155 offset:5120
	ds_read_b128 v[238:241], v155 offset:6144
	ds_read_b128 v[242:245], v155 offset:7168
	global_load_lds_dwordx4 v148, s[40:41]
	s_add_i32 m0, s12, 0xe000
	s_nop 0
	global_load_lds_dwordx4 v150, s[40:41]
	s_waitcnt vmcnt(8) lgkmcnt(0)
	s_barrier
	v_mfma_f32_16x16x32_bf16 v[124:127], v[182:185], v[214:217], v[124:127]
	v_mfma_f32_16x16x32_bf16 v[120:123], v[190:193], v[214:217], v[120:123]
	v_mfma_f32_16x16x32_bf16 v[116:119], v[182:185], v[222:225], v[116:119]
	v_mfma_f32_16x16x32_bf16 v[112:115], v[190:193], v[222:225], v[112:115]
	v_mfma_f32_16x16x32_bf16 v[100:103], v[182:185], v[230:233], v[100:103]
	v_mfma_f32_16x16x32_bf16 v[96:99], v[190:193], v[230:233], v[96:99]
	v_mfma_f32_16x16x32_bf16 v[84:87], v[182:185], v[238:241], v[84:87]
	v_mfma_f32_16x16x32_bf16 v[80:83], v[190:193], v[238:241], v[80:83]
	v_mfma_f32_16x16x32_bf16 v[124:127], v[186:189], v[218:221], v[124:127]
	v_mfma_f32_16x16x32_bf16 v[120:123], v[194:197], v[218:221], v[120:123]
	v_mfma_f32_16x16x32_bf16 v[116:119], v[186:189], v[226:229], v[116:119]
	v_mfma_f32_16x16x32_bf16 v[112:115], v[194:197], v[226:229], v[112:115]
	v_mfma_f32_16x16x32_bf16 v[100:103], v[186:189], v[234:237], v[100:103]
	v_mfma_f32_16x16x32_bf16 v[96:99], v[194:197], v[234:237], v[96:99]
	v_mfma_f32_16x16x32_bf16 v[84:87], v[186:189], v[242:245], v[84:87]
	v_mfma_f32_16x16x32_bf16 v[80:83], v[194:197], v[242:245], v[80:83]
	v_mfma_f32_16x16x32_bf16 v[108:111], v[198:201], v[214:217], v[108:111]
	v_mfma_f32_16x16x32_bf16 v[104:107], v[206:209], v[214:217], v[104:107]
	v_mfma_f32_16x16x32_bf16 v[92:95], v[198:201], v[222:225], v[92:95]
	v_mfma_f32_16x16x32_bf16 v[88:91], v[206:209], v[222:225], v[88:91]
	v_mfma_f32_16x16x32_bf16 v[76:79], v[198:201], v[230:233], v[76:79]
	v_mfma_f32_16x16x32_bf16 v[72:75], v[206:209], v[230:233], v[72:75]
	v_mfma_f32_16x16x32_bf16 v[68:71], v[198:201], v[238:241], v[68:71]
	v_mfma_f32_16x16x32_bf16 v[64:67], v[206:209], v[238:241], v[64:67]
	v_mfma_f32_16x16x32_bf16 v[108:111], v[202:205], v[218:221], v[108:111]
	v_mfma_f32_16x16x32_bf16 v[104:107], v[210:213], v[218:221], v[104:107]
	v_mfma_f32_16x16x32_bf16 v[92:95], v[202:205], v[226:229], v[92:95]
	v_mfma_f32_16x16x32_bf16 v[88:91], v[210:213], v[226:229], v[88:91]
	v_mfma_f32_16x16x32_bf16 v[76:79], v[202:205], v[234:237], v[76:79]
	v_mfma_f32_16x16x32_bf16 v[72:75], v[210:213], v[234:237], v[72:75]
	v_mfma_f32_16x16x32_bf16 v[68:71], v[202:205], v[242:245], v[68:71]
	v_mfma_f32_16x16x32_bf16 v[64:67], v[210:213], v[242:245], v[64:67]
	s_barrier
	s_add_u32 s60, s44, 0x80
	s_addc_u32 s61, s45, 0
	s_add_u32 s62, s46, 0x80
	s_addc_u32 s63, s47, 0
	s_add_i32 s21, s22, s3
	s_mov_b32 m0, s21
	ds_read_b128 v[214:217], v155 offset:16384
	ds_read_b128 v[218:221], v155 offset:17408
	ds_read_b128 v[222:225], v155 offset:18432
	ds_read_b128 v[226:229], v155 offset:19456
	ds_read_b128 v[230:233], v155 offset:20480
	ds_read_b128 v[234:237], v155 offset:21504
	ds_read_b128 v[238:241], v155 offset:22528
	ds_read_b128 v[242:245], v155 offset:23552
	global_load_lds_dwordx4 v130, s[44:45]
	s_add_i32 m0, s21, 0x2000
	s_add_u32 s24, s44, 0x40000
	s_addc_u32 s25, s45, 0
	s_add_i32 s21, s23, s3
	global_load_lds_dwordx4 v146, s[44:45]
	s_mov_b32 m0, s21
	s_nop 0
	global_load_lds_dwordx4 v130, s[24:25]
	s_add_i32 m0, s21, 0x2000
	s_nop 0
	global_load_lds_dwordx4 v146, s[24:25]
	s_mov_b32 m0, s12
	s_nop 0
	global_load_lds_dwordx4 v142, s[46:47]
	s_mov_b32 m0, s13
	s_nop 0
	global_load_lds_dwordx4 v144, s[46:47]
	s_waitcnt vmcnt(8) lgkmcnt(0)
	s_barrier
	v_mfma_f32_16x16x32_bf16 v[60:63], v[182:185], v[214:217], v[60:63]
	v_mfma_f32_16x16x32_bf16 v[56:59], v[190:193], v[214:217], v[56:59]
	v_mfma_f32_16x16x32_bf16 v[52:55], v[182:185], v[222:225], v[52:55]
	v_mfma_f32_16x16x32_bf16 v[48:51], v[190:193], v[222:225], v[48:51]
	v_mfma_f32_16x16x32_bf16 v[36:39], v[182:185], v[230:233], v[36:39]
	v_mfma_f32_16x16x32_bf16 v[32:35], v[190:193], v[230:233], v[32:35]
	v_mfma_f32_16x16x32_bf16 v[20:23], v[182:185], v[238:241], v[20:23]
	v_mfma_f32_16x16x32_bf16 v[16:19], v[190:193], v[238:241], v[16:19]
	v_mfma_f32_16x16x32_bf16 v[60:63], v[186:189], v[218:221], v[60:63]
	v_mfma_f32_16x16x32_bf16 v[56:59], v[194:197], v[218:221], v[56:59]
	v_mfma_f32_16x16x32_bf16 v[52:55], v[186:189], v[226:229], v[52:55]
	v_mfma_f32_16x16x32_bf16 v[48:51], v[194:197], v[226:229], v[48:51]
	v_mfma_f32_16x16x32_bf16 v[36:39], v[186:189], v[234:237], v[36:39]
	v_mfma_f32_16x16x32_bf16 v[32:35], v[194:197], v[234:237], v[32:35]
	v_mfma_f32_16x16x32_bf16 v[20:23], v[186:189], v[242:245], v[20:23]
	v_mfma_f32_16x16x32_bf16 v[16:19], v[194:197], v[242:245], v[16:19]
	v_mfma_f32_16x16x32_bf16 v[44:47], v[198:201], v[214:217], v[44:47]
	v_mfma_f32_16x16x32_bf16 v[40:43], v[206:209], v[214:217], v[40:43]
	v_mfma_f32_16x16x32_bf16 v[28:31], v[198:201], v[222:225], v[28:31]
	v_mfma_f32_16x16x32_bf16 v[24:27], v[206:209], v[222:225], v[24:27]
	v_mfma_f32_16x16x32_bf16 v[12:15], v[198:201], v[230:233], v[12:15]
	v_mfma_f32_16x16x32_bf16 v[8:11], v[206:209], v[230:233], v[8:11]
	v_mfma_f32_16x16x32_bf16 v[4:7], v[198:201], v[238:241], v[4:7]
	v_mfma_f32_16x16x32_bf16 v[0:3], v[206:209], v[238:241], v[0:3]
	v_mfma_f32_16x16x32_bf16 v[44:47], v[202:205], v[218:221], v[44:47]
	v_mfma_f32_16x16x32_bf16 v[40:43], v[210:213], v[218:221], v[40:43]
	v_mfma_f32_16x16x32_bf16 v[28:31], v[202:205], v[226:229], v[28:31]
	v_mfma_f32_16x16x32_bf16 v[24:27], v[210:213], v[226:229], v[24:27]
	v_mfma_f32_16x16x32_bf16 v[12:15], v[202:205], v[234:237], v[12:15]
	v_mfma_f32_16x16x32_bf16 v[8:11], v[210:213], v[234:237], v[8:11]
	v_mfma_f32_16x16x32_bf16 v[4:7], v[202:205], v[242:245], v[4:7]
	v_mfma_f32_16x16x32_bf16 v[0:3], v[210:213], v[242:245], v[0:3]
	s_barrier
	v_add_u32_e32 v181, s34, v153
	ds_read_b128 v[182:185], v181
	ds_read_b128 v[186:189], v181 offset:1024
	ds_read_b128 v[190:193], v181 offset:2048
	ds_read_b128 v[194:197], v181 offset:3072
	v_add_u32_e32 v181, s35, v153
	ds_read_b128 v[198:201], v181
	ds_read_b128 v[202:205], v181 offset:1024
	ds_read_b128 v[206:209], v181 offset:2048
	ds_read_b128 v[210:213], v181 offset:3072
	s_add_u32 s24, s46, 0xc0000
	s_addc_u32 s25, s47, 0
	s_mov_b32 m0, s18
	ds_read_b128 v[214:217], v155 offset:32768
	ds_read_b128 v[218:221], v155 offset:33792
	ds_read_b128 v[222:225], v155 offset:34816
	ds_read_b128 v[226:229], v155 offset:35840
	ds_read_b128 v[230:233], v155 offset:36864
	ds_read_b128 v[234:237], v155 offset:37888
	ds_read_b128 v[238:241], v155 offset:38912
	ds_read_b128 v[242:245], v155 offset:39936
	global_load_lds_dwordx4 v142, s[24:25]
	s_mov_b32 m0, s19
	s_nop 0
	global_load_lds_dwordx4 v144, s[24:25]
	s_waitcnt vmcnt(8) lgkmcnt(0)
	s_barrier
	v_mfma_f32_16x16x32_bf16 v[124:127], v[182:185], v[214:217], v[124:127]
	v_mfma_f32_16x16x32_bf16 v[120:123], v[190:193], v[214:217], v[120:123]
	v_mfma_f32_16x16x32_bf16 v[116:119], v[182:185], v[222:225], v[116:119]
	v_mfma_f32_16x16x32_bf16 v[112:115], v[190:193], v[222:225], v[112:115]
	v_mfma_f32_16x16x32_bf16 v[100:103], v[182:185], v[230:233], v[100:103]
	v_mfma_f32_16x16x32_bf16 v[96:99], v[190:193], v[230:233], v[96:99]
	v_mfma_f32_16x16x32_bf16 v[84:87], v[182:185], v[238:241], v[84:87]
	v_mfma_f32_16x16x32_bf16 v[80:83], v[190:193], v[238:241], v[80:83]
	v_mfma_f32_16x16x32_bf16 v[124:127], v[186:189], v[218:221], v[124:127]
	v_mfma_f32_16x16x32_bf16 v[120:123], v[194:197], v[218:221], v[120:123]
	v_mfma_f32_16x16x32_bf16 v[116:119], v[186:189], v[226:229], v[116:119]
	v_mfma_f32_16x16x32_bf16 v[112:115], v[194:197], v[226:229], v[112:115]
	v_mfma_f32_16x16x32_bf16 v[100:103], v[186:189], v[234:237], v[100:103]
	v_mfma_f32_16x16x32_bf16 v[96:99], v[194:197], v[234:237], v[96:99]
	v_mfma_f32_16x16x32_bf16 v[84:87], v[186:189], v[242:245], v[84:87]
	v_mfma_f32_16x16x32_bf16 v[80:83], v[194:197], v[242:245], v[80:83]
	v_mfma_f32_16x16x32_bf16 v[108:111], v[198:201], v[214:217], v[108:111]
	v_mfma_f32_16x16x32_bf16 v[104:107], v[206:209], v[214:217], v[104:107]
	v_mfma_f32_16x16x32_bf16 v[92:95], v[198:201], v[222:225], v[92:95]
	v_mfma_f32_16x16x32_bf16 v[88:91], v[206:209], v[222:225], v[88:91]
	v_mfma_f32_16x16x32_bf16 v[76:79], v[198:201], v[230:233], v[76:79]
	v_mfma_f32_16x16x32_bf16 v[72:75], v[206:209], v[230:233], v[72:75]
	v_mfma_f32_16x16x32_bf16 v[68:71], v[198:201], v[238:241], v[68:71]
	v_mfma_f32_16x16x32_bf16 v[64:67], v[206:209], v[238:241], v[64:67]
	v_mfma_f32_16x16x32_bf16 v[108:111], v[202:205], v[218:221], v[108:111]
	v_mfma_f32_16x16x32_bf16 v[104:107], v[210:213], v[218:221], v[104:107]
	v_mfma_f32_16x16x32_bf16 v[92:95], v[202:205], v[226:229], v[92:95]
	v_mfma_f32_16x16x32_bf16 v[88:91], v[210:213], v[226:229], v[88:91]
	v_mfma_f32_16x16x32_bf16 v[76:79], v[202:205], v[234:237], v[76:79]
	v_mfma_f32_16x16x32_bf16 v[72:75], v[210:213], v[234:237], v[72:75]
	v_mfma_f32_16x16x32_bf16 v[68:71], v[202:205], v[242:245], v[68:71]
	v_mfma_f32_16x16x32_bf16 v[64:67], v[210:213], v[242:245], v[64:67]
	s_barrier
	s_add_i32 s21, s34, s3
	s_mov_b32 m0, s21
	ds_read_b128 v[214:217], v155 offset:49152
	ds_read_b128 v[218:221], v155 offset:50176
	ds_read_b128 v[222:225], v155 offset:51200
	ds_read_b128 v[226:229], v155 offset:52224
	ds_read_b128 v[230:233], v155 offset:53248
	ds_read_b128 v[234:237], v155 offset:54272
	ds_read_b128 v[238:241], v155 offset:55296
	ds_read_b128 v[242:245], v155 offset:56320
	global_load_lds_dwordx4 v130, s[60:61]
	s_add_i32 m0, s21, 0x2000
	s_add_u32 s24, s44, 0x40080
	s_addc_u32 s25, s45, 0
	s_add_i32 s21, s35, s3
	global_load_lds_dwordx4 v146, s[60:61]
	s_mov_b32 m0, s21
	s_nop 0
	global_load_lds_dwordx4 v130, s[24:25]
	s_add_i32 m0, s21, 0x2000
	s_nop 0
	global_load_lds_dwordx4 v146, s[24:25]
	s_mov_b32 m0, s20
	s_nop 0
	global_load_lds_dwordx4 v142, s[62:63]
	s_mov_b32 m0, s26
	s_nop 0
	global_load_lds_dwordx4 v144, s[62:63]
	s_waitcnt vmcnt(8) lgkmcnt(0)
	s_barrier
	v_mfma_f32_16x16x32_bf16 v[60:63], v[182:185], v[214:217], v[60:63]
	v_mfma_f32_16x16x32_bf16 v[56:59], v[190:193], v[214:217], v[56:59]
	v_mfma_f32_16x16x32_bf16 v[52:55], v[182:185], v[222:225], v[52:55]
	v_mfma_f32_16x16x32_bf16 v[48:51], v[190:193], v[222:225], v[48:51]
	v_mfma_f32_16x16x32_bf16 v[36:39], v[182:185], v[230:233], v[36:39]
	v_mfma_f32_16x16x32_bf16 v[32:35], v[190:193], v[230:233], v[32:35]
	v_mfma_f32_16x16x32_bf16 v[20:23], v[182:185], v[238:241], v[20:23]
	v_mfma_f32_16x16x32_bf16 v[16:19], v[190:193], v[238:241], v[16:19]
	v_mfma_f32_16x16x32_bf16 v[60:63], v[186:189], v[218:221], v[60:63]
	v_mfma_f32_16x16x32_bf16 v[56:59], v[194:197], v[218:221], v[56:59]
	v_mfma_f32_16x16x32_bf16 v[52:55], v[186:189], v[226:229], v[52:55]
	v_mfma_f32_16x16x32_bf16 v[48:51], v[194:197], v[226:229], v[48:51]
	v_mfma_f32_16x16x32_bf16 v[36:39], v[186:189], v[234:237], v[36:39]
	v_mfma_f32_16x16x32_bf16 v[32:35], v[194:197], v[234:237], v[32:35]
	v_mfma_f32_16x16x32_bf16 v[20:23], v[186:189], v[242:245], v[20:23]
	v_mfma_f32_16x16x32_bf16 v[16:19], v[194:197], v[242:245], v[16:19]
	v_mfma_f32_16x16x32_bf16 v[44:47], v[198:201], v[214:217], v[44:47]
	v_mfma_f32_16x16x32_bf16 v[40:43], v[206:209], v[214:217], v[40:43]
	v_mfma_f32_16x16x32_bf16 v[28:31], v[198:201], v[222:225], v[28:31]
	v_mfma_f32_16x16x32_bf16 v[24:27], v[206:209], v[222:225], v[24:27]
	v_mfma_f32_16x16x32_bf16 v[12:15], v[198:201], v[230:233], v[12:15]
	v_mfma_f32_16x16x32_bf16 v[8:11], v[206:209], v[230:233], v[8:11]
	v_mfma_f32_16x16x32_bf16 v[4:7], v[198:201], v[238:241], v[4:7]
	v_mfma_f32_16x16x32_bf16 v[0:3], v[206:209], v[238:241], v[0:3]
	v_mfma_f32_16x16x32_bf16 v[44:47], v[202:205], v[218:221], v[44:47]
	v_mfma_f32_16x16x32_bf16 v[40:43], v[210:213], v[218:221], v[40:43]
	v_mfma_f32_16x16x32_bf16 v[28:31], v[202:205], v[226:229], v[28:31]
	v_mfma_f32_16x16x32_bf16 v[24:27], v[210:213], v[226:229], v[24:27]
	v_mfma_f32_16x16x32_bf16 v[12:15], v[202:205], v[234:237], v[12:15]
	v_mfma_f32_16x16x32_bf16 v[8:11], v[210:213], v[234:237], v[8:11]
	v_mfma_f32_16x16x32_bf16 v[4:7], v[202:205], v[242:245], v[4:7]
	v_mfma_f32_16x16x32_bf16 v[0:3], v[210:213], v[242:245], v[0:3]
	s_barrier
	s_add_u32 s29, s29, 0x100
	s_addc_u32 s49, s49, 0
	s_cmp_ge_i32 s50, s48
	s_mov_b64 s[40:41], s[42:43]
	s_mov_b32 s44, s50
	s_cbranch_scc0 .LBB0_855

.LBB0_871:
	s_ashr_i32 s17, s16, 31
	s_lshl_b64 s[18:19], s[16:17], 19
	v_readlane_b32 s24, v252, 27
	v_readlane_b32 s25, v252, 28
	s_add_u32 s28, s24, s18
	s_addc_u32 s29, s25, s19
	s_and_b64 s[18:19], s[4:5], exec
	s_cselect_b32 s17, s29, s41
	s_cselect_b32 s18, s28, s40
	s_ashr_i32 s11, s10, 31
	s_lshl_b64 s[36:37], s[10:11], 19
	v_readlane_b32 s11, v252, 23
	s_add_u32 s36, s11, s36
	v_readlane_b32 s11, v252, 24
	s_addc_u32 s37, s11, s37
	s_and_b64 s[38:39], s[4:5], exec
	s_cselect_b32 s11, s37, s43
	s_cselect_b32 s19, s36, s42
	s_add_u32 s40, s40, 0x40080
	s_addc_u32 s41, s41, 0
	s_add_u32 s38, s42, 0x100
	s_addc_u32 s39, s43, 0
	s_mov_b32 s46, -2
	v_add_u32_e32 v156, s22, v153
	ds_read_b128 v[182:185], v156
	ds_read_b128 v[186:189], v156 offset:1024
	ds_read_b128 v[190:193], v156 offset:2048
	ds_read_b128 v[194:197], v156 offset:3072
	v_add_u32_e32 v156, s23, v153
	ds_read_b128 v[198:201], v156
	ds_read_b128 v[202:205], v156 offset:1024
	ds_read_b128 v[206:209], v156 offset:2048
	ds_read_b128 v[210:213], v156 offset:3072
	s_add_u32 s21, s40, 0xfffc0080
	s_addc_u32 s24, s41, -1
	s_cmp_eq_u32 s46, 12
	s_cselect_b32 s45, s17, s24
	s_cselect_b32 s44, s18, s21
	s_cselect_b32 s43, s11, s39
	s_cselect_b32 s42, s19, s38
	s_add_i32 m0, s12, 0xc000
	ds_read_b128 v[214:217], v155
	ds_read_b128 v[218:221], v155 offset:1024
	ds_read_b128 v[222:225], v155 offset:2048
	ds_read_b128 v[226:229], v155 offset:3072
	ds_read_b128 v[230:233], v155 offset:4096
	ds_read_b128 v[234:237], v155 offset:5120
	ds_read_b128 v[238:241], v155 offset:6144
	ds_read_b128 v[242:245], v155 offset:7168
	global_load_lds_dwordx4 v148, s[40:41]
	s_add_i32 m0, s12, 0xe000
	s_nop 0
	global_load_lds_dwordx4 v150, s[40:41]
	s_waitcnt vmcnt(8) lgkmcnt(0)
	s_barrier
	v_mfma_f32_16x16x32_bf16 v[124:127], v[182:185], v[214:217], 0
	v_mfma_f32_16x16x32_bf16 v[120:123], v[190:193], v[214:217], 0
	v_mfma_f32_16x16x32_bf16 v[116:119], v[182:185], v[222:225], 0
	v_mfma_f32_16x16x32_bf16 v[112:115], v[190:193], v[222:225], 0
	v_mfma_f32_16x16x32_bf16 v[100:103], v[182:185], v[230:233], 0
	v_mfma_f32_16x16x32_bf16 v[96:99], v[190:193], v[230:233], 0
	v_mfma_f32_16x16x32_bf16 v[84:87], v[182:185], v[238:241], 0
	v_mfma_f32_16x16x32_bf16 v[80:83], v[190:193], v[238:241], 0
	v_mfma_f32_16x16x32_bf16 v[124:127], v[186:189], v[218:221], v[124:127]
	v_mfma_f32_16x16x32_bf16 v[120:123], v[194:197], v[218:221], v[120:123]
	v_mfma_f32_16x16x32_bf16 v[116:119], v[186:189], v[226:229], v[116:119]
	v_mfma_f32_16x16x32_bf16 v[112:115], v[194:197], v[226:229], v[112:115]
	v_mfma_f32_16x16x32_bf16 v[100:103], v[186:189], v[234:237], v[100:103]
	v_mfma_f32_16x16x32_bf16 v[96:99], v[194:197], v[234:237], v[96:99]
	v_mfma_f32_16x16x32_bf16 v[84:87], v[186:189], v[242:245], v[84:87]
	v_mfma_f32_16x16x32_bf16 v[80:83], v[194:197], v[242:245], v[80:83]
	v_mfma_f32_16x16x32_bf16 v[108:111], v[198:201], v[214:217], 0
	v_mfma_f32_16x16x32_bf16 v[104:107], v[206:209], v[214:217], 0
	v_mfma_f32_16x16x32_bf16 v[92:95], v[198:201], v[222:225], 0
	v_mfma_f32_16x16x32_bf16 v[88:91], v[206:209], v[222:225], 0
	v_mfma_f32_16x16x32_bf16 v[76:79], v[198:201], v[230:233], 0
	v_mfma_f32_16x16x32_bf16 v[72:75], v[206:209], v[230:233], 0
	v_mfma_f32_16x16x32_bf16 v[68:71], v[198:201], v[238:241], 0
	v_mfma_f32_16x16x32_bf16 v[64:67], v[206:209], v[238:241], 0
	v_mfma_f32_16x16x32_bf16 v[108:111], v[202:205], v[218:221], v[108:111]
	v_mfma_f32_16x16x32_bf16 v[104:107], v[210:213], v[218:221], v[104:107]
	v_mfma_f32_16x16x32_bf16 v[92:95], v[202:205], v[226:229], v[92:95]
	v_mfma_f32_16x16x32_bf16 v[88:91], v[210:213], v[226:229], v[88:91]
	v_mfma_f32_16x16x32_bf16 v[76:79], v[202:205], v[234:237], v[76:79]
	v_mfma_f32_16x16x32_bf16 v[72:75], v[210:213], v[234:237], v[72:75]
	v_mfma_f32_16x16x32_bf16 v[68:71], v[202:205], v[242:245], v[68:71]
	v_mfma_f32_16x16x32_bf16 v[64:67], v[210:213], v[242:245], v[64:67]
	s_barrier
	s_add_u32 s60, s42, 0x80
	s_addc_u32 s61, s43, 0
	s_add_u32 s62, s44, 0x80
	s_addc_u32 s63, s45, 0
	s_add_i32 s21, s22, s3
	s_mov_b32 m0, s21
	ds_read_b128 v[214:217], v155 offset:16384
	ds_read_b128 v[218:221], v155 offset:17408
	ds_read_b128 v[222:225], v155 offset:18432
	ds_read_b128 v[226:229], v155 offset:19456
	ds_read_b128 v[230:233], v155 offset:20480
	ds_read_b128 v[234:237], v155 offset:21504
	ds_read_b128 v[238:241], v155 offset:22528
	ds_read_b128 v[242:245], v155 offset:23552
	global_load_lds_dwordx4 v130, s[42:43]
	s_add_i32 m0, s21, 0x2000
	s_add_u32 s48, s42, 0x40000
	s_addc_u32 s49, s43, 0
	s_add_i32 s21, s23, s3
	global_load_lds_dwordx4 v142, s[42:43]
	s_mov_b32 m0, s21
	s_nop 0
	global_load_lds_dwordx4 v130, s[48:49]
	s_add_i32 m0, s21, 0x2000
	s_nop 0
	global_load_lds_dwordx4 v142, s[48:49]
	s_mov_b32 m0, s12
	s_nop 0
	global_load_lds_dwordx4 v146, s[44:45]
	s_mov_b32 m0, s13
	s_nop 0
	global_load_lds_dwordx4 v144, s[44:45]
	s_waitcnt vmcnt(8) lgkmcnt(0)
	s_barrier
	v_mfma_f32_16x16x32_bf16 v[60:63], v[182:185], v[214:217], 0
	v_mfma_f32_16x16x32_bf16 v[56:59], v[190:193], v[214:217], 0
	v_mfma_f32_16x16x32_bf16 v[52:55], v[182:185], v[222:225], 0
	v_mfma_f32_16x16x32_bf16 v[48:51], v[190:193], v[222:225], 0
	v_mfma_f32_16x16x32_bf16 v[36:39], v[182:185], v[230:233], 0
	v_mfma_f32_16x16x32_bf16 v[32:35], v[190:193], v[230:233], 0
	v_mfma_f32_16x16x32_bf16 v[20:23], v[182:185], v[238:241], 0
	v_mfma_f32_16x16x32_bf16 v[16:19], v[190:193], v[238:241], 0
	v_mfma_f32_16x16x32_bf16 v[60:63], v[186:189], v[218:221], v[60:63]
	v_mfma_f32_16x16x32_bf16 v[56:59], v[194:197], v[218:221], v[56:59]
	v_mfma_f32_16x16x32_bf16 v[52:55], v[186:189], v[226:229], v[52:55]
	v_mfma_f32_16x16x32_bf16 v[48:51], v[194:197], v[226:229], v[48:51]
	v_mfma_f32_16x16x32_bf16 v[36:39], v[186:189], v[234:237], v[36:39]
	v_mfma_f32_16x16x32_bf16 v[32:35], v[194:197], v[234:237], v[32:35]
	v_mfma_f32_16x16x32_bf16 v[20:23], v[186:189], v[242:245], v[20:23]
	v_mfma_f32_16x16x32_bf16 v[16:19], v[194:197], v[242:245], v[16:19]
	v_mfma_f32_16x16x32_bf16 v[44:47], v[198:201], v[214:217], 0
	v_mfma_f32_16x16x32_bf16 v[40:43], v[206:209], v[214:217], 0
	v_mfma_f32_16x16x32_bf16 v[28:31], v[198:201], v[222:225], 0
	v_mfma_f32_16x16x32_bf16 v[24:27], v[206:209], v[222:225], 0
	v_mfma_f32_16x16x32_bf16 v[12:15], v[198:201], v[230:233], 0
	v_mfma_f32_16x16x32_bf16 v[8:11], v[206:209], v[230:233], 0
	v_mfma_f32_16x16x32_bf16 v[4:7], v[198:201], v[238:241], 0
	v_mfma_f32_16x16x32_bf16 v[0:3], v[206:209], v[238:241], 0
	v_mfma_f32_16x16x32_bf16 v[44:47], v[202:205], v[218:221], v[44:47]
	v_mfma_f32_16x16x32_bf16 v[40:43], v[210:213], v[218:221], v[40:43]
	v_mfma_f32_16x16x32_bf16 v[28:31], v[202:205], v[226:229], v[28:31]
	v_mfma_f32_16x16x32_bf16 v[24:27], v[210:213], v[226:229], v[24:27]
	v_mfma_f32_16x16x32_bf16 v[12:15], v[202:205], v[234:237], v[12:15]
	v_mfma_f32_16x16x32_bf16 v[8:11], v[210:213], v[234:237], v[8:11]
	v_mfma_f32_16x16x32_bf16 v[4:7], v[202:205], v[242:245], v[4:7]
	v_mfma_f32_16x16x32_bf16 v[0:3], v[210:213], v[242:245], v[0:3]
	s_barrier
	v_add_u32_e32 v181, s34, v153
	ds_read_b128 v[182:185], v181
	ds_read_b128 v[186:189], v181 offset:1024
	ds_read_b128 v[190:193], v181 offset:2048
	ds_read_b128 v[194:197], v181 offset:3072
	v_add_u32_e32 v181, s35, v153
	ds_read_b128 v[198:201], v181
	ds_read_b128 v[202:205], v181 offset:1024
	ds_read_b128 v[206:209], v181 offset:2048
	ds_read_b128 v[210:213], v181 offset:3072
	s_add_u32 s44, s44, 0x40000
	s_addc_u32 s45, s45, 0
	s_mov_b32 m0, s20
	ds_read_b128 v[214:217], v155 offset:32768
	ds_read_b128 v[218:221], v155 offset:33792
	ds_read_b128 v[222:225], v155 offset:34816
	ds_read_b128 v[226:229], v155 offset:35840
	ds_read_b128 v[230:233], v155 offset:36864
	ds_read_b128 v[234:237], v155 offset:37888
	ds_read_b128 v[238:241], v155 offset:38912
	ds_read_b128 v[242:245], v155 offset:39936
	global_load_lds_dwordx4 v146, s[44:45]
	s_mov_b32 m0, s26
	s_nop 0
	global_load_lds_dwordx4 v144, s[44:45]
	s_waitcnt vmcnt(8) lgkmcnt(0)
	s_barrier
	v_mfma_f32_16x16x32_bf16 v[124:127], v[182:185], v[214:217], v[124:127]
	v_mfma_f32_16x16x32_bf16 v[120:123], v[190:193], v[214:217], v[120:123]
	v_mfma_f32_16x16x32_bf16 v[116:119], v[182:185], v[222:225], v[116:119]
	v_mfma_f32_16x16x32_bf16 v[112:115], v[190:193], v[222:225], v[112:115]
	v_mfma_f32_16x16x32_bf16 v[100:103], v[182:185], v[230:233], v[100:103]
	v_mfma_f32_16x16x32_bf16 v[96:99], v[190:193], v[230:233], v[96:99]
	v_mfma_f32_16x16x32_bf16 v[84:87], v[182:185], v[238:241], v[84:87]
	v_mfma_f32_16x16x32_bf16 v[80:83], v[190:193], v[238:241], v[80:83]
	v_mfma_f32_16x16x32_bf16 v[124:127], v[186:189], v[218:221], v[124:127]
	v_mfma_f32_16x16x32_bf16 v[120:123], v[194:197], v[218:221], v[120:123]
	v_mfma_f32_16x16x32_bf16 v[116:119], v[186:189], v[226:229], v[116:119]
	v_mfma_f32_16x16x32_bf16 v[112:115], v[194:197], v[226:229], v[112:115]
	v_mfma_f32_16x16x32_bf16 v[100:103], v[186:189], v[234:237], v[100:103]
	v_mfma_f32_16x16x32_bf16 v[96:99], v[194:197], v[234:237], v[96:99]
	v_mfma_f32_16x16x32_bf16 v[84:87], v[186:189], v[242:245], v[84:87]
	v_mfma_f32_16x16x32_bf16 v[80:83], v[194:197], v[242:245], v[80:83]
	v_mfma_f32_16x16x32_bf16 v[108:111], v[198:201], v[214:217], v[108:111]
	v_mfma_f32_16x16x32_bf16 v[104:107], v[206:209], v[214:217], v[104:107]
	v_mfma_f32_16x16x32_bf16 v[92:95], v[198:201], v[222:225], v[92:95]
	v_mfma_f32_16x16x32_bf16 v[88:91], v[206:209], v[222:225], v[88:91]
	v_mfma_f32_16x16x32_bf16 v[76:79], v[198:201], v[230:233], v[76:79]
	v_mfma_f32_16x16x32_bf16 v[72:75], v[206:209], v[230:233], v[72:75]
	v_mfma_f32_16x16x32_bf16 v[68:71], v[198:201], v[238:241], v[68:71]
	v_mfma_f32_16x16x32_bf16 v[64:67], v[206:209], v[238:241], v[64:67]
	v_mfma_f32_16x16x32_bf16 v[108:111], v[202:205], v[218:221], v[108:111]
	v_mfma_f32_16x16x32_bf16 v[104:107], v[210:213], v[218:221], v[104:107]
	v_mfma_f32_16x16x32_bf16 v[92:95], v[202:205], v[226:229], v[92:95]
	v_mfma_f32_16x16x32_bf16 v[88:91], v[210:213], v[226:229], v[88:91]
	v_mfma_f32_16x16x32_bf16 v[76:79], v[202:205], v[234:237], v[76:79]
	v_mfma_f32_16x16x32_bf16 v[72:75], v[210:213], v[234:237], v[72:75]
	v_mfma_f32_16x16x32_bf16 v[68:71], v[202:205], v[242:245], v[68:71]
	v_mfma_f32_16x16x32_bf16 v[64:67], v[210:213], v[242:245], v[64:67]
	s_barrier
	s_add_i32 s21, s34, s3
	s_mov_b32 m0, s21
	ds_read_b128 v[214:217], v155 offset:49152
	ds_read_b128 v[218:221], v155 offset:50176
	ds_read_b128 v[222:225], v155 offset:51200
	ds_read_b128 v[226:229], v155 offset:52224
	ds_read_b128 v[230:233], v155 offset:53248
	ds_read_b128 v[234:237], v155 offset:54272
	ds_read_b128 v[238:241], v155 offset:55296
	ds_read_b128 v[242:245], v155 offset:56320
	global_load_lds_dwordx4 v130, s[60:61]
	s_add_i32 m0, s21, 0x2000
	s_add_u32 s42, s42, 0x40080
	s_addc_u32 s43, s43, 0
	s_add_i32 s21, s35, s3
	global_load_lds_dwordx4 v142, s[60:61]
	s_mov_b32 m0, s21
	s_nop 0
	global_load_lds_dwordx4 v130, s[42:43]
	s_add_i32 m0, s21, 0x2000
	s_nop 0
	global_load_lds_dwordx4 v142, s[42:43]
	s_mov_b32 m0, s0
	s_nop 0
	global_load_lds_dwordx4 v146, s[62:63]
	s_mov_b32 m0, s1
	s_nop 0
	global_load_lds_dwordx4 v144, s[62:63]
	s_waitcnt vmcnt(8) lgkmcnt(0)
	s_barrier
	v_mfma_f32_16x16x32_bf16 v[60:63], v[182:185], v[214:217], v[60:63]
	v_mfma_f32_16x16x32_bf16 v[56:59], v[190:193], v[214:217], v[56:59]
	v_mfma_f32_16x16x32_bf16 v[52:55], v[182:185], v[222:225], v[52:55]
	v_mfma_f32_16x16x32_bf16 v[48:51], v[190:193], v[222:225], v[48:51]
	v_mfma_f32_16x16x32_bf16 v[36:39], v[182:185], v[230:233], v[36:39]
	v_mfma_f32_16x16x32_bf16 v[32:35], v[190:193], v[230:233], v[32:35]
	v_mfma_f32_16x16x32_bf16 v[20:23], v[182:185], v[238:241], v[20:23]
	v_mfma_f32_16x16x32_bf16 v[16:19], v[190:193], v[238:241], v[16:19]
	v_mfma_f32_16x16x32_bf16 v[60:63], v[186:189], v[218:221], v[60:63]
	v_mfma_f32_16x16x32_bf16 v[56:59], v[194:197], v[218:221], v[56:59]
	v_mfma_f32_16x16x32_bf16 v[52:55], v[186:189], v[226:229], v[52:55]
	v_mfma_f32_16x16x32_bf16 v[48:51], v[194:197], v[226:229], v[48:51]
	v_mfma_f32_16x16x32_bf16 v[36:39], v[186:189], v[234:237], v[36:39]
	v_mfma_f32_16x16x32_bf16 v[32:35], v[194:197], v[234:237], v[32:35]
	v_mfma_f32_16x16x32_bf16 v[20:23], v[186:189], v[242:245], v[20:23]
	v_mfma_f32_16x16x32_bf16 v[16:19], v[194:197], v[242:245], v[16:19]
	v_mfma_f32_16x16x32_bf16 v[44:47], v[198:201], v[214:217], v[44:47]
	v_mfma_f32_16x16x32_bf16 v[40:43], v[206:209], v[214:217], v[40:43]
	v_mfma_f32_16x16x32_bf16 v[28:31], v[198:201], v[222:225], v[28:31]
	v_mfma_f32_16x16x32_bf16 v[24:27], v[206:209], v[222:225], v[24:27]
	v_mfma_f32_16x16x32_bf16 v[12:15], v[198:201], v[230:233], v[12:15]
	v_mfma_f32_16x16x32_bf16 v[8:11], v[206:209], v[230:233], v[8:11]
	v_mfma_f32_16x16x32_bf16 v[4:7], v[198:201], v[238:241], v[4:7]
	v_mfma_f32_16x16x32_bf16 v[0:3], v[206:209], v[238:241], v[0:3]
	v_mfma_f32_16x16x32_bf16 v[44:47], v[202:205], v[218:221], v[44:47]
	v_mfma_f32_16x16x32_bf16 v[40:43], v[210:213], v[218:221], v[40:43]
	v_mfma_f32_16x16x32_bf16 v[28:31], v[202:205], v[226:229], v[28:31]
	v_mfma_f32_16x16x32_bf16 v[24:27], v[210:213], v[226:229], v[24:27]
	v_mfma_f32_16x16x32_bf16 v[12:15], v[202:205], v[234:237], v[12:15]
	v_mfma_f32_16x16x32_bf16 v[8:11], v[210:213], v[234:237], v[8:11]
	v_mfma_f32_16x16x32_bf16 v[4:7], v[202:205], v[242:245], v[4:7]
	v_mfma_f32_16x16x32_bf16 v[0:3], v[210:213], v[242:245], v[0:3]
	s_barrier
	s_add_i32 s46, s46, 2
	s_add_u32 s40, s40, 0x100
	s_addc_u32 s41, s41, 0
	s_add_u32 s38, s38, 0x100
	s_addc_u32 s39, s39, 0
	s_cmp_gt_u32 s46, 13
	s_cbranch_scc1 .Lpeel_done_872

.LBB0_1271:
	s_add_i32 s11, s48, -2
	s_add_u32 s29, s42, 0x100
	s_addc_u32 s49, s43, 0
	s_mov_b32 s44, 0
	v_add_u32_e32 v156, s22, v153
	ds_read_b128 v[182:185], v156
	ds_read_b128 v[186:189], v156 offset:1024
	ds_read_b128 v[190:193], v156 offset:2048
	ds_read_b128 v[194:197], v156 offset:3072
	v_add_u32_e32 v156, s23, v153
	ds_read_b128 v[198:201], v156
	ds_read_b128 v[202:205], v156 offset:1024
	ds_read_b128 v[206:209], v156 offset:2048
	ds_read_b128 v[210:213], v156 offset:3072
	s_add_i32 s50, s44, 2
	s_add_u32 s42, s40, 0x100
	s_addc_u32 s43, s41, 0
	s_cmp_eq_u32 s11, s44
	s_cselect_b32 s44, s36, s29
	s_cselect_b32 s47, s17, s43
	s_cselect_b32 s46, s16, s42
	s_cselect_b32 s45, s37, s49
	s_add_i32 m0, s12, 0xc000
	ds_read_b128 v[214:217], v155
	ds_read_b128 v[218:221], v155 offset:1024
	ds_read_b128 v[222:225], v155 offset:2048
	ds_read_b128 v[226:229], v155 offset:3072
	ds_read_b128 v[230:233], v155 offset:4096
	ds_read_b128 v[234:237], v155 offset:5120
	ds_read_b128 v[238:241], v155 offset:6144
	ds_read_b128 v[242:245], v155 offset:7168
	global_load_lds_dwordx4 v148, s[40:41]
	s_add_i32 m0, s12, 0xe000
	s_nop 0
	global_load_lds_dwordx4 v150, s[40:41]
	s_waitcnt vmcnt(8) lgkmcnt(0)
	s_barrier
	v_mfma_f32_16x16x32_bf16 v[124:127], v[182:185], v[214:217], 0
	v_mfma_f32_16x16x32_bf16 v[120:123], v[190:193], v[214:217], 0
	v_mfma_f32_16x16x32_bf16 v[116:119], v[182:185], v[222:225], 0
	v_mfma_f32_16x16x32_bf16 v[112:115], v[190:193], v[222:225], 0
	v_mfma_f32_16x16x32_bf16 v[100:103], v[182:185], v[230:233], 0
	v_mfma_f32_16x16x32_bf16 v[96:99], v[190:193], v[230:233], 0
	v_mfma_f32_16x16x32_bf16 v[84:87], v[182:185], v[238:241], 0
	v_mfma_f32_16x16x32_bf16 v[80:83], v[190:193], v[238:241], 0
	v_mfma_f32_16x16x32_bf16 v[124:127], v[186:189], v[218:221], v[124:127]
	v_mfma_f32_16x16x32_bf16 v[120:123], v[194:197], v[218:221], v[120:123]
	v_mfma_f32_16x16x32_bf16 v[116:119], v[186:189], v[226:229], v[116:119]
	v_mfma_f32_16x16x32_bf16 v[112:115], v[194:197], v[226:229], v[112:115]
	v_mfma_f32_16x16x32_bf16 v[100:103], v[186:189], v[234:237], v[100:103]
	v_mfma_f32_16x16x32_bf16 v[96:99], v[194:197], v[234:237], v[96:99]
	v_mfma_f32_16x16x32_bf16 v[84:87], v[186:189], v[242:245], v[84:87]
	v_mfma_f32_16x16x32_bf16 v[80:83], v[194:197], v[242:245], v[80:83]
	v_mfma_f32_16x16x32_bf16 v[108:111], v[198:201], v[214:217], 0
	v_mfma_f32_16x16x32_bf16 v[104:107], v[206:209], v[214:217], 0
	v_mfma_f32_16x16x32_bf16 v[92:95], v[198:201], v[222:225], 0
	v_mfma_f32_16x16x32_bf16 v[88:91], v[206:209], v[222:225], 0
	v_mfma_f32_16x16x32_bf16 v[76:79], v[198:201], v[230:233], 0
	v_mfma_f32_16x16x32_bf16 v[72:75], v[206:209], v[230:233], 0
	v_mfma_f32_16x16x32_bf16 v[68:71], v[198:201], v[238:241], 0
	v_mfma_f32_16x16x32_bf16 v[64:67], v[206:209], v[238:241], 0
	v_mfma_f32_16x16x32_bf16 v[108:111], v[202:205], v[218:221], v[108:111]
	v_mfma_f32_16x16x32_bf16 v[104:107], v[210:213], v[218:221], v[104:107]
	v_mfma_f32_16x16x32_bf16 v[92:95], v[202:205], v[226:229], v[92:95]
	v_mfma_f32_16x16x32_bf16 v[88:91], v[210:213], v[226:229], v[88:91]
	v_mfma_f32_16x16x32_bf16 v[76:79], v[202:205], v[234:237], v[76:79]
	v_mfma_f32_16x16x32_bf16 v[72:75], v[210:213], v[234:237], v[72:75]
	v_mfma_f32_16x16x32_bf16 v[68:71], v[202:205], v[242:245], v[68:71]
	v_mfma_f32_16x16x32_bf16 v[64:67], v[210:213], v[242:245], v[64:67]
	s_barrier
	s_add_u32 s60, s44, 0x80
	s_addc_u32 s61, s45, 0
	s_add_u32 s62, s46, 0x80
	s_addc_u32 s63, s47, 0
	s_add_i32 s21, s22, s3
	s_mov_b32 m0, s21
	ds_read_b128 v[214:217], v155 offset:16384
	ds_read_b128 v[218:221], v155 offset:17408
	ds_read_b128 v[222:225], v155 offset:18432
	ds_read_b128 v[226:229], v155 offset:19456
	ds_read_b128 v[230:233], v155 offset:20480
	ds_read_b128 v[234:237], v155 offset:21504
	ds_read_b128 v[238:241], v155 offset:22528
	ds_read_b128 v[242:245], v155 offset:23552
	global_load_lds_dwordx4 v130, s[44:45]
	s_add_i32 m0, s21, 0x2000
	s_add_u32 s40, s44, 0x40000
	s_addc_u32 s41, s45, 0
	s_add_i32 s21, s23, s3
	global_load_lds_dwordx4 v146, s[44:45]
	s_mov_b32 m0, s21
	s_nop 0
	global_load_lds_dwordx4 v130, s[40:41]
	s_add_i32 m0, s21, 0x2000
	s_nop 0
	global_load_lds_dwordx4 v146, s[40:41]
	s_mov_b32 m0, s12
	s_nop 0
	global_load_lds_dwordx4 v142, s[46:47]
	s_mov_b32 m0, s13
	s_nop 0
	global_load_lds_dwordx4 v144, s[46:47]
	s_waitcnt vmcnt(8) lgkmcnt(0)
	s_barrier
	v_mfma_f32_16x16x32_bf16 v[60:63], v[182:185], v[214:217], 0
	v_mfma_f32_16x16x32_bf16 v[56:59], v[190:193], v[214:217], 0
	v_mfma_f32_16x16x32_bf16 v[52:55], v[182:185], v[222:225], 0
	v_mfma_f32_16x16x32_bf16 v[48:51], v[190:193], v[222:225], 0
	v_mfma_f32_16x16x32_bf16 v[36:39], v[182:185], v[230:233], 0
	v_mfma_f32_16x16x32_bf16 v[32:35], v[190:193], v[230:233], 0
	v_mfma_f32_16x16x32_bf16 v[20:23], v[182:185], v[238:241], 0
	v_mfma_f32_16x16x32_bf16 v[16:19], v[190:193], v[238:241], 0
	v_mfma_f32_16x16x32_bf16 v[60:63], v[186:189], v[218:221], v[60:63]
	v_mfma_f32_16x16x32_bf16 v[56:59], v[194:197], v[218:221], v[56:59]
	v_mfma_f32_16x16x32_bf16 v[52:55], v[186:189], v[226:229], v[52:55]
	v_mfma_f32_16x16x32_bf16 v[48:51], v[194:197], v[226:229], v[48:51]
	v_mfma_f32_16x16x32_bf16 v[36:39], v[186:189], v[234:237], v[36:39]
	v_mfma_f32_16x16x32_bf16 v[32:35], v[194:197], v[234:237], v[32:35]
	v_mfma_f32_16x16x32_bf16 v[20:23], v[186:189], v[242:245], v[20:23]
	v_mfma_f32_16x16x32_bf16 v[16:19], v[194:197], v[242:245], v[16:19]
	v_mfma_f32_16x16x32_bf16 v[44:47], v[198:201], v[214:217], 0
	v_mfma_f32_16x16x32_bf16 v[40:43], v[206:209], v[214:217], 0
	v_mfma_f32_16x16x32_bf16 v[28:31], v[198:201], v[222:225], 0
	v_mfma_f32_16x16x32_bf16 v[24:27], v[206:209], v[222:225], 0
	v_mfma_f32_16x16x32_bf16 v[12:15], v[198:201], v[230:233], 0
	v_mfma_f32_16x16x32_bf16 v[8:11], v[206:209], v[230:233], 0
	v_mfma_f32_16x16x32_bf16 v[4:7], v[198:201], v[238:241], 0
	v_mfma_f32_16x16x32_bf16 v[0:3], v[206:209], v[238:241], 0
	v_mfma_f32_16x16x32_bf16 v[44:47], v[202:205], v[218:221], v[44:47]
	v_mfma_f32_16x16x32_bf16 v[40:43], v[210:213], v[218:221], v[40:43]
	v_mfma_f32_16x16x32_bf16 v[28:31], v[202:205], v[226:229], v[28:31]
	v_mfma_f32_16x16x32_bf16 v[24:27], v[210:213], v[226:229], v[24:27]
	v_mfma_f32_16x16x32_bf16 v[12:15], v[202:205], v[234:237], v[12:15]
	v_mfma_f32_16x16x32_bf16 v[8:11], v[210:213], v[234:237], v[8:11]
	v_mfma_f32_16x16x32_bf16 v[4:7], v[202:205], v[242:245], v[4:7]
	v_mfma_f32_16x16x32_bf16 v[0:3], v[210:213], v[242:245], v[0:3]
	s_barrier
	v_add_u32_e32 v181, s34, v153
	ds_read_b128 v[182:185], v181
	ds_read_b128 v[186:189], v181 offset:1024
	ds_read_b128 v[190:193], v181 offset:2048
	ds_read_b128 v[194:197], v181 offset:3072
	v_add_u32_e32 v181, s35, v153
	ds_read_b128 v[198:201], v181
	ds_read_b128 v[202:205], v181 offset:1024
	ds_read_b128 v[206:209], v181 offset:2048
	ds_read_b128 v[210:213], v181 offset:3072
	s_add_u32 s40, s46, 0xb0000
	s_addc_u32 s41, s47, 0
	s_mov_b32 m0, s18
	ds_read_b128 v[214:217], v155 offset:32768
	ds_read_b128 v[218:221], v155 offset:33792
	ds_read_b128 v[222:225], v155 offset:34816
	ds_read_b128 v[226:229], v155 offset:35840
	ds_read_b128 v[230:233], v155 offset:36864
	ds_read_b128 v[234:237], v155 offset:37888
	ds_read_b128 v[238:241], v155 offset:38912
	ds_read_b128 v[242:245], v155 offset:39936
	global_load_lds_dwordx4 v142, s[40:41]
	s_mov_b32 m0, s19
	s_nop 0
	global_load_lds_dwordx4 v144, s[40:41]
	s_waitcnt vmcnt(8) lgkmcnt(0)
	s_barrier
	v_mfma_f32_16x16x32_bf16 v[124:127], v[182:185], v[214:217], v[124:127]
	v_mfma_f32_16x16x32_bf16 v[120:123], v[190:193], v[214:217], v[120:123]
	v_mfma_f32_16x16x32_bf16 v[116:119], v[182:185], v[222:225], v[116:119]
	v_mfma_f32_16x16x32_bf16 v[112:115], v[190:193], v[222:225], v[112:115]
	v_mfma_f32_16x16x32_bf16 v[100:103], v[182:185], v[230:233], v[100:103]
	v_mfma_f32_16x16x32_bf16 v[96:99], v[190:193], v[230:233], v[96:99]
	v_mfma_f32_16x16x32_bf16 v[84:87], v[182:185], v[238:241], v[84:87]
	v_mfma_f32_16x16x32_bf16 v[80:83], v[190:193], v[238:241], v[80:83]
	v_mfma_f32_16x16x32_bf16 v[124:127], v[186:189], v[218:221], v[124:127]
	v_mfma_f32_16x16x32_bf16 v[120:123], v[194:197], v[218:221], v[120:123]
	v_mfma_f32_16x16x32_bf16 v[116:119], v[186:189], v[226:229], v[116:119]
	v_mfma_f32_16x16x32_bf16 v[112:115], v[194:197], v[226:229], v[112:115]
	v_mfma_f32_16x16x32_bf16 v[100:103], v[186:189], v[234:237], v[100:103]
	v_mfma_f32_16x16x32_bf16 v[96:99], v[194:197], v[234:237], v[96:99]
	v_mfma_f32_16x16x32_bf16 v[84:87], v[186:189], v[242:245], v[84:87]
	v_mfma_f32_16x16x32_bf16 v[80:83], v[194:197], v[242:245], v[80:83]
	v_mfma_f32_16x16x32_bf16 v[108:111], v[198:201], v[214:217], v[108:111]
	v_mfma_f32_16x16x32_bf16 v[104:107], v[206:209], v[214:217], v[104:107]
	v_mfma_f32_16x16x32_bf16 v[92:95], v[198:201], v[222:225], v[92:95]
	v_mfma_f32_16x16x32_bf16 v[88:91], v[206:209], v[222:225], v[88:91]
	v_mfma_f32_16x16x32_bf16 v[76:79], v[198:201], v[230:233], v[76:79]
	v_mfma_f32_16x16x32_bf16 v[72:75], v[206:209], v[230:233], v[72:75]
	v_mfma_f32_16x16x32_bf16 v[68:71], v[198:201], v[238:241], v[68:71]
	v_mfma_f32_16x16x32_bf16 v[64:67], v[206:209], v[238:241], v[64:67]
	v_mfma_f32_16x16x32_bf16 v[108:111], v[202:205], v[218:221], v[108:111]
	v_mfma_f32_16x16x32_bf16 v[104:107], v[210:213], v[218:221], v[104:107]
	v_mfma_f32_16x16x32_bf16 v[92:95], v[202:205], v[226:229], v[92:95]
	v_mfma_f32_16x16x32_bf16 v[88:91], v[210:213], v[226:229], v[88:91]
	v_mfma_f32_16x16x32_bf16 v[76:79], v[202:205], v[234:237], v[76:79]
	v_mfma_f32_16x16x32_bf16 v[72:75], v[210:213], v[234:237], v[72:75]
	v_mfma_f32_16x16x32_bf16 v[68:71], v[202:205], v[242:245], v[68:71]
	v_mfma_f32_16x16x32_bf16 v[64:67], v[210:213], v[242:245], v[64:67]
	s_barrier
	s_add_i32 s21, s34, s3
	s_mov_b32 m0, s21
	ds_read_b128 v[214:217], v155 offset:49152
	ds_read_b128 v[218:221], v155 offset:50176
	ds_read_b128 v[222:225], v155 offset:51200
	ds_read_b128 v[226:229], v155 offset:52224
	ds_read_b128 v[230:233], v155 offset:53248
	ds_read_b128 v[234:237], v155 offset:54272
	ds_read_b128 v[238:241], v155 offset:55296
	ds_read_b128 v[242:245], v155 offset:56320
	global_load_lds_dwordx4 v130, s[60:61]
	s_add_i32 m0, s21, 0x2000
	s_add_u32 s40, s44, 0x40080
	s_addc_u32 s41, s45, 0
	s_add_i32 s21, s35, s3
	global_load_lds_dwordx4 v146, s[60:61]
	s_mov_b32 m0, s21
	s_nop 0
	global_load_lds_dwordx4 v130, s[40:41]
	s_add_i32 m0, s21, 0x2000
	s_nop 0
	global_load_lds_dwordx4 v146, s[40:41]
	s_mov_b32 m0, s20
	s_nop 0
	global_load_lds_dwordx4 v142, s[62:63]
	s_mov_b32 m0, s26
	s_nop 0
	global_load_lds_dwordx4 v144, s[62:63]
	s_waitcnt vmcnt(8) lgkmcnt(0)
	s_barrier
	v_mfma_f32_16x16x32_bf16 v[60:63], v[182:185], v[214:217], v[60:63]
	v_mfma_f32_16x16x32_bf16 v[56:59], v[190:193], v[214:217], v[56:59]
	v_mfma_f32_16x16x32_bf16 v[52:55], v[182:185], v[222:225], v[52:55]
	v_mfma_f32_16x16x32_bf16 v[48:51], v[190:193], v[222:225], v[48:51]
	v_mfma_f32_16x16x32_bf16 v[36:39], v[182:185], v[230:233], v[36:39]
	v_mfma_f32_16x16x32_bf16 v[32:35], v[190:193], v[230:233], v[32:35]
	v_mfma_f32_16x16x32_bf16 v[20:23], v[182:185], v[238:241], v[20:23]
	v_mfma_f32_16x16x32_bf16 v[16:19], v[190:193], v[238:241], v[16:19]
	v_mfma_f32_16x16x32_bf16 v[60:63], v[186:189], v[218:221], v[60:63]
	v_mfma_f32_16x16x32_bf16 v[56:59], v[194:197], v[218:221], v[56:59]
	v_mfma_f32_16x16x32_bf16 v[52:55], v[186:189], v[226:229], v[52:55]
	v_mfma_f32_16x16x32_bf16 v[48:51], v[194:197], v[226:229], v[48:51]
	v_mfma_f32_16x16x32_bf16 v[36:39], v[186:189], v[234:237], v[36:39]
	v_mfma_f32_16x16x32_bf16 v[32:35], v[194:197], v[234:237], v[32:35]
	v_mfma_f32_16x16x32_bf16 v[20:23], v[186:189], v[242:245], v[20:23]
	v_mfma_f32_16x16x32_bf16 v[16:19], v[194:197], v[242:245], v[16:19]
	v_mfma_f32_16x16x32_bf16 v[44:47], v[198:201], v[214:217], v[44:47]
	v_mfma_f32_16x16x32_bf16 v[40:43], v[206:209], v[214:217], v[40:43]
	v_mfma_f32_16x16x32_bf16 v[28:31], v[198:201], v[222:225], v[28:31]
	v_mfma_f32_16x16x32_bf16 v[24:27], v[206:209], v[222:225], v[24:27]
	v_mfma_f32_16x16x32_bf16 v[12:15], v[198:201], v[230:233], v[12:15]
	v_mfma_f32_16x16x32_bf16 v[8:11], v[206:209], v[230:233], v[8:11]
	v_mfma_f32_16x16x32_bf16 v[4:7], v[198:201], v[238:241], v[4:7]
	v_mfma_f32_16x16x32_bf16 v[0:3], v[206:209], v[238:241], v[0:3]
	v_mfma_f32_16x16x32_bf16 v[44:47], v[202:205], v[218:221], v[44:47]
	v_mfma_f32_16x16x32_bf16 v[40:43], v[210:213], v[218:221], v[40:43]
	v_mfma_f32_16x16x32_bf16 v[28:31], v[202:205], v[226:229], v[28:31]
	v_mfma_f32_16x16x32_bf16 v[24:27], v[210:213], v[226:229], v[24:27]
	v_mfma_f32_16x16x32_bf16 v[12:15], v[202:205], v[234:237], v[12:15]
	v_mfma_f32_16x16x32_bf16 v[8:11], v[210:213], v[234:237], v[8:11]
	v_mfma_f32_16x16x32_bf16 v[4:7], v[202:205], v[242:245], v[4:7]
	v_mfma_f32_16x16x32_bf16 v[0:3], v[210:213], v[242:245], v[0:3]
	s_barrier
	s_add_u32 s29, s29, 0x100
	s_addc_u32 s49, s49, 0
	s_cmp_ge_i32 s50, s48
	s_mov_b64 s[40:41], s[42:43]
	s_mov_b32 s44, s50
	s_cbranch_scc1 .Lpeel_done_1272
.LBB0_1272:
	v_add_u32_e32 v156, s22, v153
	ds_read_b128 v[182:185], v156
	ds_read_b128 v[186:189], v156 offset:1024
	ds_read_b128 v[190:193], v156 offset:2048
	ds_read_b128 v[194:197], v156 offset:3072
	v_add_u32_e32 v156, s23, v153
	ds_read_b128 v[198:201], v156
	ds_read_b128 v[202:205], v156 offset:1024
	ds_read_b128 v[206:209], v156 offset:2048
	ds_read_b128 v[210:213], v156 offset:3072
	s_add_i32 s50, s44, 2
	s_add_u32 s42, s40, 0x100
	s_addc_u32 s43, s41, 0
	s_cmp_eq_u32 s11, s44
	s_cselect_b32 s44, s36, s29
	s_cselect_b32 s47, s17, s43
	s_cselect_b32 s46, s16, s42
	s_cselect_b32 s45, s37, s49
	s_add_i32 m0, s12, 0xc000
	ds_read_b128 v[214:217], v155
	ds_read_b128 v[218:221], v155 offset:1024
	ds_read_b128 v[222:225], v155 offset:2048
	ds_read_b128 v[226:229], v155 offset:3072
	ds_read_b128 v[230:233], v155 offset:4096
	ds_read_b128 v[234:237], v155 offset:5120
	ds_read_b128 v[238:241], v155 offset:6144
	ds_read_b128 v[242:245], v155 offset:7168
	global_load_lds_dwordx4 v148, s[40:41]
	s_add_i32 m0, s12, 0xe000
	s_nop 0
	global_load_lds_dwordx4 v150, s[40:41]
	s_waitcnt vmcnt(8) lgkmcnt(0)
	s_barrier
	v_mfma_f32_16x16x32_bf16 v[124:127], v[182:185], v[214:217], v[124:127]
	v_mfma_f32_16x16x32_bf16 v[120:123], v[190:193], v[214:217], v[120:123]
	v_mfma_f32_16x16x32_bf16 v[116:119], v[182:185], v[222:225], v[116:119]
	v_mfma_f32_16x16x32_bf16 v[112:115], v[190:193], v[222:225], v[112:115]
	v_mfma_f32_16x16x32_bf16 v[100:103], v[182:185], v[230:233], v[100:103]
	v_mfma_f32_16x16x32_bf16 v[96:99], v[190:193], v[230:233], v[96:99]
	v_mfma_f32_16x16x32_bf16 v[84:87], v[182:185], v[238:241], v[84:87]
	v_mfma_f32_16x16x32_bf16 v[80:83], v[190:193], v[238:241], v[80:83]
	v_mfma_f32_16x16x32_bf16 v[124:127], v[186:189], v[218:221], v[124:127]
	v_mfma_f32_16x16x32_bf16 v[120:123], v[194:197], v[218:221], v[120:123]
	v_mfma_f32_16x16x32_bf16 v[116:119], v[186:189], v[226:229], v[116:119]
	v_mfma_f32_16x16x32_bf16 v[112:115], v[194:197], v[226:229], v[112:115]
	v_mfma_f32_16x16x32_bf16 v[100:103], v[186:189], v[234:237], v[100:103]
	v_mfma_f32_16x16x32_bf16 v[96:99], v[194:197], v[234:237], v[96:99]
	v_mfma_f32_16x16x32_bf16 v[84:87], v[186:189], v[242:245], v[84:87]
	v_mfma_f32_16x16x32_bf16 v[80:83], v[194:197], v[242:245], v[80:83]
	v_mfma_f32_16x16x32_bf16 v[108:111], v[198:201], v[214:217], v[108:111]
	v_mfma_f32_16x16x32_bf16 v[104:107], v[206:209], v[214:217], v[104:107]
	v_mfma_f32_16x16x32_bf16 v[92:95], v[198:201], v[222:225], v[92:95]
	v_mfma_f32_16x16x32_bf16 v[88:91], v[206:209], v[222:225], v[88:91]
	v_mfma_f32_16x16x32_bf16 v[76:79], v[198:201], v[230:233], v[76:79]
	v_mfma_f32_16x16x32_bf16 v[72:75], v[206:209], v[230:233], v[72:75]
	v_mfma_f32_16x16x32_bf16 v[68:71], v[198:201], v[238:241], v[68:71]
	v_mfma_f32_16x16x32_bf16 v[64:67], v[206:209], v[238:241], v[64:67]
	v_mfma_f32_16x16x32_bf16 v[108:111], v[202:205], v[218:221], v[108:111]
	v_mfma_f32_16x16x32_bf16 v[104:107], v[210:213], v[218:221], v[104:107]
	v_mfma_f32_16x16x32_bf16 v[92:95], v[202:205], v[226:229], v[92:95]
	v_mfma_f32_16x16x32_bf16 v[88:91], v[210:213], v[226:229], v[88:91]
	v_mfma_f32_16x16x32_bf16 v[76:79], v[202:205], v[234:237], v[76:79]
	v_mfma_f32_16x16x32_bf16 v[72:75], v[210:213], v[234:237], v[72:75]
	v_mfma_f32_16x16x32_bf16 v[68:71], v[202:205], v[242:245], v[68:71]
	v_mfma_f32_16x16x32_bf16 v[64:67], v[210:213], v[242:245], v[64:67]
	s_barrier
	s_add_u32 s60, s44, 0x80
	s_addc_u32 s61, s45, 0
	s_add_u32 s62, s46, 0x80
	s_addc_u32 s63, s47, 0
	s_add_i32 s21, s22, s3
	s_mov_b32 m0, s21
	ds_read_b128 v[214:217], v155 offset:16384
	ds_read_b128 v[218:221], v155 offset:17408
	ds_read_b128 v[222:225], v155 offset:18432
	ds_read_b128 v[226:229], v155 offset:19456
	ds_read_b128 v[230:233], v155 offset:20480
	ds_read_b128 v[234:237], v155 offset:21504
	ds_read_b128 v[238:241], v155 offset:22528
	ds_read_b128 v[242:245], v155 offset:23552
	global_load_lds_dwordx4 v130, s[44:45]
	s_add_i32 m0, s21, 0x2000
	s_add_u32 s40, s44, 0x40000
	s_addc_u32 s41, s45, 0
	s_add_i32 s21, s23, s3
	global_load_lds_dwordx4 v146, s[44:45]
	s_mov_b32 m0, s21
	s_nop 0
	global_load_lds_dwordx4 v130, s[40:41]
	s_add_i32 m0, s21, 0x2000
	s_nop 0
	global_load_lds_dwordx4 v146, s[40:41]
	s_mov_b32 m0, s12
	s_nop 0
	global_load_lds_dwordx4 v142, s[46:47]
	s_mov_b32 m0, s13
	s_nop 0
	global_load_lds_dwordx4 v144, s[46:47]
	s_waitcnt vmcnt(8) lgkmcnt(0)
	s_barrier
	v_mfma_f32_16x16x32_bf16 v[60:63], v[182:185], v[214:217], v[60:63]
	v_mfma_f32_16x16x32_bf16 v[56:59], v[190:193], v[214:217], v[56:59]
	v_mfma_f32_16x16x32_bf16 v[52:55], v[182:185], v[222:225], v[52:55]
	v_mfma_f32_16x16x32_bf16 v[48:51], v[190:193], v[222:225], v[48:51]
	v_mfma_f32_16x16x32_bf16 v[36:39], v[182:185], v[230:233], v[36:39]
	v_mfma_f32_16x16x32_bf16 v[32:35], v[190:193], v[230:233], v[32:35]
	v_mfma_f32_16x16x32_bf16 v[20:23], v[182:185], v[238:241], v[20:23]
	v_mfma_f32_16x16x32_bf16 v[16:19], v[190:193], v[238:241], v[16:19]
	v_mfma_f32_16x16x32_bf16 v[60:63], v[186:189], v[218:221], v[60:63]
	v_mfma_f32_16x16x32_bf16 v[56:59], v[194:197], v[218:221], v[56:59]
	v_mfma_f32_16x16x32_bf16 v[52:55], v[186:189], v[226:229], v[52:55]
	v_mfma_f32_16x16x32_bf16 v[48:51], v[194:197], v[226:229], v[48:51]
	v_mfma_f32_16x16x32_bf16 v[36:39], v[186:189], v[234:237], v[36:39]
	v_mfma_f32_16x16x32_bf16 v[32:35], v[194:197], v[234:237], v[32:35]
	v_mfma_f32_16x16x32_bf16 v[20:23], v[186:189], v[242:245], v[20:23]
	v_mfma_f32_16x16x32_bf16 v[16:19], v[194:197], v[242:245], v[16:19]
	v_mfma_f32_16x16x32_bf16 v[44:47], v[198:201], v[214:217], v[44:47]
	v_mfma_f32_16x16x32_bf16 v[40:43], v[206:209], v[214:217], v[40:43]
	v_mfma_f32_16x16x32_bf16 v[28:31], v[198:201], v[222:225], v[28:31]
	v_mfma_f32_16x16x32_bf16 v[24:27], v[206:209], v[222:225], v[24:27]
	v_mfma_f32_16x16x32_bf16 v[12:15], v[198:201], v[230:233], v[12:15]
	v_mfma_f32_16x16x32_bf16 v[8:11], v[206:209], v[230:233], v[8:11]
	v_mfma_f32_16x16x32_bf16 v[4:7], v[198:201], v[238:241], v[4:7]
	v_mfma_f32_16x16x32_bf16 v[0:3], v[206:209], v[238:241], v[0:3]
	v_mfma_f32_16x16x32_bf16 v[44:47], v[202:205], v[218:221], v[44:47]
	v_mfma_f32_16x16x32_bf16 v[40:43], v[210:213], v[218:221], v[40:43]
	v_mfma_f32_16x16x32_bf16 v[28:31], v[202:205], v[226:229], v[28:31]
	v_mfma_f32_16x16x32_bf16 v[24:27], v[210:213], v[226:229], v[24:27]
	v_mfma_f32_16x16x32_bf16 v[12:15], v[202:205], v[234:237], v[12:15]
	v_mfma_f32_16x16x32_bf16 v[8:11], v[210:213], v[234:237], v[8:11]
	v_mfma_f32_16x16x32_bf16 v[4:7], v[202:205], v[242:245], v[4:7]
	v_mfma_f32_16x16x32_bf16 v[0:3], v[210:213], v[242:245], v[0:3]
	s_barrier
	v_add_u32_e32 v181, s34, v153
	ds_read_b128 v[182:185], v181
	ds_read_b128 v[186:189], v181 offset:1024
	ds_read_b128 v[190:193], v181 offset:2048
	ds_read_b128 v[194:197], v181 offset:3072
	v_add_u32_e32 v181, s35, v153
	ds_read_b128 v[198:201], v181
	ds_read_b128 v[202:205], v181 offset:1024
	ds_read_b128 v[206:209], v181 offset:2048
	ds_read_b128 v[210:213], v181 offset:3072
	s_add_u32 s40, s46, 0xb0000
	s_addc_u32 s41, s47, 0
	s_mov_b32 m0, s18
	ds_read_b128 v[214:217], v155 offset:32768
	ds_read_b128 v[218:221], v155 offset:33792
	ds_read_b128 v[222:225], v155 offset:34816
	ds_read_b128 v[226:229], v155 offset:35840
	ds_read_b128 v[230:233], v155 offset:36864
	ds_read_b128 v[234:237], v155 offset:37888
	ds_read_b128 v[238:241], v155 offset:38912
	ds_read_b128 v[242:245], v155 offset:39936
	global_load_lds_dwordx4 v142, s[40:41]
	s_mov_b32 m0, s19
	s_nop 0
	global_load_lds_dwordx4 v144, s[40:41]
	s_waitcnt vmcnt(8) lgkmcnt(0)
	s_barrier
	v_mfma_f32_16x16x32_bf16 v[124:127], v[182:185], v[214:217], v[124:127]
	v_mfma_f32_16x16x32_bf16 v[120:123], v[190:193], v[214:217], v[120:123]
	v_mfma_f32_16x16x32_bf16 v[116:119], v[182:185], v[222:225], v[116:119]
	v_mfma_f32_16x16x32_bf16 v[112:115], v[190:193], v[222:225], v[112:115]
	v_mfma_f32_16x16x32_bf16 v[100:103], v[182:185], v[230:233], v[100:103]
	v_mfma_f32_16x16x32_bf16 v[96:99], v[190:193], v[230:233], v[96:99]
	v_mfma_f32_16x16x32_bf16 v[84:87], v[182:185], v[238:241], v[84:87]
	v_mfma_f32_16x16x32_bf16 v[80:83], v[190:193], v[238:241], v[80:83]
	v_mfma_f32_16x16x32_bf16 v[124:127], v[186:189], v[218:221], v[124:127]
	v_mfma_f32_16x16x32_bf16 v[120:123], v[194:197], v[218:221], v[120:123]
	v_mfma_f32_16x16x32_bf16 v[116:119], v[186:189], v[226:229], v[116:119]
	v_mfma_f32_16x16x32_bf16 v[112:115], v[194:197], v[226:229], v[112:115]
	v_mfma_f32_16x16x32_bf16 v[100:103], v[186:189], v[234:237], v[100:103]
	v_mfma_f32_16x16x32_bf16 v[96:99], v[194:197], v[234:237], v[96:99]
	v_mfma_f32_16x16x32_bf16 v[84:87], v[186:189], v[242:245], v[84:87]
	v_mfma_f32_16x16x32_bf16 v[80:83], v[194:197], v[242:245], v[80:83]
	v_mfma_f32_16x16x32_bf16 v[108:111], v[198:201], v[214:217], v[108:111]
	v_mfma_f32_16x16x32_bf16 v[104:107], v[206:209], v[214:217], v[104:107]
	v_mfma_f32_16x16x32_bf16 v[92:95], v[198:201], v[222:225], v[92:95]
	v_mfma_f32_16x16x32_bf16 v[88:91], v[206:209], v[222:225], v[88:91]
	v_mfma_f32_16x16x32_bf16 v[76:79], v[198:201], v[230:233], v[76:79]
	v_mfma_f32_16x16x32_bf16 v[72:75], v[206:209], v[230:233], v[72:75]
	v_mfma_f32_16x16x32_bf16 v[68:71], v[198:201], v[238:241], v[68:71]
	v_mfma_f32_16x16x32_bf16 v[64:67], v[206:209], v[238:241], v[64:67]
	v_mfma_f32_16x16x32_bf16 v[108:111], v[202:205], v[218:221], v[108:111]
	v_mfma_f32_16x16x32_bf16 v[104:107], v[210:213], v[218:221], v[104:107]
	v_mfma_f32_16x16x32_bf16 v[92:95], v[202:205], v[226:229], v[92:95]
	v_mfma_f32_16x16x32_bf16 v[88:91], v[210:213], v[226:229], v[88:91]
	v_mfma_f32_16x16x32_bf16 v[76:79], v[202:205], v[234:237], v[76:79]
	v_mfma_f32_16x16x32_bf16 v[72:75], v[210:213], v[234:237], v[72:75]
	v_mfma_f32_16x16x32_bf16 v[68:71], v[202:205], v[242:245], v[68:71]
	v_mfma_f32_16x16x32_bf16 v[64:67], v[210:213], v[242:245], v[64:67]
	s_barrier
	s_add_i32 s21, s34, s3
	s_mov_b32 m0, s21
	ds_read_b128 v[214:217], v155 offset:49152
	ds_read_b128 v[218:221], v155 offset:50176
	ds_read_b128 v[222:225], v155 offset:51200
	ds_read_b128 v[226:229], v155 offset:52224
	ds_read_b128 v[230:233], v155 offset:53248
	ds_read_b128 v[234:237], v155 offset:54272
	ds_read_b128 v[238:241], v155 offset:55296
	ds_read_b128 v[242:245], v155 offset:56320
	global_load_lds_dwordx4 v130, s[60:61]
	s_add_i32 m0, s21, 0x2000
	s_add_u32 s40, s44, 0x40080
	s_addc_u32 s41, s45, 0
	s_add_i32 s21, s35, s3
	global_load_lds_dwordx4 v146, s[60:61]
	s_mov_b32 m0, s21
	s_nop 0
	global_load_lds_dwordx4 v130, s[40:41]
	s_add_i32 m0, s21, 0x2000
	s_nop 0
	global_load_lds_dwordx4 v146, s[40:41]
	s_mov_b32 m0, s20
	s_nop 0
	global_load_lds_dwordx4 v142, s[62:63]
	s_mov_b32 m0, s26
	s_nop 0
	global_load_lds_dwordx4 v144, s[62:63]
	s_waitcnt vmcnt(8) lgkmcnt(0)
	s_barrier
	v_mfma_f32_16x16x32_bf16 v[60:63], v[182:185], v[214:217], v[60:63]
	v_mfma_f32_16x16x32_bf16 v[56:59], v[190:193], v[214:217], v[56:59]
	v_mfma_f32_16x16x32_bf16 v[52:55], v[182:185], v[222:225], v[52:55]
	v_mfma_f32_16x16x32_bf16 v[48:51], v[190:193], v[222:225], v[48:51]
	v_mfma_f32_16x16x32_bf16 v[36:39], v[182:185], v[230:233], v[36:39]
	v_mfma_f32_16x16x32_bf16 v[32:35], v[190:193], v[230:233], v[32:35]
	v_mfma_f32_16x16x32_bf16 v[20:23], v[182:185], v[238:241], v[20:23]
	v_mfma_f32_16x16x32_bf16 v[16:19], v[190:193], v[238:241], v[16:19]
	v_mfma_f32_16x16x32_bf16 v[60:63], v[186:189], v[218:221], v[60:63]
	v_mfma_f32_16x16x32_bf16 v[56:59], v[194:197], v[218:221], v[56:59]
	v_mfma_f32_16x16x32_bf16 v[52:55], v[186:189], v[226:229], v[52:55]
	v_mfma_f32_16x16x32_bf16 v[48:51], v[194:197], v[226:229], v[48:51]
	v_mfma_f32_16x16x32_bf16 v[36:39], v[186:189], v[234:237], v[36:39]
	v_mfma_f32_16x16x32_bf16 v[32:35], v[194:197], v[234:237], v[32:35]
	v_mfma_f32_16x16x32_bf16 v[20:23], v[186:189], v[242:245], v[20:23]
	v_mfma_f32_16x16x32_bf16 v[16:19], v[194:197], v[242:245], v[16:19]
	v_mfma_f32_16x16x32_bf16 v[44:47], v[198:201], v[214:217], v[44:47]
	v_mfma_f32_16x16x32_bf16 v[40:43], v[206:209], v[214:217], v[40:43]
	v_mfma_f32_16x16x32_bf16 v[28:31], v[198:201], v[222:225], v[28:31]
	v_mfma_f32_16x16x32_bf16 v[24:27], v[206:209], v[222:225], v[24:27]
	v_mfma_f32_16x16x32_bf16 v[12:15], v[198:201], v[230:233], v[12:15]
	v_mfma_f32_16x16x32_bf16 v[8:11], v[206:209], v[230:233], v[8:11]
	v_mfma_f32_16x16x32_bf16 v[4:7], v[198:201], v[238:241], v[4:7]
	v_mfma_f32_16x16x32_bf16 v[0:3], v[206:209], v[238:241], v[0:3]
	v_mfma_f32_16x16x32_bf16 v[44:47], v[202:205], v[218:221], v[44:47]
	v_mfma_f32_16x16x32_bf16 v[40:43], v[210:213], v[218:221], v[40:43]
	v_mfma_f32_16x16x32_bf16 v[28:31], v[202:205], v[226:229], v[28:31]
	v_mfma_f32_16x16x32_bf16 v[24:27], v[210:213], v[226:229], v[24:27]
	v_mfma_f32_16x16x32_bf16 v[12:15], v[202:205], v[234:237], v[12:15]
	v_mfma_f32_16x16x32_bf16 v[8:11], v[210:213], v[234:237], v[8:11]
	v_mfma_f32_16x16x32_bf16 v[4:7], v[202:205], v[242:245], v[4:7]
	v_mfma_f32_16x16x32_bf16 v[0:3], v[210:213], v[242:245], v[0:3]
	s_barrier
	s_add_u32 s29, s29, 0x100
	s_addc_u32 s49, s49, 0
	s_cmp_ge_i32 s50, s48
	s_mov_b64 s[40:41], s[42:43]
	s_mov_b32 s44, s50
	s_cbranch_scc0 .LBB0_1272

.LBB0_1437:
	s_ashr_i32 s11, s10, 31
	s_lshl_b64 s[12:13], s[10:11], 19
	v_readlane_b32 s14, v252, 27
	v_readlane_b32 s15, v252, 28
	s_add_u32 s28, s14, s12
	s_addc_u32 s29, s15, s13
	s_and_b64 s[12:13], s[40:41], exec
	s_cselect_b32 s3, s29, s17
	s_cselect_b32 s11, s28, s16
	s_ashr_i32 s9, s8, 31
	s_lshl_b64 s[12:13], s[8:9], 19
	s_add_u32 s36, s26, s12
	s_addc_u32 s37, s46, s13
	s_and_b64 s[12:13], s[40:41], exec
	s_cselect_b32 s9, s37, s43
	s_cselect_b32 s12, s36, s42
	s_add_u32 s16, s16, 0x40080
	s_addc_u32 s17, s17, 0
	s_add_u32 s13, s42, 0x100
	s_addc_u32 s14, s43, 0
	s_mov_b32 s15, -2
	v_add_u32_e32 v152, s22, v155
	ds_read_b128 v[182:185], v152
	ds_read_b128 v[186:189], v152 offset:1024
	ds_read_b128 v[190:193], v152 offset:2048
	ds_read_b128 v[194:197], v152 offset:3072
	v_add_u32_e32 v152, s23, v155
	ds_read_b128 v[198:201], v152
	ds_read_b128 v[202:205], v152 offset:1024
	ds_read_b128 v[206:209], v152 offset:2048
	ds_read_b128 v[210:213], v152 offset:3072
	s_add_u32 s18, s16, 0xfffc0080
	s_addc_u32 s19, s17, -1
	s_cmp_eq_u32 s15, 12
	s_cselect_b32 s45, s3, s19
	s_cselect_b32 s44, s11, s18
	s_cselect_b32 s43, s9, s14
	s_cselect_b32 s42, s12, s13
	s_add_i32 m0, s48, 0xc000
	ds_read_b128 v[214:217], v157
	ds_read_b128 v[218:221], v157 offset:1024
	ds_read_b128 v[222:225], v157 offset:2048
	ds_read_b128 v[226:229], v157 offset:3072
	ds_read_b128 v[230:233], v157 offset:4096
	ds_read_b128 v[234:237], v157 offset:5120
	ds_read_b128 v[238:241], v157 offset:6144
	ds_read_b128 v[242:245], v157 offset:7168
	global_load_lds_dwordx4 v148, s[16:17]
	s_add_i32 m0, s48, 0xe000
	s_nop 0
	global_load_lds_dwordx4 v150, s[16:17]
	s_waitcnt vmcnt(8) lgkmcnt(0)
	s_barrier
	v_mfma_f32_16x16x32_bf16 v[124:127], v[182:185], v[214:217], 0
	v_mfma_f32_16x16x32_bf16 v[120:123], v[190:193], v[214:217], 0
	v_mfma_f32_16x16x32_bf16 v[108:111], v[182:185], v[222:225], 0
	v_mfma_f32_16x16x32_bf16 v[104:107], v[190:193], v[222:225], 0
	v_mfma_f32_16x16x32_bf16 v[92:95], v[182:185], v[230:233], 0
	v_mfma_f32_16x16x32_bf16 v[88:91], v[190:193], v[230:233], 0
	v_mfma_f32_16x16x32_bf16 v[76:79], v[182:185], v[238:241], 0
	v_mfma_f32_16x16x32_bf16 v[72:75], v[190:193], v[238:241], 0
	v_mfma_f32_16x16x32_bf16 v[124:127], v[186:189], v[218:221], v[124:127]
	v_mfma_f32_16x16x32_bf16 v[120:123], v[194:197], v[218:221], v[120:123]
	v_mfma_f32_16x16x32_bf16 v[108:111], v[186:189], v[226:229], v[108:111]
	v_mfma_f32_16x16x32_bf16 v[104:107], v[194:197], v[226:229], v[104:107]
	v_mfma_f32_16x16x32_bf16 v[92:95], v[186:189], v[234:237], v[92:95]
	v_mfma_f32_16x16x32_bf16 v[88:91], v[194:197], v[234:237], v[88:91]
	v_mfma_f32_16x16x32_bf16 v[76:79], v[186:189], v[242:245], v[76:79]
	v_mfma_f32_16x16x32_bf16 v[72:75], v[194:197], v[242:245], v[72:75]
	v_mfma_f32_16x16x32_bf16 v[116:119], v[198:201], v[214:217], 0
	v_mfma_f32_16x16x32_bf16 v[112:115], v[206:209], v[214:217], 0
	v_mfma_f32_16x16x32_bf16 v[100:103], v[198:201], v[222:225], 0
	v_mfma_f32_16x16x32_bf16 v[96:99], v[206:209], v[222:225], 0
	v_mfma_f32_16x16x32_bf16 v[84:87], v[198:201], v[230:233], 0
	v_mfma_f32_16x16x32_bf16 v[80:83], v[206:209], v[230:233], 0
	v_mfma_f32_16x16x32_bf16 v[68:71], v[198:201], v[238:241], 0
	v_mfma_f32_16x16x32_bf16 v[64:67], v[206:209], v[238:241], 0
	v_mfma_f32_16x16x32_bf16 v[116:119], v[202:205], v[218:221], v[116:119]
	v_mfma_f32_16x16x32_bf16 v[112:115], v[210:213], v[218:221], v[112:115]
	v_mfma_f32_16x16x32_bf16 v[100:103], v[202:205], v[226:229], v[100:103]
	v_mfma_f32_16x16x32_bf16 v[96:99], v[210:213], v[226:229], v[96:99]
	v_mfma_f32_16x16x32_bf16 v[84:87], v[202:205], v[234:237], v[84:87]
	v_mfma_f32_16x16x32_bf16 v[80:83], v[210:213], v[234:237], v[80:83]
	v_mfma_f32_16x16x32_bf16 v[68:71], v[202:205], v[242:245], v[68:71]
	v_mfma_f32_16x16x32_bf16 v[64:67], v[210:213], v[242:245], v[64:67]
	s_barrier
	s_add_u32 s60, s42, 0x80
	s_addc_u32 s61, s43, 0
	s_add_u32 s62, s44, 0x80
	s_addc_u32 s63, s45, 0
	s_add_i32 s18, s22, s47
	s_mov_b32 m0, s18
	ds_read_b128 v[214:217], v157 offset:16384
	ds_read_b128 v[218:221], v157 offset:17408
	ds_read_b128 v[222:225], v157 offset:18432
	ds_read_b128 v[226:229], v157 offset:19456
	ds_read_b128 v[230:233], v157 offset:20480
	ds_read_b128 v[234:237], v157 offset:21504
	ds_read_b128 v[238:241], v157 offset:22528
	ds_read_b128 v[242:245], v157 offset:23552
	global_load_lds_dwordx4 v130, s[42:43]
	s_add_i32 m0, s18, 0x2000
	s_add_u32 s18, s42, 0x40000
	s_addc_u32 s19, s43, 0
	s_add_i32 s21, s23, s47
	global_load_lds_dwordx4 v142, s[42:43]
	s_mov_b32 m0, s21
	s_nop 0
	global_load_lds_dwordx4 v130, s[18:19]
	s_add_i32 m0, s21, 0x2000
	s_nop 0
	global_load_lds_dwordx4 v142, s[18:19]
	s_mov_b32 m0, s48
	s_nop 0
	global_load_lds_dwordx4 v146, s[44:45]
	s_mov_b32 m0, s49
	s_nop 0
	global_load_lds_dwordx4 v144, s[44:45]
	s_waitcnt vmcnt(8) lgkmcnt(0)
	s_barrier
	v_mfma_f32_16x16x32_bf16 v[60:63], v[182:185], v[214:217], 0
	v_mfma_f32_16x16x32_bf16 v[56:59], v[190:193], v[214:217], 0
	v_mfma_f32_16x16x32_bf16 v[44:47], v[182:185], v[222:225], 0
	v_mfma_f32_16x16x32_bf16 v[40:43], v[190:193], v[222:225], 0
	v_mfma_f32_16x16x32_bf16 v[28:31], v[182:185], v[230:233], 0
	v_mfma_f32_16x16x32_bf16 v[24:27], v[190:193], v[230:233], 0
	v_mfma_f32_16x16x32_bf16 v[12:15], v[182:185], v[238:241], 0
	v_mfma_f32_16x16x32_bf16 v[8:11], v[190:193], v[238:241], 0
	v_mfma_f32_16x16x32_bf16 v[60:63], v[186:189], v[218:221], v[60:63]
	v_mfma_f32_16x16x32_bf16 v[56:59], v[194:197], v[218:221], v[56:59]
	v_mfma_f32_16x16x32_bf16 v[44:47], v[186:189], v[226:229], v[44:47]
	v_mfma_f32_16x16x32_bf16 v[40:43], v[194:197], v[226:229], v[40:43]
	v_mfma_f32_16x16x32_bf16 v[28:31], v[186:189], v[234:237], v[28:31]
	v_mfma_f32_16x16x32_bf16 v[24:27], v[194:197], v[234:237], v[24:27]
	v_mfma_f32_16x16x32_bf16 v[12:15], v[186:189], v[242:245], v[12:15]
	v_mfma_f32_16x16x32_bf16 v[8:11], v[194:197], v[242:245], v[8:11]
	v_mfma_f32_16x16x32_bf16 v[52:55], v[198:201], v[214:217], 0
	v_mfma_f32_16x16x32_bf16 v[48:51], v[206:209], v[214:217], 0
	v_mfma_f32_16x16x32_bf16 v[36:39], v[198:201], v[222:225], 0
	v_mfma_f32_16x16x32_bf16 v[32:35], v[206:209], v[222:225], 0
	v_mfma_f32_16x16x32_bf16 v[20:23], v[198:201], v[230:233], 0
	v_mfma_f32_16x16x32_bf16 v[16:19], v[206:209], v[230:233], 0
	v_mfma_f32_16x16x32_bf16 v[4:7], v[198:201], v[238:241], 0
	v_mfma_f32_16x16x32_bf16 v[0:3], v[206:209], v[238:241], 0
	v_mfma_f32_16x16x32_bf16 v[52:55], v[202:205], v[218:221], v[52:55]
	v_mfma_f32_16x16x32_bf16 v[48:51], v[210:213], v[218:221], v[48:51]
	v_mfma_f32_16x16x32_bf16 v[36:39], v[202:205], v[226:229], v[36:39]
	v_mfma_f32_16x16x32_bf16 v[32:35], v[210:213], v[226:229], v[32:35]
	v_mfma_f32_16x16x32_bf16 v[20:23], v[202:205], v[234:237], v[20:23]
	v_mfma_f32_16x16x32_bf16 v[16:19], v[210:213], v[234:237], v[16:19]
	v_mfma_f32_16x16x32_bf16 v[4:7], v[202:205], v[242:245], v[4:7]
	v_mfma_f32_16x16x32_bf16 v[0:3], v[210:213], v[242:245], v[0:3]
	s_barrier
	v_add_u32_e32 v181, s34, v155
	ds_read_b128 v[182:185], v181
	ds_read_b128 v[186:189], v181 offset:1024
	ds_read_b128 v[190:193], v181 offset:2048
	ds_read_b128 v[194:197], v181 offset:3072
	v_add_u32_e32 v181, s35, v155
	ds_read_b128 v[198:201], v181
	ds_read_b128 v[202:205], v181 offset:1024
	ds_read_b128 v[206:209], v181 offset:2048
	ds_read_b128 v[210:213], v181 offset:3072
	s_add_u32 s18, s44, 0x40000
	s_addc_u32 s19, s45, 0
	s_mov_b32 m0, s50
	ds_read_b128 v[214:217], v157 offset:32768
	ds_read_b128 v[218:221], v157 offset:33792
	ds_read_b128 v[222:225], v157 offset:34816
	ds_read_b128 v[226:229], v157 offset:35840
	ds_read_b128 v[230:233], v157 offset:36864
	ds_read_b128 v[234:237], v157 offset:37888
	ds_read_b128 v[238:241], v157 offset:38912
	ds_read_b128 v[242:245], v157 offset:39936
	global_load_lds_dwordx4 v146, s[18:19]
	s_mov_b32 m0, s51
	s_nop 0
	global_load_lds_dwordx4 v144, s[18:19]
	s_waitcnt vmcnt(8) lgkmcnt(0)
	s_barrier
	v_mfma_f32_16x16x32_bf16 v[124:127], v[182:185], v[214:217], v[124:127]
	v_mfma_f32_16x16x32_bf16 v[120:123], v[190:193], v[214:217], v[120:123]
	v_mfma_f32_16x16x32_bf16 v[108:111], v[182:185], v[222:225], v[108:111]
	v_mfma_f32_16x16x32_bf16 v[104:107], v[190:193], v[222:225], v[104:107]
	v_mfma_f32_16x16x32_bf16 v[92:95], v[182:185], v[230:233], v[92:95]
	v_mfma_f32_16x16x32_bf16 v[88:91], v[190:193], v[230:233], v[88:91]
	v_mfma_f32_16x16x32_bf16 v[76:79], v[182:185], v[238:241], v[76:79]
	v_mfma_f32_16x16x32_bf16 v[72:75], v[190:193], v[238:241], v[72:75]
	v_mfma_f32_16x16x32_bf16 v[124:127], v[186:189], v[218:221], v[124:127]
	v_mfma_f32_16x16x32_bf16 v[120:123], v[194:197], v[218:221], v[120:123]
	v_mfma_f32_16x16x32_bf16 v[108:111], v[186:189], v[226:229], v[108:111]
	v_mfma_f32_16x16x32_bf16 v[104:107], v[194:197], v[226:229], v[104:107]
	v_mfma_f32_16x16x32_bf16 v[92:95], v[186:189], v[234:237], v[92:95]
	v_mfma_f32_16x16x32_bf16 v[88:91], v[194:197], v[234:237], v[88:91]
	v_mfma_f32_16x16x32_bf16 v[76:79], v[186:189], v[242:245], v[76:79]
	v_mfma_f32_16x16x32_bf16 v[72:75], v[194:197], v[242:245], v[72:75]
	v_mfma_f32_16x16x32_bf16 v[116:119], v[198:201], v[214:217], v[116:119]
	v_mfma_f32_16x16x32_bf16 v[112:115], v[206:209], v[214:217], v[112:115]
	v_mfma_f32_16x16x32_bf16 v[100:103], v[198:201], v[222:225], v[100:103]
	v_mfma_f32_16x16x32_bf16 v[96:99], v[206:209], v[222:225], v[96:99]
	v_mfma_f32_16x16x32_bf16 v[84:87], v[198:201], v[230:233], v[84:87]
	v_mfma_f32_16x16x32_bf16 v[80:83], v[206:209], v[230:233], v[80:83]
	v_mfma_f32_16x16x32_bf16 v[68:71], v[198:201], v[238:241], v[68:71]
	v_mfma_f32_16x16x32_bf16 v[64:67], v[206:209], v[238:241], v[64:67]
	v_mfma_f32_16x16x32_bf16 v[116:119], v[202:205], v[218:221], v[116:119]
	v_mfma_f32_16x16x32_bf16 v[112:115], v[210:213], v[218:221], v[112:115]
	v_mfma_f32_16x16x32_bf16 v[100:103], v[202:205], v[226:229], v[100:103]
	v_mfma_f32_16x16x32_bf16 v[96:99], v[210:213], v[226:229], v[96:99]
	v_mfma_f32_16x16x32_bf16 v[84:87], v[202:205], v[234:237], v[84:87]
	v_mfma_f32_16x16x32_bf16 v[80:83], v[210:213], v[234:237], v[80:83]
	v_mfma_f32_16x16x32_bf16 v[68:71], v[202:205], v[242:245], v[68:71]
	v_mfma_f32_16x16x32_bf16 v[64:67], v[210:213], v[242:245], v[64:67]
	s_barrier
	s_add_i32 s18, s34, s47
	s_mov_b32 m0, s18
	ds_read_b128 v[214:217], v157 offset:49152
	ds_read_b128 v[218:221], v157 offset:50176
	ds_read_b128 v[222:225], v157 offset:51200
	ds_read_b128 v[226:229], v157 offset:52224
	ds_read_b128 v[230:233], v157 offset:53248
	ds_read_b128 v[234:237], v157 offset:54272
	ds_read_b128 v[238:241], v157 offset:55296
	ds_read_b128 v[242:245], v157 offset:56320
	global_load_lds_dwordx4 v130, s[60:61]
	s_add_i32 m0, s18, 0x2000
	s_add_u32 s18, s42, 0x40080
	s_addc_u32 s19, s43, 0
	s_add_i32 s21, s35, s47
	global_load_lds_dwordx4 v142, s[60:61]
	s_mov_b32 m0, s21
	s_nop 0
	global_load_lds_dwordx4 v130, s[18:19]
	s_add_i32 m0, s21, 0x2000
	s_nop 0
	global_load_lds_dwordx4 v142, s[18:19]
	s_mov_b32 m0, s52
	s_nop 0
	global_load_lds_dwordx4 v146, s[62:63]
	s_mov_b32 m0, s53
	s_nop 0
	global_load_lds_dwordx4 v144, s[62:63]
	s_waitcnt vmcnt(8) lgkmcnt(0)
	s_barrier
	v_mfma_f32_16x16x32_bf16 v[60:63], v[182:185], v[214:217], v[60:63]
	v_mfma_f32_16x16x32_bf16 v[56:59], v[190:193], v[214:217], v[56:59]
	v_mfma_f32_16x16x32_bf16 v[44:47], v[182:185], v[222:225], v[44:47]
	v_mfma_f32_16x16x32_bf16 v[40:43], v[190:193], v[222:225], v[40:43]
	v_mfma_f32_16x16x32_bf16 v[28:31], v[182:185], v[230:233], v[28:31]
	v_mfma_f32_16x16x32_bf16 v[24:27], v[190:193], v[230:233], v[24:27]
	v_mfma_f32_16x16x32_bf16 v[12:15], v[182:185], v[238:241], v[12:15]
	v_mfma_f32_16x16x32_bf16 v[8:11], v[190:193], v[238:241], v[8:11]
	v_mfma_f32_16x16x32_bf16 v[60:63], v[186:189], v[218:221], v[60:63]
	v_mfma_f32_16x16x32_bf16 v[56:59], v[194:197], v[218:221], v[56:59]
	v_mfma_f32_16x16x32_bf16 v[44:47], v[186:189], v[226:229], v[44:47]
	v_mfma_f32_16x16x32_bf16 v[40:43], v[194:197], v[226:229], v[40:43]
	v_mfma_f32_16x16x32_bf16 v[28:31], v[186:189], v[234:237], v[28:31]
	v_mfma_f32_16x16x32_bf16 v[24:27], v[194:197], v[234:237], v[24:27]
	v_mfma_f32_16x16x32_bf16 v[12:15], v[186:189], v[242:245], v[12:15]
	v_mfma_f32_16x16x32_bf16 v[8:11], v[194:197], v[242:245], v[8:11]
	v_mfma_f32_16x16x32_bf16 v[52:55], v[198:201], v[214:217], v[52:55]
	v_mfma_f32_16x16x32_bf16 v[48:51], v[206:209], v[214:217], v[48:51]
	v_mfma_f32_16x16x32_bf16 v[36:39], v[198:201], v[222:225], v[36:39]
	v_mfma_f32_16x16x32_bf16 v[32:35], v[206:209], v[222:225], v[32:35]
	v_mfma_f32_16x16x32_bf16 v[20:23], v[198:201], v[230:233], v[20:23]
	v_mfma_f32_16x16x32_bf16 v[16:19], v[206:209], v[230:233], v[16:19]
	v_mfma_f32_16x16x32_bf16 v[4:7], v[198:201], v[238:241], v[4:7]
	v_mfma_f32_16x16x32_bf16 v[0:3], v[206:209], v[238:241], v[0:3]
	v_mfma_f32_16x16x32_bf16 v[52:55], v[202:205], v[218:221], v[52:55]
	v_mfma_f32_16x16x32_bf16 v[48:51], v[210:213], v[218:221], v[48:51]
	v_mfma_f32_16x16x32_bf16 v[36:39], v[202:205], v[226:229], v[36:39]
	v_mfma_f32_16x16x32_bf16 v[32:35], v[210:213], v[226:229], v[32:35]
	v_mfma_f32_16x16x32_bf16 v[20:23], v[202:205], v[234:237], v[20:23]
	v_mfma_f32_16x16x32_bf16 v[16:19], v[210:213], v[234:237], v[16:19]
	v_mfma_f32_16x16x32_bf16 v[4:7], v[202:205], v[242:245], v[4:7]
	v_mfma_f32_16x16x32_bf16 v[0:3], v[210:213], v[242:245], v[0:3]
	s_barrier
	s_add_i32 s15, s15, 2
	s_add_u32 s16, s16, 0x100
	s_addc_u32 s17, s17, 0
	s_add_u32 s13, s13, 0x100
	s_addc_u32 s14, s14, 0
	s_cmp_gt_u32 s15, 13
	s_cbranch_scc1 .Lpeel_done_1438
.LBB0_1438:
	v_add_u32_e32 v152, s22, v155
	ds_read_b128 v[182:185], v152
	ds_read_b128 v[186:189], v152 offset:1024
	ds_read_b128 v[190:193], v152 offset:2048
	ds_read_b128 v[194:197], v152 offset:3072
	v_add_u32_e32 v152, s23, v155
	ds_read_b128 v[198:201], v152
	ds_read_b128 v[202:205], v152 offset:1024
	ds_read_b128 v[206:209], v152 offset:2048
	ds_read_b128 v[210:213], v152 offset:3072
	s_add_u32 s18, s16, 0xfffc0080
	s_addc_u32 s19, s17, -1
	s_cmp_eq_u32 s15, 12
	s_cselect_b32 s45, s3, s19
	s_cselect_b32 s44, s11, s18
	s_cselect_b32 s43, s9, s14
	s_cselect_b32 s42, s12, s13
	s_add_i32 m0, s48, 0xc000
	ds_read_b128 v[214:217], v157
	ds_read_b128 v[218:221], v157 offset:1024
	ds_read_b128 v[222:225], v157 offset:2048
	ds_read_b128 v[226:229], v157 offset:3072
	ds_read_b128 v[230:233], v157 offset:4096
	ds_read_b128 v[234:237], v157 offset:5120
	ds_read_b128 v[238:241], v157 offset:6144
	ds_read_b128 v[242:245], v157 offset:7168
	global_load_lds_dwordx4 v148, s[16:17]
	s_add_i32 m0, s48, 0xe000
	s_nop 0
	global_load_lds_dwordx4 v150, s[16:17]
	s_waitcnt vmcnt(8) lgkmcnt(0)
	s_barrier
	v_mfma_f32_16x16x32_bf16 v[124:127], v[182:185], v[214:217], v[124:127]
	v_mfma_f32_16x16x32_bf16 v[120:123], v[190:193], v[214:217], v[120:123]
	v_mfma_f32_16x16x32_bf16 v[108:111], v[182:185], v[222:225], v[108:111]
	v_mfma_f32_16x16x32_bf16 v[104:107], v[190:193], v[222:225], v[104:107]
	v_mfma_f32_16x16x32_bf16 v[92:95], v[182:185], v[230:233], v[92:95]
	v_mfma_f32_16x16x32_bf16 v[88:91], v[190:193], v[230:233], v[88:91]
	v_mfma_f32_16x16x32_bf16 v[76:79], v[182:185], v[238:241], v[76:79]
	v_mfma_f32_16x16x32_bf16 v[72:75], v[190:193], v[238:241], v[72:75]
	v_mfma_f32_16x16x32_bf16 v[124:127], v[186:189], v[218:221], v[124:127]
	v_mfma_f32_16x16x32_bf16 v[120:123], v[194:197], v[218:221], v[120:123]
	v_mfma_f32_16x16x32_bf16 v[108:111], v[186:189], v[226:229], v[108:111]
	v_mfma_f32_16x16x32_bf16 v[104:107], v[194:197], v[226:229], v[104:107]
	v_mfma_f32_16x16x32_bf16 v[92:95], v[186:189], v[234:237], v[92:95]
	v_mfma_f32_16x16x32_bf16 v[88:91], v[194:197], v[234:237], v[88:91]
	v_mfma_f32_16x16x32_bf16 v[76:79], v[186:189], v[242:245], v[76:79]
	v_mfma_f32_16x16x32_bf16 v[72:75], v[194:197], v[242:245], v[72:75]
	v_mfma_f32_16x16x32_bf16 v[116:119], v[198:201], v[214:217], v[116:119]
	v_mfma_f32_16x16x32_bf16 v[112:115], v[206:209], v[214:217], v[112:115]
	v_mfma_f32_16x16x32_bf16 v[100:103], v[198:201], v[222:225], v[100:103]
	v_mfma_f32_16x16x32_bf16 v[96:99], v[206:209], v[222:225], v[96:99]
	v_mfma_f32_16x16x32_bf16 v[84:87], v[198:201], v[230:233], v[84:87]
	v_mfma_f32_16x16x32_bf16 v[80:83], v[206:209], v[230:233], v[80:83]
	v_mfma_f32_16x16x32_bf16 v[68:71], v[198:201], v[238:241], v[68:71]
	v_mfma_f32_16x16x32_bf16 v[64:67], v[206:209], v[238:241], v[64:67]
	v_mfma_f32_16x16x32_bf16 v[116:119], v[202:205], v[218:221], v[116:119]
	v_mfma_f32_16x16x32_bf16 v[112:115], v[210:213], v[218:221], v[112:115]
	v_mfma_f32_16x16x32_bf16 v[100:103], v[202:205], v[226:229], v[100:103]
	v_mfma_f32_16x16x32_bf16 v[96:99], v[210:213], v[226:229], v[96:99]
	v_mfma_f32_16x16x32_bf16 v[84:87], v[202:205], v[234:237], v[84:87]
	v_mfma_f32_16x16x32_bf16 v[80:83], v[210:213], v[234:237], v[80:83]
	v_mfma_f32_16x16x32_bf16 v[68:71], v[202:205], v[242:245], v[68:71]
	v_mfma_f32_16x16x32_bf16 v[64:67], v[210:213], v[242:245], v[64:67]
	s_barrier
	s_add_u32 s60, s42, 0x80
	s_addc_u32 s61, s43, 0
	s_add_u32 s62, s44, 0x80
	s_addc_u32 s63, s45, 0
	s_add_i32 s18, s22, s47
	s_mov_b32 m0, s18
	ds_read_b128 v[214:217], v157 offset:16384
	ds_read_b128 v[218:221], v157 offset:17408
	ds_read_b128 v[222:225], v157 offset:18432
	ds_read_b128 v[226:229], v157 offset:19456
	ds_read_b128 v[230:233], v157 offset:20480
	ds_read_b128 v[234:237], v157 offset:21504
	ds_read_b128 v[238:241], v157 offset:22528
	ds_read_b128 v[242:245], v157 offset:23552
	global_load_lds_dwordx4 v130, s[42:43]
	s_add_i32 m0, s18, 0x2000
	s_add_u32 s18, s42, 0x40000
	s_addc_u32 s19, s43, 0
	s_add_i32 s21, s23, s47
	global_load_lds_dwordx4 v142, s[42:43]
	s_mov_b32 m0, s21
	s_nop 0
	global_load_lds_dwordx4 v130, s[18:19]
	s_add_i32 m0, s21, 0x2000
	s_nop 0
	global_load_lds_dwordx4 v142, s[18:19]
	s_mov_b32 m0, s48
	s_nop 0
	global_load_lds_dwordx4 v146, s[44:45]
	s_mov_b32 m0, s49
	s_nop 0
	global_load_lds_dwordx4 v144, s[44:45]
	s_waitcnt vmcnt(8) lgkmcnt(0)
	s_barrier
	v_mfma_f32_16x16x32_bf16 v[60:63], v[182:185], v[214:217], v[60:63]
	v_mfma_f32_16x16x32_bf16 v[56:59], v[190:193], v[214:217], v[56:59]
	v_mfma_f32_16x16x32_bf16 v[44:47], v[182:185], v[222:225], v[44:47]
	v_mfma_f32_16x16x32_bf16 v[40:43], v[190:193], v[222:225], v[40:43]
	v_mfma_f32_16x16x32_bf16 v[28:31], v[182:185], v[230:233], v[28:31]
	v_mfma_f32_16x16x32_bf16 v[24:27], v[190:193], v[230:233], v[24:27]
	v_mfma_f32_16x16x32_bf16 v[12:15], v[182:185], v[238:241], v[12:15]
	v_mfma_f32_16x16x32_bf16 v[8:11], v[190:193], v[238:241], v[8:11]
	v_mfma_f32_16x16x32_bf16 v[60:63], v[186:189], v[218:221], v[60:63]
	v_mfma_f32_16x16x32_bf16 v[56:59], v[194:197], v[218:221], v[56:59]
	v_mfma_f32_16x16x32_bf16 v[44:47], v[186:189], v[226:229], v[44:47]
	v_mfma_f32_16x16x32_bf16 v[40:43], v[194:197], v[226:229], v[40:43]
	v_mfma_f32_16x16x32_bf16 v[28:31], v[186:189], v[234:237], v[28:31]
	v_mfma_f32_16x16x32_bf16 v[24:27], v[194:197], v[234:237], v[24:27]
	v_mfma_f32_16x16x32_bf16 v[12:15], v[186:189], v[242:245], v[12:15]
	v_mfma_f32_16x16x32_bf16 v[8:11], v[194:197], v[242:245], v[8:11]
	v_mfma_f32_16x16x32_bf16 v[52:55], v[198:201], v[214:217], v[52:55]
	v_mfma_f32_16x16x32_bf16 v[48:51], v[206:209], v[214:217], v[48:51]
	v_mfma_f32_16x16x32_bf16 v[36:39], v[198:201], v[222:225], v[36:39]
	v_mfma_f32_16x16x32_bf16 v[32:35], v[206:209], v[222:225], v[32:35]
	v_mfma_f32_16x16x32_bf16 v[20:23], v[198:201], v[230:233], v[20:23]
	v_mfma_f32_16x16x32_bf16 v[16:19], v[206:209], v[230:233], v[16:19]
	v_mfma_f32_16x16x32_bf16 v[4:7], v[198:201], v[238:241], v[4:7]
	v_mfma_f32_16x16x32_bf16 v[0:3], v[206:209], v[238:241], v[0:3]
	v_mfma_f32_16x16x32_bf16 v[52:55], v[202:205], v[218:221], v[52:55]
	v_mfma_f32_16x16x32_bf16 v[48:51], v[210:213], v[218:221], v[48:51]
	v_mfma_f32_16x16x32_bf16 v[36:39], v[202:205], v[226:229], v[36:39]
	v_mfma_f32_16x16x32_bf16 v[32:35], v[210:213], v[226:229], v[32:35]
	v_mfma_f32_16x16x32_bf16 v[20:23], v[202:205], v[234:237], v[20:23]
	v_mfma_f32_16x16x32_bf16 v[16:19], v[210:213], v[234:237], v[16:19]
	v_mfma_f32_16x16x32_bf16 v[4:7], v[202:205], v[242:245], v[4:7]
	v_mfma_f32_16x16x32_bf16 v[0:3], v[210:213], v[242:245], v[0:3]
	s_barrier
	v_add_u32_e32 v181, s34, v155
	ds_read_b128 v[182:185], v181
	ds_read_b128 v[186:189], v181 offset:1024
	ds_read_b128 v[190:193], v181 offset:2048
	ds_read_b128 v[194:197], v181 offset:3072
	v_add_u32_e32 v181, s35, v155
	ds_read_b128 v[198:201], v181
	ds_read_b128 v[202:205], v181 offset:1024
	ds_read_b128 v[206:209], v181 offset:2048
	ds_read_b128 v[210:213], v181 offset:3072
	s_add_u32 s18, s44, 0x40000
	s_addc_u32 s19, s45, 0
	s_mov_b32 m0, s50
	ds_read_b128 v[214:217], v157 offset:32768
	ds_read_b128 v[218:221], v157 offset:33792
	ds_read_b128 v[222:225], v157 offset:34816
	ds_read_b128 v[226:229], v157 offset:35840
	ds_read_b128 v[230:233], v157 offset:36864
	ds_read_b128 v[234:237], v157 offset:37888
	ds_read_b128 v[238:241], v157 offset:38912
	ds_read_b128 v[242:245], v157 offset:39936
	global_load_lds_dwordx4 v146, s[18:19]
	s_mov_b32 m0, s51
	s_nop 0
	global_load_lds_dwordx4 v144, s[18:19]
	s_waitcnt vmcnt(8) lgkmcnt(0)
	s_barrier
	v_mfma_f32_16x16x32_bf16 v[124:127], v[182:185], v[214:217], v[124:127]
	v_mfma_f32_16x16x32_bf16 v[120:123], v[190:193], v[214:217], v[120:123]
	v_mfma_f32_16x16x32_bf16 v[108:111], v[182:185], v[222:225], v[108:111]
	v_mfma_f32_16x16x32_bf16 v[104:107], v[190:193], v[222:225], v[104:107]
	v_mfma_f32_16x16x32_bf16 v[92:95], v[182:185], v[230:233], v[92:95]
	v_mfma_f32_16x16x32_bf16 v[88:91], v[190:193], v[230:233], v[88:91]
	v_mfma_f32_16x16x32_bf16 v[76:79], v[182:185], v[238:241], v[76:79]
	v_mfma_f32_16x16x32_bf16 v[72:75], v[190:193], v[238:241], v[72:75]
	v_mfma_f32_16x16x32_bf16 v[124:127], v[186:189], v[218:221], v[124:127]
	v_mfma_f32_16x16x32_bf16 v[120:123], v[194:197], v[218:221], v[120:123]
	v_mfma_f32_16x16x32_bf16 v[108:111], v[186:189], v[226:229], v[108:111]
	v_mfma_f32_16x16x32_bf16 v[104:107], v[194:197], v[226:229], v[104:107]
	v_mfma_f32_16x16x32_bf16 v[92:95], v[186:189], v[234:237], v[92:95]
	v_mfma_f32_16x16x32_bf16 v[88:91], v[194:197], v[234:237], v[88:91]
	v_mfma_f32_16x16x32_bf16 v[76:79], v[186:189], v[242:245], v[76:79]
	v_mfma_f32_16x16x32_bf16 v[72:75], v[194:197], v[242:245], v[72:75]
	v_mfma_f32_16x16x32_bf16 v[116:119], v[198:201], v[214:217], v[116:119]
	v_mfma_f32_16x16x32_bf16 v[112:115], v[206:209], v[214:217], v[112:115]
	v_mfma_f32_16x16x32_bf16 v[100:103], v[198:201], v[222:225], v[100:103]
	v_mfma_f32_16x16x32_bf16 v[96:99], v[206:209], v[222:225], v[96:99]
	v_mfma_f32_16x16x32_bf16 v[84:87], v[198:201], v[230:233], v[84:87]
	v_mfma_f32_16x16x32_bf16 v[80:83], v[206:209], v[230:233], v[80:83]
	v_mfma_f32_16x16x32_bf16 v[68:71], v[198:201], v[238:241], v[68:71]
	v_mfma_f32_16x16x32_bf16 v[64:67], v[206:209], v[238:241], v[64:67]
	v_mfma_f32_16x16x32_bf16 v[116:119], v[202:205], v[218:221], v[116:119]
	v_mfma_f32_16x16x32_bf16 v[112:115], v[210:213], v[218:221], v[112:115]
	v_mfma_f32_16x16x32_bf16 v[100:103], v[202:205], v[226:229], v[100:103]
	v_mfma_f32_16x16x32_bf16 v[96:99], v[210:213], v[226:229], v[96:99]
	v_mfma_f32_16x16x32_bf16 v[84:87], v[202:205], v[234:237], v[84:87]
	v_mfma_f32_16x16x32_bf16 v[80:83], v[210:213], v[234:237], v[80:83]
	v_mfma_f32_16x16x32_bf16 v[68:71], v[202:205], v[242:245], v[68:71]
	v_mfma_f32_16x16x32_bf16 v[64:67], v[210:213], v[242:245], v[64:67]
	s_barrier
	s_add_i32 s18, s34, s47
	s_mov_b32 m0, s18
	ds_read_b128 v[214:217], v157 offset:49152
	ds_read_b128 v[218:221], v157 offset:50176
	ds_read_b128 v[222:225], v157 offset:51200
	ds_read_b128 v[226:229], v157 offset:52224
	ds_read_b128 v[230:233], v157 offset:53248
	ds_read_b128 v[234:237], v157 offset:54272
	ds_read_b128 v[238:241], v157 offset:55296
	ds_read_b128 v[242:245], v157 offset:56320
	global_load_lds_dwordx4 v130, s[60:61]
	s_add_i32 m0, s18, 0x2000
	s_add_u32 s18, s42, 0x40080
	s_addc_u32 s19, s43, 0
	s_add_i32 s21, s35, s47
	global_load_lds_dwordx4 v142, s[60:61]
	s_mov_b32 m0, s21
	s_nop 0
	global_load_lds_dwordx4 v130, s[18:19]
	s_add_i32 m0, s21, 0x2000
	s_nop 0
	global_load_lds_dwordx4 v142, s[18:19]
	s_mov_b32 m0, s52
	s_nop 0
	global_load_lds_dwordx4 v146, s[62:63]
	s_mov_b32 m0, s53
	s_nop 0
	global_load_lds_dwordx4 v144, s[62:63]
	s_waitcnt vmcnt(8) lgkmcnt(0)
	s_barrier
	v_mfma_f32_16x16x32_bf16 v[60:63], v[182:185], v[214:217], v[60:63]
	v_mfma_f32_16x16x32_bf16 v[56:59], v[190:193], v[214:217], v[56:59]
	v_mfma_f32_16x16x32_bf16 v[44:47], v[182:185], v[222:225], v[44:47]
	v_mfma_f32_16x16x32_bf16 v[40:43], v[190:193], v[222:225], v[40:43]
	v_mfma_f32_16x16x32_bf16 v[28:31], v[182:185], v[230:233], v[28:31]
	v_mfma_f32_16x16x32_bf16 v[24:27], v[190:193], v[230:233], v[24:27]
	v_mfma_f32_16x16x32_bf16 v[12:15], v[182:185], v[238:241], v[12:15]
	v_mfma_f32_16x16x32_bf16 v[8:11], v[190:193], v[238:241], v[8:11]
	v_mfma_f32_16x16x32_bf16 v[60:63], v[186:189], v[218:221], v[60:63]
	v_mfma_f32_16x16x32_bf16 v[56:59], v[194:197], v[218:221], v[56:59]
	v_mfma_f32_16x16x32_bf16 v[44:47], v[186:189], v[226:229], v[44:47]
	v_mfma_f32_16x16x32_bf16 v[40:43], v[194:197], v[226:229], v[40:43]
	v_mfma_f32_16x16x32_bf16 v[28:31], v[186:189], v[234:237], v[28:31]
	v_mfma_f32_16x16x32_bf16 v[24:27], v[194:197], v[234:237], v[24:27]
	v_mfma_f32_16x16x32_bf16 v[12:15], v[186:189], v[242:245], v[12:15]
	v_mfma_f32_16x16x32_bf16 v[8:11], v[194:197], v[242:245], v[8:11]
	v_mfma_f32_16x16x32_bf16 v[52:55], v[198:201], v[214:217], v[52:55]
	v_mfma_f32_16x16x32_bf16 v[48:51], v[206:209], v[214:217], v[48:51]
	v_mfma_f32_16x16x32_bf16 v[36:39], v[198:201], v[222:225], v[36:39]
	v_mfma_f32_16x16x32_bf16 v[32:35], v[206:209], v[222:225], v[32:35]
	v_mfma_f32_16x16x32_bf16 v[20:23], v[198:201], v[230:233], v[20:23]
	v_mfma_f32_16x16x32_bf16 v[16:19], v[206:209], v[230:233], v[16:19]
	v_mfma_f32_16x16x32_bf16 v[4:7], v[198:201], v[238:241], v[4:7]
	v_mfma_f32_16x16x32_bf16 v[0:3], v[206:209], v[238:241], v[0:3]
	v_mfma_f32_16x16x32_bf16 v[52:55], v[202:205], v[218:221], v[52:55]
	v_mfma_f32_16x16x32_bf16 v[48:51], v[210:213], v[218:221], v[48:51]
	v_mfma_f32_16x16x32_bf16 v[36:39], v[202:205], v[226:229], v[36:39]
	v_mfma_f32_16x16x32_bf16 v[32:35], v[210:213], v[226:229], v[32:35]
	v_mfma_f32_16x16x32_bf16 v[20:23], v[202:205], v[234:237], v[20:23]
	v_mfma_f32_16x16x32_bf16 v[16:19], v[210:213], v[234:237], v[16:19]
	v_mfma_f32_16x16x32_bf16 v[4:7], v[202:205], v[242:245], v[4:7]
	v_mfma_f32_16x16x32_bf16 v[0:3], v[210:213], v[242:245], v[0:3]
	s_barrier
	s_add_i32 s15, s15, 2
	s_add_u32 s16, s16, 0x100
	s_addc_u32 s17, s17, 0
	s_add_u32 s13, s13, 0x100
	s_addc_u32 s14, s14, 0
	s_cmp_gt_u32 s15, 13
	s_cbranch_scc0 .LBB0_1438

.LBB0_1510:
	s_add_i32 s11, s49, -2
	s_add_u32 s50, s40, 0x100
	s_addc_u32 s51, s41, 0
	s_mov_b32 s42, 0
	v_add_u32_e32 v156, s22, v153
	ds_read_b128 v[182:185], v156
	ds_read_b128 v[186:189], v156 offset:1024
	ds_read_b128 v[190:193], v156 offset:2048
	ds_read_b128 v[194:197], v156 offset:3072
	v_add_u32_e32 v156, s23, v153
	ds_read_b128 v[198:201], v156
	ds_read_b128 v[202:205], v156 offset:1024
	ds_read_b128 v[206:209], v156 offset:2048
	ds_read_b128 v[210:213], v156 offset:3072
	s_add_i32 s52, s42, 2
	s_add_u32 s40, s36, 0x100
	s_addc_u32 s41, s37, 0
	s_cmp_eq_u32 s11, s42
	s_cselect_b32 s42, s28, s50
	s_cselect_b32 s45, s17, s41
	s_cselect_b32 s44, s16, s40
	s_cselect_b32 s43, s29, s51
	s_add_i32 m0, s13, 0xc000
	ds_read_b128 v[214:217], v155
	ds_read_b128 v[218:221], v155 offset:1024
	ds_read_b128 v[222:225], v155 offset:2048
	ds_read_b128 v[226:229], v155 offset:3072
	ds_read_b128 v[230:233], v155 offset:4096
	ds_read_b128 v[234:237], v155 offset:5120
	ds_read_b128 v[238:241], v155 offset:6144
	ds_read_b128 v[242:245], v155 offset:7168
	global_load_lds_dwordx4 v148, s[36:37]
	s_add_i32 m0, s13, 0xe000
	s_nop 0
	global_load_lds_dwordx4 v150, s[36:37]
	s_waitcnt vmcnt(8) lgkmcnt(0)
	s_barrier
	v_mfma_f32_16x16x32_bf16 v[124:127], v[182:185], v[214:217], 0
	v_mfma_f32_16x16x32_bf16 v[120:123], v[190:193], v[214:217], 0
	v_mfma_f32_16x16x32_bf16 v[116:119], v[182:185], v[222:225], 0
	v_mfma_f32_16x16x32_bf16 v[112:115], v[190:193], v[222:225], 0
	v_mfma_f32_16x16x32_bf16 v[100:103], v[182:185], v[230:233], 0
	v_mfma_f32_16x16x32_bf16 v[96:99], v[190:193], v[230:233], 0
	v_mfma_f32_16x16x32_bf16 v[84:87], v[182:185], v[238:241], 0
	v_mfma_f32_16x16x32_bf16 v[80:83], v[190:193], v[238:241], 0
	v_mfma_f32_16x16x32_bf16 v[124:127], v[186:189], v[218:221], v[124:127]
	v_mfma_f32_16x16x32_bf16 v[120:123], v[194:197], v[218:221], v[120:123]
	v_mfma_f32_16x16x32_bf16 v[116:119], v[186:189], v[226:229], v[116:119]
	v_mfma_f32_16x16x32_bf16 v[112:115], v[194:197], v[226:229], v[112:115]
	v_mfma_f32_16x16x32_bf16 v[100:103], v[186:189], v[234:237], v[100:103]
	v_mfma_f32_16x16x32_bf16 v[96:99], v[194:197], v[234:237], v[96:99]
	v_mfma_f32_16x16x32_bf16 v[84:87], v[186:189], v[242:245], v[84:87]
	v_mfma_f32_16x16x32_bf16 v[80:83], v[194:197], v[242:245], v[80:83]
	v_mfma_f32_16x16x32_bf16 v[108:111], v[198:201], v[214:217], 0
	v_mfma_f32_16x16x32_bf16 v[104:107], v[206:209], v[214:217], 0
	v_mfma_f32_16x16x32_bf16 v[92:95], v[198:201], v[222:225], 0
	v_mfma_f32_16x16x32_bf16 v[88:91], v[206:209], v[222:225], 0
	v_mfma_f32_16x16x32_bf16 v[76:79], v[198:201], v[230:233], 0
	v_mfma_f32_16x16x32_bf16 v[72:75], v[206:209], v[230:233], 0
	v_mfma_f32_16x16x32_bf16 v[68:71], v[198:201], v[238:241], 0
	v_mfma_f32_16x16x32_bf16 v[64:67], v[206:209], v[238:241], 0
	v_mfma_f32_16x16x32_bf16 v[108:111], v[202:205], v[218:221], v[108:111]
	v_mfma_f32_16x16x32_bf16 v[104:107], v[210:213], v[218:221], v[104:107]
	v_mfma_f32_16x16x32_bf16 v[92:95], v[202:205], v[226:229], v[92:95]
	v_mfma_f32_16x16x32_bf16 v[88:91], v[210:213], v[226:229], v[88:91]
	v_mfma_f32_16x16x32_bf16 v[76:79], v[202:205], v[234:237], v[76:79]
	v_mfma_f32_16x16x32_bf16 v[72:75], v[210:213], v[234:237], v[72:75]
	v_mfma_f32_16x16x32_bf16 v[68:71], v[202:205], v[242:245], v[68:71]
	v_mfma_f32_16x16x32_bf16 v[64:67], v[210:213], v[242:245], v[64:67]
	s_barrier
	s_add_u32 s60, s42, 0x80
	s_addc_u32 s61, s43, 0
	s_add_u32 s62, s44, 0x80
	s_addc_u32 s63, s45, 0
	s_add_i32 s21, s22, s12
	s_mov_b32 m0, s21
	ds_read_b128 v[214:217], v155 offset:16384
	ds_read_b128 v[218:221], v155 offset:17408
	ds_read_b128 v[222:225], v155 offset:18432
	ds_read_b128 v[226:229], v155 offset:19456
	ds_read_b128 v[230:233], v155 offset:20480
	ds_read_b128 v[234:237], v155 offset:21504
	ds_read_b128 v[238:241], v155 offset:22528
	ds_read_b128 v[242:245], v155 offset:23552
	global_load_lds_dwordx4 v130, s[42:43]
	s_add_i32 m0, s21, 0x2000
	s_add_u32 s24, s42, 0xb0000
	s_addc_u32 s25, s43, 0
	s_add_i32 s21, s23, s12
	global_load_lds_dwordx4 v146, s[42:43]
	s_mov_b32 m0, s21
	s_nop 0
	global_load_lds_dwordx4 v130, s[24:25]
	s_add_i32 m0, s21, 0x2000
	s_nop 0
	global_load_lds_dwordx4 v146, s[24:25]
	s_mov_b32 m0, s13
	s_nop 0
	global_load_lds_dwordx4 v142, s[44:45]
	s_mov_b32 m0, s19
	s_nop 0
	global_load_lds_dwordx4 v144, s[44:45]
	s_waitcnt vmcnt(8) lgkmcnt(0)
	s_barrier
	v_mfma_f32_16x16x32_bf16 v[60:63], v[182:185], v[214:217], 0
	v_mfma_f32_16x16x32_bf16 v[56:59], v[190:193], v[214:217], 0
	v_mfma_f32_16x16x32_bf16 v[52:55], v[182:185], v[222:225], 0
	v_mfma_f32_16x16x32_bf16 v[48:51], v[190:193], v[222:225], 0
	v_mfma_f32_16x16x32_bf16 v[36:39], v[182:185], v[230:233], 0
	v_mfma_f32_16x16x32_bf16 v[32:35], v[190:193], v[230:233], 0
	v_mfma_f32_16x16x32_bf16 v[20:23], v[182:185], v[238:241], 0
	v_mfma_f32_16x16x32_bf16 v[16:19], v[190:193], v[238:241], 0
	v_mfma_f32_16x16x32_bf16 v[60:63], v[186:189], v[218:221], v[60:63]
	v_mfma_f32_16x16x32_bf16 v[56:59], v[194:197], v[218:221], v[56:59]
	v_mfma_f32_16x16x32_bf16 v[52:55], v[186:189], v[226:229], v[52:55]
	v_mfma_f32_16x16x32_bf16 v[48:51], v[194:197], v[226:229], v[48:51]
	v_mfma_f32_16x16x32_bf16 v[36:39], v[186:189], v[234:237], v[36:39]
	v_mfma_f32_16x16x32_bf16 v[32:35], v[194:197], v[234:237], v[32:35]
	v_mfma_f32_16x16x32_bf16 v[20:23], v[186:189], v[242:245], v[20:23]
	v_mfma_f32_16x16x32_bf16 v[16:19], v[194:197], v[242:245], v[16:19]
	v_mfma_f32_16x16x32_bf16 v[44:47], v[198:201], v[214:217], 0
	v_mfma_f32_16x16x32_bf16 v[40:43], v[206:209], v[214:217], 0
	v_mfma_f32_16x16x32_bf16 v[28:31], v[198:201], v[222:225], 0
	v_mfma_f32_16x16x32_bf16 v[24:27], v[206:209], v[222:225], 0
	v_mfma_f32_16x16x32_bf16 v[12:15], v[198:201], v[230:233], 0
	v_mfma_f32_16x16x32_bf16 v[8:11], v[206:209], v[230:233], 0
	v_mfma_f32_16x16x32_bf16 v[4:7], v[198:201], v[238:241], 0
	v_mfma_f32_16x16x32_bf16 v[0:3], v[206:209], v[238:241], 0
	v_mfma_f32_16x16x32_bf16 v[44:47], v[202:205], v[218:221], v[44:47]
	v_mfma_f32_16x16x32_bf16 v[40:43], v[210:213], v[218:221], v[40:43]
	v_mfma_f32_16x16x32_bf16 v[28:31], v[202:205], v[226:229], v[28:31]
	v_mfma_f32_16x16x32_bf16 v[24:27], v[210:213], v[226:229], v[24:27]
	v_mfma_f32_16x16x32_bf16 v[12:15], v[202:205], v[234:237], v[12:15]
	v_mfma_f32_16x16x32_bf16 v[8:11], v[210:213], v[234:237], v[8:11]
	v_mfma_f32_16x16x32_bf16 v[4:7], v[202:205], v[242:245], v[4:7]
	v_mfma_f32_16x16x32_bf16 v[0:3], v[210:213], v[242:245], v[0:3]
	s_barrier
	v_add_u32_e32 v181, s34, v153
	ds_read_b128 v[182:185], v181
	ds_read_b128 v[186:189], v181 offset:1024
	ds_read_b128 v[190:193], v181 offset:2048
	ds_read_b128 v[194:197], v181 offset:3072
	v_add_u32_e32 v181, s35, v153
	ds_read_b128 v[198:201], v181
	ds_read_b128 v[202:205], v181 offset:1024
	ds_read_b128 v[206:209], v181 offset:2048
	ds_read_b128 v[210:213], v181 offset:3072
	s_add_u32 s24, s44, 0xb0000
	s_addc_u32 s25, s45, 0
	s_mov_b32 m0, s20
	ds_read_b128 v[214:217], v155 offset:32768
	ds_read_b128 v[218:221], v155 offset:33792
	ds_read_b128 v[222:225], v155 offset:34816
	ds_read_b128 v[226:229], v155 offset:35840
	ds_read_b128 v[230:233], v155 offset:36864
	ds_read_b128 v[234:237], v155 offset:37888
	ds_read_b128 v[238:241], v155 offset:38912
	ds_read_b128 v[242:245], v155 offset:39936
	global_load_lds_dwordx4 v142, s[24:25]
	s_mov_b32 m0, s26
	s_nop 0
	global_load_lds_dwordx4 v144, s[24:25]
	s_waitcnt vmcnt(8) lgkmcnt(0)
	s_barrier
	v_mfma_f32_16x16x32_bf16 v[124:127], v[182:185], v[214:217], v[124:127]
	v_mfma_f32_16x16x32_bf16 v[120:123], v[190:193], v[214:217], v[120:123]
	v_mfma_f32_16x16x32_bf16 v[116:119], v[182:185], v[222:225], v[116:119]
	v_mfma_f32_16x16x32_bf16 v[112:115], v[190:193], v[222:225], v[112:115]
	v_mfma_f32_16x16x32_bf16 v[100:103], v[182:185], v[230:233], v[100:103]
	v_mfma_f32_16x16x32_bf16 v[96:99], v[190:193], v[230:233], v[96:99]
	v_mfma_f32_16x16x32_bf16 v[84:87], v[182:185], v[238:241], v[84:87]
	v_mfma_f32_16x16x32_bf16 v[80:83], v[190:193], v[238:241], v[80:83]
	v_mfma_f32_16x16x32_bf16 v[124:127], v[186:189], v[218:221], v[124:127]
	v_mfma_f32_16x16x32_bf16 v[120:123], v[194:197], v[218:221], v[120:123]
	v_mfma_f32_16x16x32_bf16 v[116:119], v[186:189], v[226:229], v[116:119]
	v_mfma_f32_16x16x32_bf16 v[112:115], v[194:197], v[226:229], v[112:115]
	v_mfma_f32_16x16x32_bf16 v[100:103], v[186:189], v[234:237], v[100:103]
	v_mfma_f32_16x16x32_bf16 v[96:99], v[194:197], v[234:237], v[96:99]
	v_mfma_f32_16x16x32_bf16 v[84:87], v[186:189], v[242:245], v[84:87]
	v_mfma_f32_16x16x32_bf16 v[80:83], v[194:197], v[242:245], v[80:83]
	v_mfma_f32_16x16x32_bf16 v[108:111], v[198:201], v[214:217], v[108:111]
	v_mfma_f32_16x16x32_bf16 v[104:107], v[206:209], v[214:217], v[104:107]
	v_mfma_f32_16x16x32_bf16 v[92:95], v[198:201], v[222:225], v[92:95]
	v_mfma_f32_16x16x32_bf16 v[88:91], v[206:209], v[222:225], v[88:91]
	v_mfma_f32_16x16x32_bf16 v[76:79], v[198:201], v[230:233], v[76:79]
	v_mfma_f32_16x16x32_bf16 v[72:75], v[206:209], v[230:233], v[72:75]
	v_mfma_f32_16x16x32_bf16 v[68:71], v[198:201], v[238:241], v[68:71]
	v_mfma_f32_16x16x32_bf16 v[64:67], v[206:209], v[238:241], v[64:67]
	v_mfma_f32_16x16x32_bf16 v[108:111], v[202:205], v[218:221], v[108:111]
	v_mfma_f32_16x16x32_bf16 v[104:107], v[210:213], v[218:221], v[104:107]
	v_mfma_f32_16x16x32_bf16 v[92:95], v[202:205], v[226:229], v[92:95]
	v_mfma_f32_16x16x32_bf16 v[88:91], v[210:213], v[226:229], v[88:91]
	v_mfma_f32_16x16x32_bf16 v[76:79], v[202:205], v[234:237], v[76:79]
	v_mfma_f32_16x16x32_bf16 v[72:75], v[210:213], v[234:237], v[72:75]
	v_mfma_f32_16x16x32_bf16 v[68:71], v[202:205], v[242:245], v[68:71]
	v_mfma_f32_16x16x32_bf16 v[64:67], v[210:213], v[242:245], v[64:67]
	s_barrier
	s_add_i32 s21, s34, s12
	s_mov_b32 m0, s21
	ds_read_b128 v[214:217], v155 offset:49152
	ds_read_b128 v[218:221], v155 offset:50176
	ds_read_b128 v[222:225], v155 offset:51200
	ds_read_b128 v[226:229], v155 offset:52224
	ds_read_b128 v[230:233], v155 offset:53248
	ds_read_b128 v[234:237], v155 offset:54272
	ds_read_b128 v[238:241], v155 offset:55296
	ds_read_b128 v[242:245], v155 offset:56320
	global_load_lds_dwordx4 v130, s[60:61]
	s_add_i32 m0, s21, 0x2000
	s_add_u32 s24, s42, 0xb0080
	s_addc_u32 s25, s43, 0
	s_add_i32 s21, s35, s12
	global_load_lds_dwordx4 v146, s[60:61]
	s_mov_b32 m0, s21
	s_nop 0
	global_load_lds_dwordx4 v130, s[24:25]
	s_add_i32 m0, s21, 0x2000
	s_nop 0
	global_load_lds_dwordx4 v146, s[24:25]
	s_mov_b32 m0, s33
	s_nop 0
	global_load_lds_dwordx4 v142, s[62:63]
	s_mov_b32 m0, s38
	s_nop 0
	global_load_lds_dwordx4 v144, s[62:63]
	s_waitcnt vmcnt(8) lgkmcnt(0)
	s_barrier
	v_mfma_f32_16x16x32_bf16 v[60:63], v[182:185], v[214:217], v[60:63]
	v_mfma_f32_16x16x32_bf16 v[56:59], v[190:193], v[214:217], v[56:59]
	v_mfma_f32_16x16x32_bf16 v[52:55], v[182:185], v[222:225], v[52:55]
	v_mfma_f32_16x16x32_bf16 v[48:51], v[190:193], v[222:225], v[48:51]
	v_mfma_f32_16x16x32_bf16 v[36:39], v[182:185], v[230:233], v[36:39]
	v_mfma_f32_16x16x32_bf16 v[32:35], v[190:193], v[230:233], v[32:35]
	v_mfma_f32_16x16x32_bf16 v[20:23], v[182:185], v[238:241], v[20:23]
	v_mfma_f32_16x16x32_bf16 v[16:19], v[190:193], v[238:241], v[16:19]
	v_mfma_f32_16x16x32_bf16 v[60:63], v[186:189], v[218:221], v[60:63]
	v_mfma_f32_16x16x32_bf16 v[56:59], v[194:197], v[218:221], v[56:59]
	v_mfma_f32_16x16x32_bf16 v[52:55], v[186:189], v[226:229], v[52:55]
	v_mfma_f32_16x16x32_bf16 v[48:51], v[194:197], v[226:229], v[48:51]
	v_mfma_f32_16x16x32_bf16 v[36:39], v[186:189], v[234:237], v[36:39]
	v_mfma_f32_16x16x32_bf16 v[32:35], v[194:197], v[234:237], v[32:35]
	v_mfma_f32_16x16x32_bf16 v[20:23], v[186:189], v[242:245], v[20:23]
	v_mfma_f32_16x16x32_bf16 v[16:19], v[194:197], v[242:245], v[16:19]
	v_mfma_f32_16x16x32_bf16 v[44:47], v[198:201], v[214:217], v[44:47]
	v_mfma_f32_16x16x32_bf16 v[40:43], v[206:209], v[214:217], v[40:43]
	v_mfma_f32_16x16x32_bf16 v[28:31], v[198:201], v[222:225], v[28:31]
	v_mfma_f32_16x16x32_bf16 v[24:27], v[206:209], v[222:225], v[24:27]
	v_mfma_f32_16x16x32_bf16 v[12:15], v[198:201], v[230:233], v[12:15]
	v_mfma_f32_16x16x32_bf16 v[8:11], v[206:209], v[230:233], v[8:11]
	v_mfma_f32_16x16x32_bf16 v[4:7], v[198:201], v[238:241], v[4:7]
	v_mfma_f32_16x16x32_bf16 v[0:3], v[206:209], v[238:241], v[0:3]
	v_mfma_f32_16x16x32_bf16 v[44:47], v[202:205], v[218:221], v[44:47]
	v_mfma_f32_16x16x32_bf16 v[40:43], v[210:213], v[218:221], v[40:43]
	v_mfma_f32_16x16x32_bf16 v[28:31], v[202:205], v[226:229], v[28:31]
	v_mfma_f32_16x16x32_bf16 v[24:27], v[210:213], v[226:229], v[24:27]
	v_mfma_f32_16x16x32_bf16 v[12:15], v[202:205], v[234:237], v[12:15]
	v_mfma_f32_16x16x32_bf16 v[8:11], v[210:213], v[234:237], v[8:11]
	v_mfma_f32_16x16x32_bf16 v[4:7], v[202:205], v[242:245], v[4:7]
	v_mfma_f32_16x16x32_bf16 v[0:3], v[210:213], v[242:245], v[0:3]
	s_barrier
	s_add_u32 s50, s50, 0x100
	s_addc_u32 s51, s51, 0
	s_cmp_ge_i32 s52, s49
	s_mov_b64 s[36:37], s[40:41]
	s_mov_b32 s42, s52
	s_cbranch_scc1 .Lpeel_done_1511
.LBB0_1511:
	v_add_u32_e32 v156, s22, v153
	ds_read_b128 v[182:185], v156
	ds_read_b128 v[186:189], v156 offset:1024
	ds_read_b128 v[190:193], v156 offset:2048
	ds_read_b128 v[194:197], v156 offset:3072
	v_add_u32_e32 v156, s23, v153
	ds_read_b128 v[198:201], v156
	ds_read_b128 v[202:205], v156 offset:1024
	ds_read_b128 v[206:209], v156 offset:2048
	ds_read_b128 v[210:213], v156 offset:3072
	s_add_i32 s52, s42, 2
	s_add_u32 s40, s36, 0x100
	s_addc_u32 s41, s37, 0
	s_cmp_eq_u32 s11, s42
	s_cselect_b32 s42, s28, s50
	s_cselect_b32 s45, s17, s41
	s_cselect_b32 s44, s16, s40
	s_cselect_b32 s43, s29, s51
	s_add_i32 m0, s13, 0xc000
	ds_read_b128 v[214:217], v155
	ds_read_b128 v[218:221], v155 offset:1024
	ds_read_b128 v[222:225], v155 offset:2048
	ds_read_b128 v[226:229], v155 offset:3072
	ds_read_b128 v[230:233], v155 offset:4096
	ds_read_b128 v[234:237], v155 offset:5120
	ds_read_b128 v[238:241], v155 offset:6144
	ds_read_b128 v[242:245], v155 offset:7168
	global_load_lds_dwordx4 v148, s[36:37]
	s_add_i32 m0, s13, 0xe000
	s_nop 0
	global_load_lds_dwordx4 v150, s[36:37]
	s_waitcnt vmcnt(8) lgkmcnt(0)
	s_barrier
	v_mfma_f32_16x16x32_bf16 v[124:127], v[182:185], v[214:217], v[124:127]
	v_mfma_f32_16x16x32_bf16 v[120:123], v[190:193], v[214:217], v[120:123]
	v_mfma_f32_16x16x32_bf16 v[116:119], v[182:185], v[222:225], v[116:119]
	v_mfma_f32_16x16x32_bf16 v[112:115], v[190:193], v[222:225], v[112:115]
	v_mfma_f32_16x16x32_bf16 v[100:103], v[182:185], v[230:233], v[100:103]
	v_mfma_f32_16x16x32_bf16 v[96:99], v[190:193], v[230:233], v[96:99]
	v_mfma_f32_16x16x32_bf16 v[84:87], v[182:185], v[238:241], v[84:87]
	v_mfma_f32_16x16x32_bf16 v[80:83], v[190:193], v[238:241], v[80:83]
	v_mfma_f32_16x16x32_bf16 v[124:127], v[186:189], v[218:221], v[124:127]
	v_mfma_f32_16x16x32_bf16 v[120:123], v[194:197], v[218:221], v[120:123]
	v_mfma_f32_16x16x32_bf16 v[116:119], v[186:189], v[226:229], v[116:119]
	v_mfma_f32_16x16x32_bf16 v[112:115], v[194:197], v[226:229], v[112:115]
	v_mfma_f32_16x16x32_bf16 v[100:103], v[186:189], v[234:237], v[100:103]
	v_mfma_f32_16x16x32_bf16 v[96:99], v[194:197], v[234:237], v[96:99]
	v_mfma_f32_16x16x32_bf16 v[84:87], v[186:189], v[242:245], v[84:87]
	v_mfma_f32_16x16x32_bf16 v[80:83], v[194:197], v[242:245], v[80:83]
	v_mfma_f32_16x16x32_bf16 v[108:111], v[198:201], v[214:217], v[108:111]
	v_mfma_f32_16x16x32_bf16 v[104:107], v[206:209], v[214:217], v[104:107]
	v_mfma_f32_16x16x32_bf16 v[92:95], v[198:201], v[222:225], v[92:95]
	v_mfma_f32_16x16x32_bf16 v[88:91], v[206:209], v[222:225], v[88:91]
	v_mfma_f32_16x16x32_bf16 v[76:79], v[198:201], v[230:233], v[76:79]
	v_mfma_f32_16x16x32_bf16 v[72:75], v[206:209], v[230:233], v[72:75]
	v_mfma_f32_16x16x32_bf16 v[68:71], v[198:201], v[238:241], v[68:71]
	v_mfma_f32_16x16x32_bf16 v[64:67], v[206:209], v[238:241], v[64:67]
	v_mfma_f32_16x16x32_bf16 v[108:111], v[202:205], v[218:221], v[108:111]
	v_mfma_f32_16x16x32_bf16 v[104:107], v[210:213], v[218:221], v[104:107]
	v_mfma_f32_16x16x32_bf16 v[92:95], v[202:205], v[226:229], v[92:95]
	v_mfma_f32_16x16x32_bf16 v[88:91], v[210:213], v[226:229], v[88:91]
	v_mfma_f32_16x16x32_bf16 v[76:79], v[202:205], v[234:237], v[76:79]
	v_mfma_f32_16x16x32_bf16 v[72:75], v[210:213], v[234:237], v[72:75]
	v_mfma_f32_16x16x32_bf16 v[68:71], v[202:205], v[242:245], v[68:71]
	v_mfma_f32_16x16x32_bf16 v[64:67], v[210:213], v[242:245], v[64:67]
	s_barrier
	s_add_u32 s60, s42, 0x80
	s_addc_u32 s61, s43, 0
	s_add_u32 s62, s44, 0x80
	s_addc_u32 s63, s45, 0
	s_add_i32 s21, s22, s12
	s_mov_b32 m0, s21
	ds_read_b128 v[214:217], v155 offset:16384
	ds_read_b128 v[218:221], v155 offset:17408
	ds_read_b128 v[222:225], v155 offset:18432
	ds_read_b128 v[226:229], v155 offset:19456
	ds_read_b128 v[230:233], v155 offset:20480
	ds_read_b128 v[234:237], v155 offset:21504
	ds_read_b128 v[238:241], v155 offset:22528
	ds_read_b128 v[242:245], v155 offset:23552
	global_load_lds_dwordx4 v130, s[42:43]
	s_add_i32 m0, s21, 0x2000
	s_add_u32 s24, s42, 0xb0000
	s_addc_u32 s25, s43, 0
	s_add_i32 s21, s23, s12
	global_load_lds_dwordx4 v146, s[42:43]
	s_mov_b32 m0, s21
	s_nop 0
	global_load_lds_dwordx4 v130, s[24:25]
	s_add_i32 m0, s21, 0x2000
	s_nop 0
	global_load_lds_dwordx4 v146, s[24:25]
	s_mov_b32 m0, s13
	s_nop 0
	global_load_lds_dwordx4 v142, s[44:45]
	s_mov_b32 m0, s19
	s_nop 0
	global_load_lds_dwordx4 v144, s[44:45]
	s_waitcnt vmcnt(8) lgkmcnt(0)
	s_barrier
	v_mfma_f32_16x16x32_bf16 v[60:63], v[182:185], v[214:217], v[60:63]
	v_mfma_f32_16x16x32_bf16 v[56:59], v[190:193], v[214:217], v[56:59]
	v_mfma_f32_16x16x32_bf16 v[52:55], v[182:185], v[222:225], v[52:55]
	v_mfma_f32_16x16x32_bf16 v[48:51], v[190:193], v[222:225], v[48:51]
	v_mfma_f32_16x16x32_bf16 v[36:39], v[182:185], v[230:233], v[36:39]
	v_mfma_f32_16x16x32_bf16 v[32:35], v[190:193], v[230:233], v[32:35]
	v_mfma_f32_16x16x32_bf16 v[20:23], v[182:185], v[238:241], v[20:23]
	v_mfma_f32_16x16x32_bf16 v[16:19], v[190:193], v[238:241], v[16:19]
	v_mfma_f32_16x16x32_bf16 v[60:63], v[186:189], v[218:221], v[60:63]
	v_mfma_f32_16x16x32_bf16 v[56:59], v[194:197], v[218:221], v[56:59]
	v_mfma_f32_16x16x32_bf16 v[52:55], v[186:189], v[226:229], v[52:55]
	v_mfma_f32_16x16x32_bf16 v[48:51], v[194:197], v[226:229], v[48:51]
	v_mfma_f32_16x16x32_bf16 v[36:39], v[186:189], v[234:237], v[36:39]
	v_mfma_f32_16x16x32_bf16 v[32:35], v[194:197], v[234:237], v[32:35]
	v_mfma_f32_16x16x32_bf16 v[20:23], v[186:189], v[242:245], v[20:23]
	v_mfma_f32_16x16x32_bf16 v[16:19], v[194:197], v[242:245], v[16:19]
	v_mfma_f32_16x16x32_bf16 v[44:47], v[198:201], v[214:217], v[44:47]
	v_mfma_f32_16x16x32_bf16 v[40:43], v[206:209], v[214:217], v[40:43]
	v_mfma_f32_16x16x32_bf16 v[28:31], v[198:201], v[222:225], v[28:31]
	v_mfma_f32_16x16x32_bf16 v[24:27], v[206:209], v[222:225], v[24:27]
	v_mfma_f32_16x16x32_bf16 v[12:15], v[198:201], v[230:233], v[12:15]
	v_mfma_f32_16x16x32_bf16 v[8:11], v[206:209], v[230:233], v[8:11]
	v_mfma_f32_16x16x32_bf16 v[4:7], v[198:201], v[238:241], v[4:7]
	v_mfma_f32_16x16x32_bf16 v[0:3], v[206:209], v[238:241], v[0:3]
	v_mfma_f32_16x16x32_bf16 v[44:47], v[202:205], v[218:221], v[44:47]
	v_mfma_f32_16x16x32_bf16 v[40:43], v[210:213], v[218:221], v[40:43]
	v_mfma_f32_16x16x32_bf16 v[28:31], v[202:205], v[226:229], v[28:31]
	v_mfma_f32_16x16x32_bf16 v[24:27], v[210:213], v[226:229], v[24:27]
	v_mfma_f32_16x16x32_bf16 v[12:15], v[202:205], v[234:237], v[12:15]
	v_mfma_f32_16x16x32_bf16 v[8:11], v[210:213], v[234:237], v[8:11]
	v_mfma_f32_16x16x32_bf16 v[4:7], v[202:205], v[242:245], v[4:7]
	v_mfma_f32_16x16x32_bf16 v[0:3], v[210:213], v[242:245], v[0:3]
	s_barrier
	v_add_u32_e32 v181, s34, v153
	ds_read_b128 v[182:185], v181
	ds_read_b128 v[186:189], v181 offset:1024
	ds_read_b128 v[190:193], v181 offset:2048
	ds_read_b128 v[194:197], v181 offset:3072
	v_add_u32_e32 v181, s35, v153
	ds_read_b128 v[198:201], v181
	ds_read_b128 v[202:205], v181 offset:1024
	ds_read_b128 v[206:209], v181 offset:2048
	ds_read_b128 v[210:213], v181 offset:3072
	s_add_u32 s24, s44, 0xb0000
	s_addc_u32 s25, s45, 0
	s_mov_b32 m0, s20
	ds_read_b128 v[214:217], v155 offset:32768
	ds_read_b128 v[218:221], v155 offset:33792
	ds_read_b128 v[222:225], v155 offset:34816
	ds_read_b128 v[226:229], v155 offset:35840
	ds_read_b128 v[230:233], v155 offset:36864
	ds_read_b128 v[234:237], v155 offset:37888
	ds_read_b128 v[238:241], v155 offset:38912
	ds_read_b128 v[242:245], v155 offset:39936
	global_load_lds_dwordx4 v142, s[24:25]
	s_mov_b32 m0, s26
	s_nop 0
	global_load_lds_dwordx4 v144, s[24:25]
	s_waitcnt vmcnt(8) lgkmcnt(0)
	s_barrier
	v_mfma_f32_16x16x32_bf16 v[124:127], v[182:185], v[214:217], v[124:127]
	v_mfma_f32_16x16x32_bf16 v[120:123], v[190:193], v[214:217], v[120:123]
	v_mfma_f32_16x16x32_bf16 v[116:119], v[182:185], v[222:225], v[116:119]
	v_mfma_f32_16x16x32_bf16 v[112:115], v[190:193], v[222:225], v[112:115]
	v_mfma_f32_16x16x32_bf16 v[100:103], v[182:185], v[230:233], v[100:103]
	v_mfma_f32_16x16x32_bf16 v[96:99], v[190:193], v[230:233], v[96:99]
	v_mfma_f32_16x16x32_bf16 v[84:87], v[182:185], v[238:241], v[84:87]
	v_mfma_f32_16x16x32_bf16 v[80:83], v[190:193], v[238:241], v[80:83]
	v_mfma_f32_16x16x32_bf16 v[124:127], v[186:189], v[218:221], v[124:127]
	v_mfma_f32_16x16x32_bf16 v[120:123], v[194:197], v[218:221], v[120:123]
	v_mfma_f32_16x16x32_bf16 v[116:119], v[186:189], v[226:229], v[116:119]
	v_mfma_f32_16x16x32_bf16 v[112:115], v[194:197], v[226:229], v[112:115]
	v_mfma_f32_16x16x32_bf16 v[100:103], v[186:189], v[234:237], v[100:103]
	v_mfma_f32_16x16x32_bf16 v[96:99], v[194:197], v[234:237], v[96:99]
	v_mfma_f32_16x16x32_bf16 v[84:87], v[186:189], v[242:245], v[84:87]
	v_mfma_f32_16x16x32_bf16 v[80:83], v[194:197], v[242:245], v[80:83]
	v_mfma_f32_16x16x32_bf16 v[108:111], v[198:201], v[214:217], v[108:111]
	v_mfma_f32_16x16x32_bf16 v[104:107], v[206:209], v[214:217], v[104:107]
	v_mfma_f32_16x16x32_bf16 v[92:95], v[198:201], v[222:225], v[92:95]
	v_mfma_f32_16x16x32_bf16 v[88:91], v[206:209], v[222:225], v[88:91]
	v_mfma_f32_16x16x32_bf16 v[76:79], v[198:201], v[230:233], v[76:79]
	v_mfma_f32_16x16x32_bf16 v[72:75], v[206:209], v[230:233], v[72:75]
	v_mfma_f32_16x16x32_bf16 v[68:71], v[198:201], v[238:241], v[68:71]
	v_mfma_f32_16x16x32_bf16 v[64:67], v[206:209], v[238:241], v[64:67]
	v_mfma_f32_16x16x32_bf16 v[108:111], v[202:205], v[218:221], v[108:111]
	v_mfma_f32_16x16x32_bf16 v[104:107], v[210:213], v[218:221], v[104:107]
	v_mfma_f32_16x16x32_bf16 v[92:95], v[202:205], v[226:229], v[92:95]
	v_mfma_f32_16x16x32_bf16 v[88:91], v[210:213], v[226:229], v[88:91]
	v_mfma_f32_16x16x32_bf16 v[76:79], v[202:205], v[234:237], v[76:79]
	v_mfma_f32_16x16x32_bf16 v[72:75], v[210:213], v[234:237], v[72:75]
	v_mfma_f32_16x16x32_bf16 v[68:71], v[202:205], v[242:245], v[68:71]
	v_mfma_f32_16x16x32_bf16 v[64:67], v[210:213], v[242:245], v[64:67]
	s_barrier
	s_add_i32 s21, s34, s12
	s_mov_b32 m0, s21
	ds_read_b128 v[214:217], v155 offset:49152
	ds_read_b128 v[218:221], v155 offset:50176
	ds_read_b128 v[222:225], v155 offset:51200
	ds_read_b128 v[226:229], v155 offset:52224
	ds_read_b128 v[230:233], v155 offset:53248
	ds_read_b128 v[234:237], v155 offset:54272
	ds_read_b128 v[238:241], v155 offset:55296
	ds_read_b128 v[242:245], v155 offset:56320
	global_load_lds_dwordx4 v130, s[60:61]
	s_add_i32 m0, s21, 0x2000
	s_add_u32 s24, s42, 0xb0080
	s_addc_u32 s25, s43, 0
	s_add_i32 s21, s35, s12
	global_load_lds_dwordx4 v146, s[60:61]
	s_mov_b32 m0, s21
	s_nop 0
	global_load_lds_dwordx4 v130, s[24:25]
	s_add_i32 m0, s21, 0x2000
	s_nop 0
	global_load_lds_dwordx4 v146, s[24:25]
	s_mov_b32 m0, s33
	s_nop 0
	global_load_lds_dwordx4 v142, s[62:63]
	s_mov_b32 m0, s38
	s_nop 0
	global_load_lds_dwordx4 v144, s[62:63]
	s_waitcnt vmcnt(8) lgkmcnt(0)
	s_barrier
	v_mfma_f32_16x16x32_bf16 v[60:63], v[182:185], v[214:217], v[60:63]
	v_mfma_f32_16x16x32_bf16 v[56:59], v[190:193], v[214:217], v[56:59]
	v_mfma_f32_16x16x32_bf16 v[52:55], v[182:185], v[222:225], v[52:55]
	v_mfma_f32_16x16x32_bf16 v[48:51], v[190:193], v[222:225], v[48:51]
	v_mfma_f32_16x16x32_bf16 v[36:39], v[182:185], v[230:233], v[36:39]
	v_mfma_f32_16x16x32_bf16 v[32:35], v[190:193], v[230:233], v[32:35]
	v_mfma_f32_16x16x32_bf16 v[20:23], v[182:185], v[238:241], v[20:23]
	v_mfma_f32_16x16x32_bf16 v[16:19], v[190:193], v[238:241], v[16:19]
	v_mfma_f32_16x16x32_bf16 v[60:63], v[186:189], v[218:221], v[60:63]
	v_mfma_f32_16x16x32_bf16 v[56:59], v[194:197], v[218:221], v[56:59]
	v_mfma_f32_16x16x32_bf16 v[52:55], v[186:189], v[226:229], v[52:55]
	v_mfma_f32_16x16x32_bf16 v[48:51], v[194:197], v[226:229], v[48:51]
	v_mfma_f32_16x16x32_bf16 v[36:39], v[186:189], v[234:237], v[36:39]
	v_mfma_f32_16x16x32_bf16 v[32:35], v[194:197], v[234:237], v[32:35]
	v_mfma_f32_16x16x32_bf16 v[20:23], v[186:189], v[242:245], v[20:23]
	v_mfma_f32_16x16x32_bf16 v[16:19], v[194:197], v[242:245], v[16:19]
	v_mfma_f32_16x16x32_bf16 v[44:47], v[198:201], v[214:217], v[44:47]
	v_mfma_f32_16x16x32_bf16 v[40:43], v[206:209], v[214:217], v[40:43]
	v_mfma_f32_16x16x32_bf16 v[28:31], v[198:201], v[222:225], v[28:31]
	v_mfma_f32_16x16x32_bf16 v[24:27], v[206:209], v[222:225], v[24:27]
	v_mfma_f32_16x16x32_bf16 v[12:15], v[198:201], v[230:233], v[12:15]
	v_mfma_f32_16x16x32_bf16 v[8:11], v[206:209], v[230:233], v[8:11]
	v_mfma_f32_16x16x32_bf16 v[4:7], v[198:201], v[238:241], v[4:7]
	v_mfma_f32_16x16x32_bf16 v[0:3], v[206:209], v[238:241], v[0:3]
	v_mfma_f32_16x16x32_bf16 v[44:47], v[202:205], v[218:221], v[44:47]
	v_mfma_f32_16x16x32_bf16 v[40:43], v[210:213], v[218:221], v[40:43]
	v_mfma_f32_16x16x32_bf16 v[28:31], v[202:205], v[226:229], v[28:31]
	v_mfma_f32_16x16x32_bf16 v[24:27], v[210:213], v[226:229], v[24:27]
	v_mfma_f32_16x16x32_bf16 v[12:15], v[202:205], v[234:237], v[12:15]
	v_mfma_f32_16x16x32_bf16 v[8:11], v[210:213], v[234:237], v[8:11]
	v_mfma_f32_16x16x32_bf16 v[4:7], v[202:205], v[242:245], v[4:7]
	v_mfma_f32_16x16x32_bf16 v[0:3], v[210:213], v[242:245], v[0:3]
	s_barrier
	s_add_u32 s50, s50, 0x100
	s_addc_u32 s51, s51, 0
	s_cmp_ge_i32 s52, s49
	s_mov_b64 s[36:37], s[40:41]
	s_mov_b32 s42, s52
	s_cbranch_scc0 .LBB0_1511
